# GEMM-phase epilogue stores made write-through (sc1) so the grid barrier's L2 write-back finds less dirty data
# baseline (speedup 1.0000x reference)
.Luph_noshift:
	v_ashrrev_i32_e32 v145, 31, v144
	s_and_b64 vcc, exec, s[22:23]
	v_mul_f32_e32 v124, v124, v143
	v_mul_f32_e32 v120, v124, v120
	v_mul_f32_e32 v124, 0xbfb8aa3b, v125
	v_exp_f32_e32 v124, v124
	s_mov_b32 s71, s28
	s_mov_b32 s38, s30
	s_mov_b64 s[42:43], s[36:37]
	v_add_f32_e32 v124, 1.0, v124
	v_rcp_f32_e32 v124, v124
	s_mov_b64 s[40:41], s[34:35]
	v_readlane_b32 s96, v255, 22
	v_mul_f32_e32 v124, v125, v124
	v_mul_f32_e32 v121, v124, v121
	v_mul_f32_e32 v124, 0xbfb8aa3b, v126
	v_exp_f32_e32 v124, v124
	s_nop 0
	v_add_f32_e32 v124, 1.0, v124
	v_rcp_f32_e32 v124, v124
	s_nop 0
	v_mul_f32_e32 v124, v126, v124
	v_mul_f32_e32 v122, v124, v122
	v_mul_f32_e32 v124, 0xbfb8aa3b, v127
	v_exp_f32_e32 v124, v124
	s_nop 0
	v_add_f32_e32 v124, 1.0, v124
	v_rcp_f32_e32 v124, v124
	s_nop 0
	v_mul_f32_e32 v124, v127, v124
	v_mul_f32_e32 v123, v124, v123
	v_mul_f32_e32 v124, 0xbfb8aa3b, v116
	v_exp_f32_e32 v124, v124
	s_nop 0
	v_add_f32_e32 v124, 1.0, v124
	v_rcp_f32_e32 v124, v124
	s_nop 0
	v_mul_f32_e32 v116, v116, v124
	v_mul_f32_e32 v112, v116, v112
	v_mul_f32_e32 v116, 0xbfb8aa3b, v117
	v_exp_f32_e32 v116, v116
	s_nop 0
	v_add_f32_e32 v116, 1.0, v116
	v_rcp_f32_e32 v116, v116
	s_nop 0
	v_mul_f32_e32 v116, v117, v116
	v_mul_f32_e32 v113, v116, v113
	v_mul_f32_e32 v116, 0xbfb8aa3b, v118
	v_exp_f32_e32 v116, v116
	v_cvt_pk_bf16_f32 v117, v122, v123
	s_nop 0
	v_add_f32_e32 v116, 1.0, v116
	v_rcp_f32_e32 v116, v116
	s_nop 0
	v_mul_f32_e32 v116, v118, v116
	v_mul_f32_e32 v114, v116, v114
	v_mul_f32_e32 v116, 0xbfb8aa3b, v119
	v_exp_f32_e32 v116, v116
	v_cvt_pk_bf16_f32 v118, v112, v113
	v_mov_b64_e32 v[112:113], s[4:5]
	s_movk_i32 s4, 0x1600
	v_add_f32_e32 v116, 1.0, v116
	v_rcp_f32_e32 v116, v116
	s_nop 0
	v_mul_f32_e32 v116, v119, v116
	v_mul_f32_e32 v115, v116, v115
	v_cvt_pk_bf16_f32 v116, v120, v121
	v_cvt_pk_bf16_f32 v119, v114, v115
	v_mad_i64_i32 v[120:121], s[26:27], v142, s4, v[112:113]
	v_lshlrev_b64 v[114:115], 1, v[144:145]
	v_lshl_add_u64 v[120:121], v[120:121], 0, v[114:115]
	global_store_dwordx4 v[120:121], v[116:119], off sc1
	s_nop 1
	v_mul_f32_e32 v116, 0xbfb8aa3b, v108
	v_exp_f32_e32 v116, v116
	s_nop 0
	v_add_f32_e32 v116, 1.0, v116
	v_rcp_f32_e32 v116, v116
	s_nop 0
	v_mul_f32_e32 v108, v108, v116
	v_mul_f32_e32 v104, v108, v104
	v_mul_f32_e32 v108, 0xbfb8aa3b, v109
	v_exp_f32_e32 v108, v108
	s_nop 0
	v_add_f32_e32 v108, 1.0, v108
	v_rcp_f32_e32 v108, v108
	s_nop 0
	v_mul_f32_e32 v108, v109, v108
	v_mul_f32_e32 v105, v108, v105
	v_mul_f32_e32 v108, 0xbfb8aa3b, v110
	v_exp_f32_e32 v108, v108
	s_nop 0
	v_add_f32_e32 v108, 1.0, v108
	v_rcp_f32_e32 v108, v108
	s_nop 0
	v_mul_f32_e32 v108, v110, v108
	v_mul_f32_e32 v106, v108, v106
	v_mul_f32_e32 v108, 0xbfb8aa3b, v111
	v_exp_f32_e32 v108, v108
	s_nop 0
	v_add_f32_e32 v108, 1.0, v108
	v_rcp_f32_e32 v108, v108
	s_nop 0
	v_mul_f32_e32 v108, v111, v108
	v_mul_f32_e32 v107, v108, v107
	v_mul_f32_e32 v108, 0xbfb8aa3b, v100
	v_exp_f32_e32 v108, v108
	s_nop 0
	v_add_f32_e32 v108, 1.0, v108
	v_rcp_f32_e32 v108, v108
	s_nop 0
	v_mul_f32_e32 v100, v100, v108
	v_mul_f32_e32 v100, v100, v96
	v_mul_f32_e32 v96, 0xbfb8aa3b, v101
	v_exp_f32_e32 v96, v96
	s_nop 0
	v_add_f32_e32 v96, 1.0, v96
	v_rcp_f32_e32 v96, v96
	s_nop 0
	v_mul_f32_e32 v96, v101, v96
	v_mul_f32_e32 v101, v96, v97
	v_mul_f32_e32 v96, 0xbfb8aa3b, v102
	v_exp_f32_e32 v96, v96
	v_cvt_pk_bf16_f32 v97, v106, v107
	s_nop 0
	v_add_f32_e32 v96, 1.0, v96
	v_rcp_f32_e32 v96, v96
	s_nop 0
	v_mul_f32_e32 v96, v102, v96
	v_mul_f32_e32 v102, v96, v98
	v_mul_f32_e32 v96, 0xbfb8aa3b, v103
	v_exp_f32_e32 v96, v96
	v_cvt_pk_bf16_f32 v98, v100, v101
	s_nop 0
	v_add_f32_e32 v96, 1.0, v96
	v_rcp_f32_e32 v96, v96
	s_nop 0
	v_mul_f32_e32 v96, v103, v96
	v_or_b32_e32 v103, 16, v142
	v_mad_i64_i32 v[100:101], s[26:27], v103, s4, v[112:113]
	v_mul_f32_e32 v99, v96, v99
	v_cvt_pk_bf16_f32 v96, v104, v105
	v_lshl_add_u64 v[100:101], v[100:101], 0, v[114:115]
	v_cvt_pk_bf16_f32 v99, v102, v99
	global_store_dwordx4 v[100:101], v[96:99], off sc1
	s_nop 1
	v_mul_f32_e32 v96, 0xbfb8aa3b, v92
	v_exp_f32_e32 v96, v96
	s_nop 0
	v_add_f32_e32 v96, 1.0, v96
	v_rcp_f32_e32 v96, v96
	s_nop 0
	v_mul_f32_e32 v92, v92, v96
	v_mul_f32_e32 v88, v92, v88
	v_mul_f32_e32 v92, 0xbfb8aa3b, v93
	v_exp_f32_e32 v92, v92
	s_nop 0
	v_add_f32_e32 v92, 1.0, v92
	v_rcp_f32_e32 v92, v92
	s_nop 0
	v_mul_f32_e32 v92, v93, v92
	v_mul_f32_e32 v89, v92, v89
	v_mul_f32_e32 v92, 0xbfb8aa3b, v94
	v_exp_f32_e32 v92, v92
	s_nop 0
	v_add_f32_e32 v92, 1.0, v92
	v_rcp_f32_e32 v92, v92
	s_nop 0
	v_mul_f32_e32 v92, v94, v92
	v_mul_f32_e32 v90, v92, v90
	v_mul_f32_e32 v92, 0xbfb8aa3b, v95
	v_exp_f32_e32 v92, v92
	s_nop 0
	v_add_f32_e32 v92, 1.0, v92
	v_rcp_f32_e32 v92, v92
	s_nop 0
	v_mul_f32_e32 v92, v95, v92
	v_mul_f32_e32 v91, v92, v91
	v_mul_f32_e32 v92, 0xbfb8aa3b, v84
	v_exp_f32_e32 v92, v92
	s_nop 0
	v_add_f32_e32 v92, 1.0, v92
	v_rcp_f32_e32 v92, v92
	s_nop 0
	v_mul_f32_e32 v84, v84, v92
	v_mul_f32_e32 v84, v84, v80
	v_mul_f32_e32 v80, 0xbfb8aa3b, v85
	v_exp_f32_e32 v80, v80
	s_nop 0
	v_add_f32_e32 v80, 1.0, v80
	v_rcp_f32_e32 v80, v80
	s_nop 0
	v_mul_f32_e32 v80, v85, v80
	v_mul_f32_e32 v85, v80, v81
	v_mul_f32_e32 v80, 0xbfb8aa3b, v86
	v_exp_f32_e32 v80, v80
	v_cvt_pk_bf16_f32 v81, v90, v91
	s_nop 0
	v_add_f32_e32 v80, 1.0, v80
	v_rcp_f32_e32 v80, v80
	s_nop 0
	v_mul_f32_e32 v80, v86, v80
	v_mul_f32_e32 v86, v80, v82
	v_mul_f32_e32 v80, 0xbfb8aa3b, v87
	v_exp_f32_e32 v80, v80
	v_cvt_pk_bf16_f32 v82, v84, v85
	s_nop 0
	v_add_f32_e32 v80, 1.0, v80
	v_rcp_f32_e32 v80, v80
	s_nop 0
	v_mul_f32_e32 v80, v87, v80
	v_or_b32_e32 v87, 32, v142
	v_mad_i64_i32 v[84:85], s[26:27], v87, s4, v[112:113]
	v_mul_f32_e32 v83, v80, v83
	v_cvt_pk_bf16_f32 v80, v88, v89
	v_lshl_add_u64 v[84:85], v[84:85], 0, v[114:115]
	v_cvt_pk_bf16_f32 v83, v86, v83
	global_store_dwordx4 v[84:85], v[80:83], off sc1
	s_nop 1
	v_mul_f32_e32 v80, 0xbfb8aa3b, v76
	v_exp_f32_e32 v80, v80
	s_nop 0
	v_add_f32_e32 v80, 1.0, v80
	v_rcp_f32_e32 v80, v80
	s_nop 0
	v_mul_f32_e32 v76, v76, v80
	v_mul_f32_e32 v72, v76, v72
	v_mul_f32_e32 v76, 0xbfb8aa3b, v77
	v_exp_f32_e32 v76, v76
	s_nop 0
	v_add_f32_e32 v76, 1.0, v76
	v_rcp_f32_e32 v76, v76
	s_nop 0
	v_mul_f32_e32 v76, v77, v76
	v_mul_f32_e32 v73, v76, v73
	v_mul_f32_e32 v76, 0xbfb8aa3b, v78
	v_exp_f32_e32 v76, v76
	s_nop 0
	v_add_f32_e32 v76, 1.0, v76
	v_rcp_f32_e32 v76, v76
	s_nop 0
	v_mul_f32_e32 v76, v78, v76
	v_mul_f32_e32 v74, v76, v74
	v_mul_f32_e32 v76, 0xbfb8aa3b, v79
	v_exp_f32_e32 v76, v76
	s_nop 0
	v_add_f32_e32 v76, 1.0, v76
	v_rcp_f32_e32 v76, v76
	s_nop 0
	v_mul_f32_e32 v76, v79, v76
	v_mul_f32_e32 v75, v76, v75
	v_mul_f32_e32 v76, 0xbfb8aa3b, v68
	v_exp_f32_e32 v76, v76
	s_nop 0
	v_add_f32_e32 v76, 1.0, v76
	v_rcp_f32_e32 v76, v76
	s_nop 0
	v_mul_f32_e32 v68, v68, v76
	v_mul_f32_e32 v68, v68, v64
	v_mul_f32_e32 v64, 0xbfb8aa3b, v69
	v_exp_f32_e32 v64, v64
	s_nop 0
	v_add_f32_e32 v64, 1.0, v64
	v_rcp_f32_e32 v64, v64
	s_nop 0
	v_mul_f32_e32 v64, v69, v64
	v_mul_f32_e32 v69, v64, v65
	v_mul_f32_e32 v64, 0xbfb8aa3b, v70
	v_exp_f32_e32 v64, v64
	v_cvt_pk_bf16_f32 v65, v74, v75
	s_nop 0
	v_add_f32_e32 v64, 1.0, v64
	v_rcp_f32_e32 v64, v64
	s_nop 0
	v_mul_f32_e32 v64, v70, v64
	v_mul_f32_e32 v70, v64, v66
	v_mul_f32_e32 v64, 0xbfb8aa3b, v71
	v_exp_f32_e32 v64, v64
	v_cvt_pk_bf16_f32 v66, v68, v69
	s_nop 0
	v_add_f32_e32 v64, 1.0, v64
	v_rcp_f32_e32 v64, v64
	s_nop 0
	v_mul_f32_e32 v64, v71, v64
	v_or_b32_e32 v71, 48, v142
	v_mad_i64_i32 v[68:69], s[26:27], v71, s4, v[112:113]
	v_mul_f32_e32 v67, v64, v67
	v_lshl_add_u64 v[68:69], v[68:69], 0, v[114:115]
	v_cvt_pk_bf16_f32 v64, v72, v73
	v_cvt_pk_bf16_f32 v67, v70, v67
	global_store_dwordx4 v[68:69], v[64:67], off sc1
	s_cmp_lg_u32 s100, 0
	s_cbranch_scc1 .Luph_nost
	s_nop 1
	v_mul_f32_e32 v65, 0xbfb8aa3b, v60
	v_exp_f32_e32 v65, v65
	v_add_u32_e32 v64, 0x80, v142
	v_add_f32_e32 v65, 1.0, v65
	v_rcp_f32_e32 v65, v65
	s_nop 0
	v_mul_f32_e32 v60, v60, v65
	v_mul_f32_e32 v56, v60, v56
	v_mul_f32_e32 v60, 0xbfb8aa3b, v61
	v_exp_f32_e32 v60, v60
	s_nop 0
	v_add_f32_e32 v60, 1.0, v60
	v_rcp_f32_e32 v60, v60
	s_nop 0
	v_mul_f32_e32 v60, v61, v60
	v_mul_f32_e32 v57, v60, v57
	v_mul_f32_e32 v60, 0xbfb8aa3b, v62
	v_exp_f32_e32 v60, v60
	s_nop 0
	v_add_f32_e32 v60, 1.0, v60
	v_rcp_f32_e32 v60, v60
	s_nop 0
	v_mul_f32_e32 v60, v62, v60
	v_mul_f32_e32 v58, v60, v58
	v_mul_f32_e32 v60, 0xbfb8aa3b, v63
	v_exp_f32_e32 v60, v60
	s_nop 0
	v_add_f32_e32 v60, 1.0, v60
	v_rcp_f32_e32 v60, v60
	s_nop 0
	v_mul_f32_e32 v60, v63, v60
	v_mul_f32_e32 v59, v60, v59
	v_mul_f32_e32 v60, 0xbfb8aa3b, v52
	v_exp_f32_e32 v60, v60
	s_nop 0
	v_add_f32_e32 v60, 1.0, v60
	v_rcp_f32_e32 v60, v60
	s_nop 0
	v_mul_f32_e32 v52, v52, v60
	v_mul_f32_e32 v52, v52, v48
	v_mul_f32_e32 v48, 0xbfb8aa3b, v53
	v_exp_f32_e32 v48, v48
	s_nop 0
	v_add_f32_e32 v48, 1.0, v48
	v_rcp_f32_e32 v48, v48
	s_nop 0
	v_mul_f32_e32 v48, v53, v48
	v_mul_f32_e32 v53, v48, v49
	v_mul_f32_e32 v48, 0xbfb8aa3b, v54
	v_exp_f32_e32 v48, v48
	v_cvt_pk_bf16_f32 v49, v58, v59
	s_nop 0
	v_add_f32_e32 v48, 1.0, v48
	v_rcp_f32_e32 v48, v48
	s_nop 0
	v_mul_f32_e32 v48, v54, v48
	v_mul_f32_e32 v54, v48, v50
	v_mul_f32_e32 v48, 0xbfb8aa3b, v55
	v_exp_f32_e32 v48, v48
	v_cvt_pk_bf16_f32 v50, v52, v53
	v_mad_i64_i32 v[52:53], s[26:27], v64, s4, v[112:113]
	v_add_f32_e32 v48, 1.0, v48
	v_rcp_f32_e32 v48, v48
	v_lshl_add_u64 v[52:53], v[52:53], 0, v[114:115]
	v_mul_f32_e32 v48, v55, v48
	v_mul_f32_e32 v51, v48, v51
	v_cvt_pk_bf16_f32 v48, v56, v57
	v_cvt_pk_bf16_f32 v51, v54, v51
	global_store_dwordx4 v[52:53], v[48:51], off sc1
	s_nop 1
	v_mul_f32_e32 v48, 0xbfb8aa3b, v44
	v_exp_f32_e32 v48, v48
	s_nop 0
	v_add_f32_e32 v48, 1.0, v48
	v_rcp_f32_e32 v48, v48
	s_nop 0
	v_mul_f32_e32 v44, v44, v48
	v_mul_f32_e32 v40, v44, v40
	v_mul_f32_e32 v44, 0xbfb8aa3b, v45
	v_exp_f32_e32 v44, v44
	s_nop 0
	v_add_f32_e32 v44, 1.0, v44
	v_rcp_f32_e32 v44, v44
	s_nop 0
	v_mul_f32_e32 v44, v45, v44
	v_mul_f32_e32 v41, v44, v41
	v_mul_f32_e32 v44, 0xbfb8aa3b, v46
	v_exp_f32_e32 v44, v44
	s_nop 0
	v_add_f32_e32 v44, 1.0, v44
	v_rcp_f32_e32 v44, v44
	s_nop 0
	v_mul_f32_e32 v44, v46, v44
	v_mul_f32_e32 v42, v44, v42
	v_mul_f32_e32 v44, 0xbfb8aa3b, v47
	v_exp_f32_e32 v44, v44
	s_nop 0
	v_add_f32_e32 v44, 1.0, v44
	v_rcp_f32_e32 v44, v44
	s_nop 0
	v_mul_f32_e32 v44, v47, v44
	v_mul_f32_e32 v43, v44, v43
	v_mul_f32_e32 v44, 0xbfb8aa3b, v36
	v_exp_f32_e32 v44, v44
	s_nop 0
	v_add_f32_e32 v44, 1.0, v44
	v_rcp_f32_e32 v44, v44
	s_nop 0
	v_mul_f32_e32 v36, v36, v44
	v_mul_f32_e32 v36, v36, v32
	v_mul_f32_e32 v32, 0xbfb8aa3b, v37
	v_exp_f32_e32 v32, v32
	s_nop 0
	v_add_f32_e32 v32, 1.0, v32
	v_rcp_f32_e32 v32, v32
	s_nop 0
	v_mul_f32_e32 v32, v37, v32
	v_mul_f32_e32 v37, v32, v33
	v_mul_f32_e32 v32, 0xbfb8aa3b, v38
	v_exp_f32_e32 v32, v32
	v_cvt_pk_bf16_f32 v33, v42, v43
	s_nop 0
	v_add_f32_e32 v32, 1.0, v32
	v_rcp_f32_e32 v32, v32
	s_nop 0
	v_mul_f32_e32 v32, v38, v32
	v_mul_f32_e32 v38, v32, v34
	v_mul_f32_e32 v32, 0xbfb8aa3b, v39
	v_exp_f32_e32 v32, v32
	v_cvt_pk_bf16_f32 v34, v36, v37
	s_nop 0
	v_add_f32_e32 v32, 1.0, v32
	v_rcp_f32_e32 v32, v32
	s_nop 0
	v_mul_f32_e32 v32, v39, v32
	v_add_u32_e32 v39, 0x90, v142
	v_mad_i64_i32 v[36:37], s[26:27], v39, s4, v[112:113]
	v_mul_f32_e32 v35, v32, v35
	v_cvt_pk_bf16_f32 v32, v40, v41
	v_lshl_add_u64 v[36:37], v[36:37], 0, v[114:115]
	v_cvt_pk_bf16_f32 v35, v38, v35
	global_store_dwordx4 v[36:37], v[32:35], off sc1
	s_nop 1
	v_mul_f32_e32 v32, 0xbfb8aa3b, v28
	v_exp_f32_e32 v32, v32
	s_nop 0
	v_add_f32_e32 v32, 1.0, v32
	v_rcp_f32_e32 v32, v32
	s_nop 0
	v_mul_f32_e32 v28, v28, v32
	v_mul_f32_e32 v24, v28, v24
	v_mul_f32_e32 v28, 0xbfb8aa3b, v29
	v_exp_f32_e32 v28, v28
	s_nop 0
	v_add_f32_e32 v28, 1.0, v28
	v_rcp_f32_e32 v28, v28
	s_nop 0
	v_mul_f32_e32 v28, v29, v28
	v_mul_f32_e32 v25, v28, v25
	v_mul_f32_e32 v28, 0xbfb8aa3b, v30
	v_exp_f32_e32 v28, v28
	s_nop 0
	v_add_f32_e32 v28, 1.0, v28
	v_rcp_f32_e32 v28, v28
	s_nop 0
	v_mul_f32_e32 v28, v30, v28
	v_mul_f32_e32 v26, v28, v26
	v_mul_f32_e32 v28, 0xbfb8aa3b, v31
	v_exp_f32_e32 v28, v28
	s_nop 0
	v_add_f32_e32 v28, 1.0, v28
	v_rcp_f32_e32 v28, v28
	s_nop 0
	v_mul_f32_e32 v28, v31, v28
	v_mul_f32_e32 v27, v28, v27
	v_mul_f32_e32 v28, 0xbfb8aa3b, v20
	v_exp_f32_e32 v28, v28
	s_nop 0
	v_add_f32_e32 v28, 1.0, v28
	v_rcp_f32_e32 v28, v28
	s_nop 0
	v_mul_f32_e32 v20, v20, v28
	v_mul_f32_e32 v20, v20, v16
	v_mul_f32_e32 v16, 0xbfb8aa3b, v21
	v_exp_f32_e32 v16, v16
	s_nop 0
	v_add_f32_e32 v16, 1.0, v16
	v_rcp_f32_e32 v16, v16
	s_nop 0
	v_mul_f32_e32 v16, v21, v16
	v_mul_f32_e32 v21, v16, v17
	v_mul_f32_e32 v16, 0xbfb8aa3b, v22
	v_exp_f32_e32 v16, v16
	v_cvt_pk_bf16_f32 v17, v26, v27
	s_nop 0
	v_add_f32_e32 v16, 1.0, v16
	v_rcp_f32_e32 v16, v16
	s_nop 0
	v_mul_f32_e32 v16, v22, v16
	v_mul_f32_e32 v22, v16, v18
	v_mul_f32_e32 v16, 0xbfb8aa3b, v23
	v_exp_f32_e32 v16, v16
	v_cvt_pk_bf16_f32 v18, v20, v21
	s_nop 0
	v_add_f32_e32 v16, 1.0, v16
	v_rcp_f32_e32 v16, v16
	s_nop 0
	v_mul_f32_e32 v16, v23, v16
	v_add_u32_e32 v23, 0xa0, v142
	v_mad_i64_i32 v[20:21], s[26:27], v23, s4, v[112:113]
	v_mul_f32_e32 v19, v16, v19
	v_cvt_pk_bf16_f32 v16, v24, v25
	v_lshl_add_u64 v[20:21], v[20:21], 0, v[114:115]
	v_cvt_pk_bf16_f32 v19, v22, v19
	global_store_dwordx4 v[20:21], v[16:19], off sc1
	s_nop 1
	v_mul_f32_e32 v16, 0xbfb8aa3b, v12
	v_exp_f32_e32 v16, v16
	s_nop 0
	v_add_f32_e32 v16, 1.0, v16
	v_rcp_f32_e32 v16, v16
	s_nop 0
	v_mul_f32_e32 v12, v12, v16
	v_mul_f32_e32 v8, v12, v8
	v_mul_f32_e32 v12, 0xbfb8aa3b, v13
	v_exp_f32_e32 v12, v12
	s_nop 0
	v_add_f32_e32 v12, 1.0, v12
	v_rcp_f32_e32 v12, v12
	s_nop 0
	v_mul_f32_e32 v12, v13, v12
	v_mul_f32_e32 v9, v12, v9
	v_mul_f32_e32 v12, 0xbfb8aa3b, v14
	v_exp_f32_e32 v12, v12
	s_nop 0
	v_add_f32_e32 v12, 1.0, v12
	v_rcp_f32_e32 v12, v12
	s_nop 0
	v_mul_f32_e32 v12, v14, v12
	v_mul_f32_e32 v10, v12, v10
	v_mul_f32_e32 v12, 0xbfb8aa3b, v15
	v_exp_f32_e32 v12, v12
	s_nop 0
	v_add_f32_e32 v12, 1.0, v12
	v_rcp_f32_e32 v12, v12
	s_nop 0
	v_mul_f32_e32 v12, v15, v12
	v_mul_f32_e32 v11, v12, v11
	v_mul_f32_e32 v12, 0xbfb8aa3b, v4
	v_exp_f32_e32 v12, v12
	s_nop 0
	v_add_f32_e32 v12, 1.0, v12
	v_rcp_f32_e32 v12, v12
	s_nop 0
	v_mul_f32_e32 v4, v4, v12
	v_mul_f32_e32 v4, v4, v0
	v_mul_f32_e32 v0, 0xbfb8aa3b, v5
	v_exp_f32_e32 v0, v0
	s_nop 0
	v_add_f32_e32 v0, 1.0, v0
	v_rcp_f32_e32 v0, v0
	s_nop 0
	v_mul_f32_e32 v0, v5, v0
	v_mul_f32_e32 v5, v0, v1
	v_mul_f32_e32 v0, 0xbfb8aa3b, v6
	v_exp_f32_e32 v0, v0
	v_cvt_pk_bf16_f32 v1, v10, v11
	s_nop 0
	v_add_f32_e32 v0, 1.0, v0
	v_rcp_f32_e32 v0, v0
	s_nop 0
	v_mul_f32_e32 v0, v6, v0
	v_mul_f32_e32 v6, v0, v2
	v_mul_f32_e32 v0, 0xbfb8aa3b, v7
	v_exp_f32_e32 v0, v0
	v_cvt_pk_bf16_f32 v2, v4, v5
	s_nop 0
	v_add_f32_e32 v0, 1.0, v0
	v_rcp_f32_e32 v0, v0
	s_nop 0
	v_mul_f32_e32 v0, v7, v0
	v_add_u32_e32 v7, 0xb0, v142
	v_mad_i64_i32 v[4:5], s[26:27], v7, s4, v[112:113]
	v_mul_f32_e32 v3, v0, v3
	v_lshl_add_u64 v[4:5], v[4:5], 0, v[114:115]
	v_cvt_pk_bf16_f32 v0, v8, v9
	v_cvt_pk_bf16_f32 v3, v6, v3
	global_store_dwordx4 v[4:5], v[0:3], off sc1

.Lpjh_s7:
	s_setprio 0
	s_add_u32 s30, s30, 0x100
	s_addc_u32 s31, s31, 0
	s_add_u32 s26, s26, 0x100
	s_addc_u32 s27, s27, 0
	s_cmp_ge_u32 s71, s54
	s_mov_b32 s34, s71
	s_barrier
	s_cbranch_scc0 .LBB0_94
	v_lshl_add_u32 v138, s69, 8, v140
	s_cmp_eq_u32 s100, 2
	s_cselect_b32 vcc_lo, 0x80, 0
	s_nop 0
	v_add_u32_e32 v138, vcc_lo, v138
	v_lshl_or_b32 v144, s70, 8, v143
	v_ashrrev_i32_e32 v139, 31, v138
	v_readlane_b32 s4, v253, 16
	v_ashrrev_i32_e32 v145, 31, v144
	v_cvt_pk_bf16_f32 v124, v124, v125
	v_cvt_pk_bf16_f32 v125, v126, v127
	v_cvt_pk_bf16_f32 v126, v120, v121
	v_lshlrev_b64 v[120:121], 11, v[138:139]
	v_readlane_b32 s5, v253, 17
	v_cvt_pk_bf16_f32 v127, v122, v123
	v_lshlrev_b64 v[122:123], 1, v[144:145]
	v_cvt_pk_bf16_f32 v116, v116, v117
	v_cvt_pk_bf16_f32 v117, v118, v119
	v_cvt_pk_bf16_f32 v119, v114, v115
	s_nop 0
	v_lshl_add_u64 v[120:121], s[4:5], 0, v[120:121]
	v_lshl_add_u64 v[120:121], v[120:121], 0, v[122:123]
	global_store_dwordx4 v[120:121], v[124:127], off sc1
	v_or_b32_e32 v114, 32, v138
	v_cvt_pk_bf16_f32 v108, v108, v109
	v_cvt_pk_bf16_f32 v109, v110, v111
	v_cvt_pk_bf16_f32 v111, v106, v107
	v_or_b32_e32 v106, 48, v138
	v_or_b32_e32 v124, 16, v138
	v_cvt_pk_bf16_f32 v68, v68, v69
	v_cvt_pk_bf16_f32 v69, v70, v71
	v_cvt_pk_bf16_f32 v70, v64, v65
	v_add_u32_e32 v64, 0x80, v138
	v_cvt_pk_bf16_f32 v60, v60, v61
	v_cvt_pk_bf16_f32 v61, v62, v63
	v_cvt_pk_bf16_f32 v63, v58, v59
	v_add_u32_e32 v58, 0x90, v138
	v_cvt_pk_bf16_f32 v52, v52, v53
	v_cvt_pk_bf16_f32 v53, v54, v55
	v_cvt_pk_bf16_f32 v55, v50, v51
	v_add_u32_e32 v50, 0xa0, v138
	v_cvt_pk_bf16_f32 v44, v44, v45
	v_cvt_pk_bf16_f32 v45, v46, v47
	v_cvt_pk_bf16_f32 v47, v42, v43
	v_add_u32_e32 v42, 0xb0, v138
	v_ashrrev_i32_e32 v125, 31, v124
	v_ashrrev_i32_e32 v115, 31, v114
	v_ashrrev_i32_e32 v107, 31, v106
	v_ashrrev_i32_e32 v65, 31, v64
	v_ashrrev_i32_e32 v59, 31, v58
	v_ashrrev_i32_e32 v51, 31, v50
	v_ashrrev_i32_e32 v43, 31, v42
	v_cvt_pk_bf16_f32 v118, v112, v113
	v_lshlrev_b64 v[112:113], 11, v[124:125]
	v_cvt_pk_bf16_f32 v110, v104, v105
	v_lshlrev_b64 v[104:105], 11, v[114:115]
	v_cvt_pk_bf16_f32 v100, v100, v101
	v_cvt_pk_bf16_f32 v101, v102, v103
	v_cvt_pk_bf16_f32 v102, v96, v97
	v_lshlrev_b64 v[96:97], 11, v[106:107]
	v_cvt_pk_bf16_f32 v62, v56, v57
	v_lshlrev_b64 v[56:57], 11, v[64:65]
	v_cvt_pk_bf16_f32 v54, v48, v49
	v_lshlrev_b64 v[48:49], 11, v[58:59]
	v_cvt_pk_bf16_f32 v46, v40, v41
	v_lshlrev_b64 v[40:41], 11, v[50:51]
	v_cvt_pk_bf16_f32 v36, v36, v37
	v_cvt_pk_bf16_f32 v37, v38, v39
	v_cvt_pk_bf16_f32 v38, v32, v33
	v_lshlrev_b64 v[32:33], 11, v[42:43]
	v_lshl_add_u64 v[112:113], s[4:5], 0, v[112:113]
	v_lshl_add_u64 v[104:105], s[4:5], 0, v[104:105]
	v_lshl_add_u64 v[96:97], s[4:5], 0, v[96:97]
	v_lshl_add_u64 v[56:57], s[4:5], 0, v[56:57]
	v_lshl_add_u64 v[48:49], s[4:5], 0, v[48:49]
	v_lshl_add_u64 v[40:41], s[4:5], 0, v[40:41]
	v_lshl_add_u64 v[32:33], s[4:5], 0, v[32:33]
	v_lshl_add_u64 v[112:113], v[112:113], 0, v[122:123]
	v_lshl_add_u64 v[104:105], v[104:105], 0, v[122:123]
	v_lshl_add_u64 v[96:97], v[96:97], 0, v[122:123]
	v_lshl_add_u64 v[56:57], v[56:57], 0, v[122:123]
	v_lshl_add_u64 v[48:49], v[48:49], 0, v[122:123]
	v_lshl_add_u64 v[40:41], v[40:41], 0, v[122:123]
	v_lshl_add_u64 v[32:33], v[32:33], 0, v[122:123]
	s_and_b64 vcc, exec, s[22:23]
	s_mov_b32 s70, s65
	s_mov_b32 s69, s68
	s_mov_b64 s[34:35], s[0:1]
	s_mov_b64 s[30:31], s[28:29]
	s_mov_b32 s71, 0x42ce8ed0
	v_readlane_b32 s6, v253, 18
	v_readlane_b32 s7, v253, 19
	v_readlane_b32 s8, v253, 20
	v_readlane_b32 s9, v253, 21
	v_readlane_b32 s10, v253, 22
	v_readlane_b32 s11, v253, 23
	v_readlane_b32 s12, v253, 24
	v_readlane_b32 s13, v253, 25
	v_readlane_b32 s14, v253, 26
	v_readlane_b32 s15, v253, 27
	v_readlane_b32 s16, v253, 28
	v_readlane_b32 s17, v253, 29
	v_readlane_b32 s18, v253, 30
	v_readlane_b32 s19, v253, 31
	global_store_dwordx4 v[112:113], v[116:119], off sc1
	global_store_dwordx4 v[104:105], v[108:111], off sc1
	v_cvt_pk_bf16_f32 v103, v98, v99
	global_store_dwordx4 v[96:97], v[100:103], off sc1
	v_cvt_pk_bf16_f32 v92, v92, v93
	v_cvt_pk_bf16_f32 v93, v94, v95
	v_cvt_pk_bf16_f32 v94, v88, v89
	v_cvt_pk_bf16_f32 v95, v90, v91
	global_store_dwordx4 v[120:121], v[92:95], off offset:256 sc1
	v_cvt_pk_bf16_f32 v84, v84, v85
	v_cvt_pk_bf16_f32 v85, v86, v87
	v_cvt_pk_bf16_f32 v86, v80, v81
	v_cvt_pk_bf16_f32 v87, v82, v83
	global_store_dwordx4 v[112:113], v[84:87], off offset:256 sc1
	v_cvt_pk_bf16_f32 v76, v76, v77
	v_cvt_pk_bf16_f32 v77, v78, v79
	v_cvt_pk_bf16_f32 v78, v72, v73
	v_cvt_pk_bf16_f32 v79, v74, v75
	global_store_dwordx4 v[104:105], v[76:79], off offset:256 sc1
	v_cvt_pk_bf16_f32 v71, v66, v67
	global_store_dwordx4 v[96:97], v[68:71], off offset:256 sc1
	s_cmp_lg_u32 s100, 0
	s_cbranch_scc1 .Lpjh_nost
	global_store_dwordx4 v[56:57], v[60:63], off sc1
	global_store_dwordx4 v[48:49], v[52:55], off sc1
	global_store_dwordx4 v[40:41], v[44:47], off sc1
	v_cvt_pk_bf16_f32 v39, v34, v35
	global_store_dwordx4 v[32:33], v[36:39], off sc1
	v_cvt_pk_bf16_f32 v28, v28, v29
	v_cvt_pk_bf16_f32 v29, v30, v31
	v_cvt_pk_bf16_f32 v30, v24, v25
	v_cvt_pk_bf16_f32 v31, v26, v27
	global_store_dwordx4 v[56:57], v[28:31], off offset:256 sc1
	v_cvt_pk_bf16_f32 v20, v20, v21
	v_cvt_pk_bf16_f32 v21, v22, v23
	v_cvt_pk_bf16_f32 v22, v16, v17
	v_cvt_pk_bf16_f32 v23, v18, v19
	global_store_dwordx4 v[48:49], v[20:23], off offset:256 sc1
	v_cvt_pk_bf16_f32 v12, v12, v13
	v_cvt_pk_bf16_f32 v13, v14, v15
	v_cvt_pk_bf16_f32 v14, v8, v9
	v_cvt_pk_bf16_f32 v15, v10, v11
	global_store_dwordx4 v[40:41], v[12:15], off offset:256 sc1
	v_cvt_pk_bf16_f32 v4, v4, v5
	v_cvt_pk_bf16_f32 v5, v6, v7
	v_cvt_pk_bf16_f32 v6, v0, v1
	v_cvt_pk_bf16_f32 v7, v2, v3
	global_store_dwordx4 v[32:33], v[4:7], off offset:256 sc1

.LBB0_114:
	s_lshl_b32 s22, s52, 4
	s_lshl_b32 s28, s26, 5
	s_add_i32 s22, s22, s20
	s_ashr_i32 s29, s28, 31
	s_lshl_b32 s27, s55, 3
	s_ashr_i32 s23, s22, 31
	s_ashr_i32 s30, s27, 31
	s_or_b64 s[28:29], s[28:29], s[0:1]
	s_add_u32 s28, s28, s27
	s_addc_u32 s29, s29, s30
	s_lshl_b64 s[22:23], s[22:23], 17
	s_lshl_b64 s[28:29], s[28:29], 10
	s_add_u32 s22, s78, s22
	s_addc_u32 s23, s79, s23
	s_add_u32 s22, s22, s28
	s_addc_u32 s23, s23, s29
	v_mov_b32_e32 v100, v245
	s_cmp_eq_u32 s26, 3
	s_cselect_b64 s[36:37], -1, 0
	v_ashrrev_i32_e32 v101, 31, v100
	v_lshl_add_u64 v[208:209], v[100:101], 4, s[22:23]
	s_and_b64 s[28:29], s[36:37], exec
	global_load_dwordx4 v[198:201], v[208:209], off
	s_cselect_b32 s27, 0, 0x800
	s_lshl_b32 s88, s27, 4
	v_lshl_add_u64 v[100:101], v[208:209], 0, s[88:89]
	global_load_dwordx4 v[202:205], v[100:101], off
	s_mov_b64 s[22:23], 0x20000
	v_lshl_add_u64 v[100:101], v[208:209], 0, s[22:23]
	s_mov_b32 s22, 0x21000
	v_add_co_u32_e32 v102, vcc, s22, v208
	v_lshl_add_u64 v[100:101], v[100:101], 0, s[88:89]
	s_nop 0
	v_addc_co_u32_e32 v103, vcc, 0, v209, vcc
	s_mov_b64 s[22:23], 0x40000
	global_load_dwordx4 v[180:183], v[102:103], off offset:-4096
	global_load_dwordx4 v[176:179], v[100:101], off
	v_lshl_add_u64 v[100:101], v[208:209], 0, s[22:23]
	s_mov_b32 s22, 0x41000
	v_lshl_add_u64 v[100:101], v[100:101], 0, s[88:89]
	v_add_co_u32_e32 v104, vcc, s22, v208
	global_load_dwordx4 v[172:175], v[100:101], off
	global_load_dwordx4 v[140:143], v[102:103], off
	v_lshl_add_u64 v[100:101], v[208:209], 0, s[82:83]
	v_addc_co_u32_e32 v105, vcc, 0, v209, vcc
	v_lshl_add_u64 v[100:101], v[100:101], 0, s[88:89]
	global_load_dwordx4 v[168:171], v[104:105], off offset:-4096
	global_load_dwordx4 v[160:163], v[100:101], off
	s_mov_b32 s22, 0x61000
	v_lshl_add_u64 v[100:101], v[208:209], 0, s[94:95]
	v_add_co_u32_e32 v106, vcc, s22, v208
	v_lshl_add_u64 v[100:101], v[100:101], 0, s[88:89]
	s_mov_b64 s[22:23], 0x21000
	global_load_dwordx4 v[152:155], v[100:101], off
	global_load_dwordx4 v[120:123], v[104:105], off
	v_lshl_add_u64 v[100:101], v[208:209], 0, s[22:23]
	v_addc_co_u32_e32 v107, vcc, 0, v209, vcc
	s_movk_i32 s4, 0x1000
	v_lshl_add_u64 v[100:101], v[100:101], 0, s[88:89]
	s_mov_b64 s[22:23], 0x41000
	global_load_dwordx4 v[164:167], v[106:107], off offset:-4096
	global_load_dwordx4 v[132:135], v[100:101], off
	v_add_co_u32_e32 v116, vcc, s4, v208
	v_lshl_add_u64 v[100:101], v[208:209], 0, s[22:23]
	s_nop 0
	v_addc_co_u32_e32 v117, vcc, 0, v209, vcc
	v_lshl_add_u64 v[100:101], v[100:101], 0, s[88:89]
	s_mov_b64 s[22:23], 0x61000
	global_load_dwordx4 v[156:159], v[116:117], off
	s_movk_i32 s33, 0x3fff
	global_load_dwordx4 v[116:119], v[100:101], off
	s_cmp_lg_u32 s26, 3
	global_load_dwordx4 v[104:107], v[106:107], off
	v_lshl_add_u64 v[100:101], v[208:209], 0, s[22:23]
	v_lshl_add_u64 v[100:101], v[100:101], 0, s[88:89]
	global_load_dwordx4 v[100:103], v[100:101], off
	v_lshl_add_u32 v216, s52, 8, v242
	s_waitcnt vmcnt(14)
	v_lshlrev_b32_e32 v206, 16, v198
	v_and_b32_e32 v207, 0xffff0000, v198
	v_rcp_f32_e32 v206, v206
	v_rcp_f32_e32 v207, v207
	v_lshlrev_b32_e32 v210, 16, v199
	v_and_b32_e32 v211, 0xffff0000, v199
	v_lshlrev_b32_e32 v198, 16, v202
	v_and_b32_e32 v199, 0xffff0000, v202
	v_pk_mul_f32 v[198:199], v[206:207], v[198:199]
	v_lshlrev_b32_e32 v212, 16, v200
	v_cndmask_b32_e64 v199, v199, v207, s[36:37]
	v_cndmask_b32_e64 v198, v198, v206, s[36:37]
	v_pk_mul_f32 v[198:199], v[148:149], v[198:199]
	v_rcp_f32_e32 v148, v210
	v_rcp_f32_e32 v149, v211
	v_and_b32_e32 v213, 0xffff0000, v200
	v_lshlrev_b32_e32 v214, 16, v201
	v_and_b32_e32 v215, 0xffff0000, v201
	v_lshlrev_b32_e32 v200, 16, v203
	v_and_b32_e32 v201, 0xffff0000, v203
	v_pk_mul_f32 v[200:201], v[148:149], v[200:201]
	v_lshlrev_b32_e32 v202, 16, v204
	v_cndmask_b32_e64 v149, v201, v149, s[36:37]
	v_cndmask_b32_e64 v148, v200, v148, s[36:37]
	v_pk_mul_f32 v[200:201], v[150:151], v[148:149]
	v_rcp_f32_e32 v148, v212
	v_rcp_f32_e32 v149, v213
	v_and_b32_e32 v203, 0xffff0000, v204
	v_lshlrev_b32_e32 v204, 16, v205
	v_and_b32_e32 v205, 0xffff0000, v205
	v_pk_mul_f32 v[150:151], v[148:149], v[202:203]
	v_lshl_or_b32 v206, s55, 8, v192
	v_cndmask_b32_e64 v149, v151, v149, s[36:37]
	v_cndmask_b32_e64 v148, v150, v148, s[36:37]
	v_pk_mul_f32 v[202:203], v[144:145], v[148:149]
	v_rcp_f32_e32 v144, v214
	v_rcp_f32_e32 v145, v215
	s_nop 0
	v_pk_mul_f32 v[148:149], v[144:145], v[204:205]
	s_nop 0
	v_cndmask_b32_e64 v145, v149, v145, s[36:37]
	v_cndmask_b32_e64 v144, v148, v144, s[36:37]
	v_pk_mul_f32 v[204:205], v[146:147], v[144:145]
	s_cbranch_scc1 .LBB0_116
	v_ashrrev_i32_e32 v217, 31, v216
	v_readlane_b32 s4, v253, 16
	v_lshlrev_b64 v[148:149], 11, v[216:217]
	v_readlane_b32 s6, v253, 18
	v_readlane_b32 s7, v253, 19
	v_ashrrev_i32_e32 v207, 31, v206
	v_cvt_pk_bf16_f32 v144, v198, v199
	v_cvt_pk_bf16_f32 v145, v200, v201
	v_cvt_pk_bf16_f32 v146, v202, v203
	v_cvt_pk_bf16_f32 v147, v204, v205
	s_nop 0
	v_lshl_add_u64 v[148:149], s[6:7], 0, v[148:149]
	v_lshl_add_u64 v[148:149], v[206:207], 1, v[148:149]
	v_readlane_b32 s5, v253, 17
	v_readlane_b32 s8, v253, 20
	v_readlane_b32 s9, v253, 21
	v_readlane_b32 s10, v253, 22
	v_readlane_b32 s11, v253, 23
	v_readlane_b32 s12, v253, 24
	v_readlane_b32 s13, v253, 25
	v_readlane_b32 s14, v253, 26
	v_readlane_b32 s15, v253, 27
	v_readlane_b32 s16, v253, 28
	v_readlane_b32 s17, v253, 29
	v_readlane_b32 s18, v253, 30
	v_readlane_b32 s19, v253, 31
	global_store_dwordx4 v[148:149], v[144:147], off sc1
.LBB0_116:
	s_waitcnt vmcnt(12)
	v_lshlrev_b32_e32 v207, 16, v180
	v_and_b32_e32 v180, 0xffff0000, v180
	v_lshlrev_b32_e32 v144, 16, v176
	v_and_b32_e32 v145, 0xffff0000, v176
	v_lshlrev_b32_e32 v146, 16, v177
	v_and_b32_e32 v147, 0xffff0000, v177
	v_rcp_f32_e32 v176, v207
	v_rcp_f32_e32 v177, v180
	v_lshlrev_b32_e32 v210, 16, v181
	v_and_b32_e32 v181, 0xffff0000, v181
	v_lshlrev_b32_e32 v211, 16, v182
	v_pk_mul_f32 v[144:145], v[176:177], v[144:145]
	v_and_b32_e32 v182, 0xffff0000, v182
	v_cndmask_b32_e64 v145, v145, v177, s[36:37]
	v_cndmask_b32_e64 v144, v144, v176, s[36:37]
	v_pk_mul_f32 v[176:177], v[136:137], v[144:145]
	v_rcp_f32_e32 v136, v210
	v_rcp_f32_e32 v137, v181
	v_lshlrev_b32_e32 v148, 16, v178
	v_and_b32_e32 v149, 0xffff0000, v178
	v_lshlrev_b32_e32 v150, 16, v179
	v_pk_mul_f32 v[144:145], v[136:137], v[146:147]
	v_and_b32_e32 v151, 0xffff0000, v179
	v_cndmask_b32_e64 v137, v145, v137, s[36:37]
	v_cndmask_b32_e64 v136, v144, v136, s[36:37]
	v_pk_mul_f32 v[178:179], v[138:139], v[136:137]
	v_rcp_f32_e32 v136, v211
	v_rcp_f32_e32 v137, v182
	v_lshlrev_b32_e32 v212, 16, v183
	v_and_b32_e32 v183, 0xffff0000, v183
	s_andn2_b64 vcc, exec, s[36:37]
	v_pk_mul_f32 v[138:139], v[136:137], v[148:149]
	s_nop 0
	v_cndmask_b32_e64 v137, v139, v137, s[36:37]
	v_cndmask_b32_e64 v136, v138, v136, s[36:37]
	v_pk_mul_f32 v[180:181], v[128:129], v[136:137]
	v_rcp_f32_e32 v128, v212
	v_rcp_f32_e32 v129, v183
	s_nop 0
	v_pk_mul_f32 v[136:137], v[128:129], v[150:151]
	s_nop 0
	v_cndmask_b32_e64 v129, v137, v129, s[36:37]
	v_cndmask_b32_e64 v128, v136, v128, s[36:37]
	v_pk_mul_f32 v[182:183], v[130:131], v[128:129]
	v_cndmask_b32_e64 v128, 0, 1, s[36:37]
	v_cmp_ne_u32_e64 s[38:39], 1, v128
	v_or_b32_e32 v128, 16, v242
	v_lshl_add_u32 v214, s52, 8, v128
	s_cbranch_vccnz .LBB0_118
	v_ashrrev_i32_e32 v215, 31, v214
	v_readlane_b32 s4, v253, 16
	v_lshlrev_b64 v[136:137], 11, v[214:215]
	v_readlane_b32 s6, v253, 18
	v_readlane_b32 s7, v253, 19
	v_ashrrev_i32_e32 v207, 31, v206
	v_cvt_pk_bf16_f32 v128, v176, v177
	v_cvt_pk_bf16_f32 v129, v178, v179
	v_cvt_pk_bf16_f32 v130, v180, v181
	v_cvt_pk_bf16_f32 v131, v182, v183
	s_nop 0
	v_lshl_add_u64 v[136:137], s[6:7], 0, v[136:137]
	v_lshl_add_u64 v[136:137], v[206:207], 1, v[136:137]
	v_readlane_b32 s5, v253, 17
	v_readlane_b32 s8, v253, 20
	v_readlane_b32 s9, v253, 21
	v_readlane_b32 s10, v253, 22
	v_readlane_b32 s11, v253, 23
	v_readlane_b32 s12, v253, 24
	v_readlane_b32 s13, v253, 25
	v_readlane_b32 s14, v253, 26
	v_readlane_b32 s15, v253, 27
	v_readlane_b32 s16, v253, 28
	v_readlane_b32 s17, v253, 29
	v_readlane_b32 s18, v253, 30
	v_readlane_b32 s19, v253, 31
	global_store_dwordx4 v[136:137], v[128:131], off sc1
.LBB0_118:
	s_waitcnt vmcnt(9)
	v_lshlrev_b32_e32 v144, 16, v168
	v_and_b32_e32 v145, 0xffff0000, v168
	v_rcp_f32_e32 v144, v144
	v_rcp_f32_e32 v145, v145
	v_lshlrev_b32_e32 v128, 16, v172
	v_and_b32_e32 v129, 0xffff0000, v172
	v_lshlrev_b32_e32 v146, 16, v169
	v_pk_mul_f32 v[128:129], v[144:145], v[128:129]
	v_and_b32_e32 v147, 0xffff0000, v169
	v_cndmask_b32_e64 v129, v129, v145, s[36:37]
	v_cndmask_b32_e64 v128, v128, v144, s[36:37]
	v_pk_mul_f32 v[168:169], v[124:125], v[128:129]
	v_rcp_f32_e32 v124, v146
	v_rcp_f32_e32 v125, v147
	v_lshlrev_b32_e32 v130, 16, v173
	v_and_b32_e32 v131, 0xffff0000, v173
	v_lshlrev_b32_e32 v148, 16, v170
	v_pk_mul_f32 v[128:129], v[124:125], v[130:131]
	v_and_b32_e32 v149, 0xffff0000, v170
	v_cndmask_b32_e64 v125, v129, v125, s[36:37]
	v_cndmask_b32_e64 v124, v128, v124, s[36:37]
	v_lshlrev_b32_e32 v150, 16, v171
	v_and_b32_e32 v151, 0xffff0000, v171
	v_pk_mul_f32 v[170:171], v[126:127], v[124:125]
	v_rcp_f32_e32 v124, v148
	v_rcp_f32_e32 v125, v149
	v_lshlrev_b32_e32 v136, 16, v174
	v_and_b32_e32 v137, 0xffff0000, v174
	v_lshlrev_b32_e32 v138, 16, v175
	v_pk_mul_f32 v[126:127], v[124:125], v[136:137]
	v_and_b32_e32 v139, 0xffff0000, v175
	v_cndmask_b32_e64 v125, v127, v125, s[36:37]
	v_cndmask_b32_e64 v124, v126, v124, s[36:37]
	v_pk_mul_f32 v[172:173], v[112:113], v[124:125]
	v_rcp_f32_e32 v112, v150
	v_rcp_f32_e32 v113, v151
	s_and_b64 vcc, exec, s[38:39]
	v_pk_mul_f32 v[124:125], v[112:113], v[138:139]
	s_nop 0
	v_cndmask_b32_e64 v113, v125, v113, s[36:37]
	v_cndmask_b32_e64 v112, v124, v112, s[36:37]
	v_pk_mul_f32 v[174:175], v[114:115], v[112:113]
	v_or_b32_e32 v112, 32, v242
	v_lshl_add_u32 v212, s52, 8, v112
	s_cbranch_vccnz .LBB0_120
	v_ashrrev_i32_e32 v213, 31, v212
	v_readlane_b32 s4, v253, 16
	v_lshlrev_b64 v[124:125], 11, v[212:213]
	v_readlane_b32 s6, v253, 18
	v_readlane_b32 s7, v253, 19
	v_ashrrev_i32_e32 v207, 31, v206
	v_cvt_pk_bf16_f32 v112, v168, v169
	v_cvt_pk_bf16_f32 v113, v170, v171
	v_cvt_pk_bf16_f32 v114, v172, v173
	v_cvt_pk_bf16_f32 v115, v174, v175
	s_nop 0
	v_lshl_add_u64 v[124:125], s[6:7], 0, v[124:125]
	v_lshl_add_u64 v[124:125], v[206:207], 1, v[124:125]
	v_readlane_b32 s5, v253, 17
	v_readlane_b32 s8, v253, 20
	v_readlane_b32 s9, v253, 21
	v_readlane_b32 s10, v253, 22
	v_readlane_b32 s11, v253, 23
	v_readlane_b32 s12, v253, 24
	v_readlane_b32 s13, v253, 25
	v_readlane_b32 s14, v253, 26
	v_readlane_b32 s15, v253, 27
	v_readlane_b32 s16, v253, 28
	v_readlane_b32 s17, v253, 29
	v_readlane_b32 s18, v253, 30
	v_readlane_b32 s19, v253, 31
	global_store_dwordx4 v[124:125], v[112:115], off sc1
.LBB0_120:
	s_waitcnt vmcnt(5)
	v_lshlrev_b32_e32 v128, 16, v164
	v_and_b32_e32 v129, 0xffff0000, v164
	v_rcp_f32_e32 v128, v128
	v_rcp_f32_e32 v129, v129
	v_lshlrev_b32_e32 v112, 16, v160
	v_and_b32_e32 v113, 0xffff0000, v160
	v_lshlrev_b32_e32 v130, 16, v165
	v_pk_mul_f32 v[112:113], v[128:129], v[112:113]
	v_and_b32_e32 v131, 0xffff0000, v165
	v_cndmask_b32_e64 v113, v113, v129, s[36:37]
	v_cndmask_b32_e64 v112, v112, v128, s[36:37]
	v_lshlrev_b32_e32 v114, 16, v161
	v_and_b32_e32 v115, 0xffff0000, v161
	v_pk_mul_f32 v[160:161], v[108:109], v[112:113]
	v_rcp_f32_e32 v108, v130
	v_rcp_f32_e32 v109, v131
	v_lshlrev_b32_e32 v136, 16, v166
	v_and_b32_e32 v137, 0xffff0000, v166
	v_lshlrev_b32_e32 v124, 16, v162
	v_pk_mul_f32 v[112:113], v[108:109], v[114:115]
	v_and_b32_e32 v125, 0xffff0000, v162
	v_cndmask_b32_e64 v109, v113, v109, s[36:37]
	v_cndmask_b32_e64 v108, v112, v108, s[36:37]
	v_lshlrev_b32_e32 v126, 16, v163
	v_and_b32_e32 v127, 0xffff0000, v163
	v_pk_mul_f32 v[162:163], v[110:111], v[108:109]
	v_rcp_f32_e32 v108, v136
	v_rcp_f32_e32 v109, v137
	v_lshlrev_b32_e32 v138, 16, v167
	v_and_b32_e32 v139, 0xffff0000, v167
	s_and_b64 vcc, exec, s[38:39]
	v_pk_mul_f32 v[110:111], v[108:109], v[124:125]
	v_lshl_add_u32 v210, s52, 8, v246
	v_cndmask_b32_e64 v109, v111, v109, s[36:37]
	v_cndmask_b32_e64 v108, v110, v108, s[36:37]
	v_pk_mul_f32 v[164:165], v[96:97], v[108:109]
	v_rcp_f32_e32 v96, v138
	v_rcp_f32_e32 v97, v139
	s_nop 0
	v_pk_mul_f32 v[108:109], v[96:97], v[126:127]
	s_nop 0
	v_cndmask_b32_e64 v97, v109, v97, s[36:37]
	v_cndmask_b32_e64 v96, v108, v96, s[36:37]
	v_pk_mul_f32 v[166:167], v[98:99], v[96:97]
	s_cbranch_vccnz .LBB0_122
	v_ashrrev_i32_e32 v211, 31, v210
	v_readlane_b32 s4, v253, 16
	v_lshlrev_b64 v[108:109], 11, v[210:211]
	v_readlane_b32 s6, v253, 18
	v_readlane_b32 s7, v253, 19
	v_ashrrev_i32_e32 v207, 31, v206
	v_cvt_pk_bf16_f32 v96, v160, v161
	v_cvt_pk_bf16_f32 v97, v162, v163
	v_cvt_pk_bf16_f32 v98, v164, v165
	v_cvt_pk_bf16_f32 v99, v166, v167
	s_nop 0
	v_lshl_add_u64 v[108:109], s[6:7], 0, v[108:109]
	v_lshl_add_u64 v[108:109], v[206:207], 1, v[108:109]
	v_readlane_b32 s5, v253, 17
	v_readlane_b32 s8, v253, 20
	v_readlane_b32 s9, v253, 21
	v_readlane_b32 s10, v253, 22
	v_readlane_b32 s11, v253, 23
	v_readlane_b32 s12, v253, 24
	v_readlane_b32 s13, v253, 25
	v_readlane_b32 s14, v253, 26
	v_readlane_b32 s15, v253, 27
	v_readlane_b32 s16, v253, 28
	v_readlane_b32 s17, v253, 29
	v_readlane_b32 s18, v253, 30
	v_readlane_b32 s19, v253, 31
	global_store_dwordx4 v[108:109], v[96:99], off sc1
.LBB0_122:
	s_mov_b64 s[22:23], 0x100000
	s_nop 0
	v_lshl_add_u64 v[96:97], v[208:209], 0, s[22:23]
	v_add_co_u32_e32 v98, vcc, 0x100000, v208
	v_lshl_add_u64 v[96:97], v[96:97], 0, s[88:89]
	s_nop 0
	v_addc_co_u32_e32 v99, vcc, 0, v209, vcc
	s_mov_b64 s[22:23], 0x120000
	global_load_dwordx4 v[144:147], v[98:99], off
	global_load_dwordx4 v[148:151], v[96:97], off
	v_lshl_add_u64 v[96:97], v[208:209], 0, s[22:23]
	v_add_co_u32_e32 v98, vcc, 0x120000, v208
	v_lshl_add_u64 v[96:97], v[96:97], 0, s[88:89]
	s_nop 0
	v_addc_co_u32_e32 v99, vcc, 0, v209, vcc
	s_mov_b64 s[22:23], 0x140000
	global_load_dwordx4 v[128:131], v[98:99], off
	global_load_dwordx4 v[136:139], v[96:97], off
	v_lshl_add_u64 v[96:97], v[208:209], 0, s[22:23]
	v_add_co_u32_e32 v98, vcc, 0x140000, v208
	v_lshl_add_u64 v[96:97], v[96:97], 0, s[88:89]
	s_nop 0
	v_addc_co_u32_e32 v99, vcc, 0, v209, vcc
	s_mov_b64 s[22:23], 0x160000
	global_load_dwordx4 v[112:115], v[98:99], off
	global_load_dwordx4 v[124:127], v[96:97], off
	v_lshl_add_u64 v[108:109], v[208:209], 0, s[22:23]
	v_add_co_u32_e32 v96, vcc, 0x160000, v208
	v_lshl_add_u64 v[108:109], v[108:109], 0, s[88:89]
	s_nop 0
	v_addc_co_u32_e32 v97, vcc, 0, v209, vcc
	global_load_dwordx4 v[96:99], v[96:97], off
	s_waitcnt vmcnt(10)
	v_lshlrev_b32_e32 v207, 16, v156
	global_load_dwordx4 v[108:111], v[108:109], off
	v_and_b32_e32 v211, 0xffff0000, v156
	v_lshlrev_b32_e32 v213, 16, v157
	v_and_b32_e32 v215, 0xffff0000, v157
	v_lshlrev_b32_e32 v217, 16, v158
	v_and_b32_e32 v251, 0xffff0000, v158
	v_lshlrev_b32_e32 v252, 16, v159
	v_and_b32_e32 v234, 0xffff0000, v159
	v_lshlrev_b32_e32 v156, 16, v152
	v_and_b32_e32 v157, 0xffff0000, v152
	v_lshlrev_b32_e32 v158, 16, v153
	v_and_b32_e32 v159, 0xffff0000, v153
	v_rcp_f32_e32 v152, v207
	v_rcp_f32_e32 v153, v211
	v_lshlrev_b32_e32 v230, 16, v154
	v_and_b32_e32 v231, 0xffff0000, v154
	v_lshlrev_b32_e32 v232, 16, v155
	v_and_b32_e32 v233, 0xffff0000, v155
	v_pk_mul_f32 v[154:155], v[152:153], v[156:157]
	s_and_b64 vcc, exec, s[38:39]
	v_cndmask_b32_e64 v153, v155, v153, s[36:37]
	v_cndmask_b32_e64 v152, v154, v152, s[36:37]
	v_pk_mul_f32 v[152:153], v[92:93], v[152:153]
	v_rcp_f32_e32 v92, v213
	v_rcp_f32_e32 v93, v215
	s_nop 0
	v_pk_mul_f32 v[154:155], v[92:93], v[158:159]
	s_nop 0
	v_cndmask_b32_e64 v93, v155, v93, s[36:37]
	v_cndmask_b32_e64 v92, v154, v92, s[36:37]
	v_pk_mul_f32 v[154:155], v[94:95], v[92:93]
	v_rcp_f32_e32 v92, v217
	v_rcp_f32_e32 v93, v251
	s_nop 0
	v_pk_mul_f32 v[94:95], v[92:93], v[230:231]
	s_nop 0
	v_cndmask_b32_e64 v93, v95, v93, s[36:37]
	v_cndmask_b32_e64 v92, v94, v92, s[36:37]
	v_pk_mul_f32 v[156:157], v[88:89], v[92:93]
	v_rcp_f32_e32 v88, v252
	v_rcp_f32_e32 v89, v234
	s_nop 0
	v_pk_mul_f32 v[92:93], v[88:89], v[232:233]
	s_nop 0
	v_cndmask_b32_e64 v89, v93, v89, s[36:37]
	v_cndmask_b32_e64 v88, v92, v88, s[36:37]
	v_pk_mul_f32 v[158:159], v[90:91], v[88:89]
	s_cbranch_vccnz .LBB0_124
	s_lshl_b32 s22, s55, 8
	v_ashrrev_i32_e32 v217, 31, v216
	v_readlane_b32 s4, v253, 16
	v_lshlrev_b64 v[92:93], 11, v[216:217]
	v_readlane_b32 s6, v253, 18
	v_readlane_b32 s7, v253, 19
	s_ashr_i32 s23, s22, 31
	v_mov_b32_e32 v95, s23
	v_lshl_add_u64 v[92:93], s[6:7], 0, v[92:93]
	v_or_b32_e32 v94, s22, v192
	v_lshl_add_u64 v[92:93], v[94:95], 1, v[92:93]
	v_cvt_pk_bf16_f32 v88, v152, v153
	v_cvt_pk_bf16_f32 v89, v154, v155
	v_cvt_pk_bf16_f32 v90, v156, v157
	v_cvt_pk_bf16_f32 v91, v158, v159
	v_readlane_b32 s5, v253, 17
	v_readlane_b32 s8, v253, 20
	v_readlane_b32 s9, v253, 21
	v_readlane_b32 s10, v253, 22
	v_readlane_b32 s11, v253, 23
	v_readlane_b32 s12, v253, 24
	v_readlane_b32 s13, v253, 25
	v_readlane_b32 s14, v253, 26
	v_readlane_b32 s15, v253, 27
	v_readlane_b32 s16, v253, 28
	v_readlane_b32 s17, v253, 29
	v_readlane_b32 s18, v253, 30
	v_readlane_b32 s19, v253, 31
	global_store_dwordx4 v[92:93], v[88:91], off offset:256 sc1
.LBB0_124:
	v_lshlrev_b32_e32 v207, 16, v140
	v_and_b32_e32 v140, 0xffff0000, v140
	v_lshlrev_b32_e32 v88, 16, v132
	v_and_b32_e32 v89, 0xffff0000, v132
	v_lshlrev_b32_e32 v90, 16, v133
	v_and_b32_e32 v91, 0xffff0000, v133
	v_rcp_f32_e32 v132, v207
	v_rcp_f32_e32 v133, v140
	v_lshlrev_b32_e32 v211, 16, v141
	v_and_b32_e32 v141, 0xffff0000, v141
	v_lshlrev_b32_e32 v213, 16, v142
	v_pk_mul_f32 v[88:89], v[132:133], v[88:89]
	v_and_b32_e32 v142, 0xffff0000, v142
	v_cndmask_b32_e64 v89, v89, v133, s[36:37]
	v_cndmask_b32_e64 v88, v88, v132, s[36:37]
	v_pk_mul_f32 v[132:133], v[84:85], v[88:89]
	v_rcp_f32_e32 v84, v211
	v_rcp_f32_e32 v85, v141
	v_lshlrev_b32_e32 v92, 16, v134
	v_and_b32_e32 v93, 0xffff0000, v134
	v_lshlrev_b32_e32 v94, 16, v135
	v_pk_mul_f32 v[88:89], v[84:85], v[90:91]
	v_and_b32_e32 v95, 0xffff0000, v135
	v_cndmask_b32_e64 v85, v89, v85, s[36:37]
	v_cndmask_b32_e64 v84, v88, v84, s[36:37]
	v_pk_mul_f32 v[134:135], v[86:87], v[84:85]
	v_rcp_f32_e32 v84, v213
	v_rcp_f32_e32 v85, v142
	v_lshlrev_b32_e32 v215, 16, v143
	v_and_b32_e32 v143, 0xffff0000, v143
	s_and_b64 vcc, exec, s[38:39]
	v_pk_mul_f32 v[86:87], v[84:85], v[92:93]
	s_nop 0
	v_cndmask_b32_e64 v85, v87, v85, s[36:37]
	v_cndmask_b32_e64 v84, v86, v84, s[36:37]
	v_pk_mul_f32 v[140:141], v[80:81], v[84:85]
	v_rcp_f32_e32 v80, v215
	v_rcp_f32_e32 v81, v143
	s_nop 0
	v_pk_mul_f32 v[84:85], v[80:81], v[94:95]
	s_nop 0
	v_cndmask_b32_e64 v81, v85, v81, s[36:37]
	v_cndmask_b32_e64 v80, v84, v80, s[36:37]
	v_pk_mul_f32 v[142:143], v[82:83], v[80:81]
	s_cbranch_vccnz .LBB0_126
	s_lshl_b32 s22, s55, 8
	v_ashrrev_i32_e32 v215, 31, v214
	v_readlane_b32 s4, v253, 16
	v_lshlrev_b64 v[84:85], 11, v[214:215]
	v_readlane_b32 s6, v253, 18
	v_readlane_b32 s7, v253, 19
	s_ashr_i32 s23, s22, 31
	v_mov_b32_e32 v87, s23
	v_lshl_add_u64 v[84:85], s[6:7], 0, v[84:85]
	v_or_b32_e32 v86, s22, v192
	v_lshl_add_u64 v[84:85], v[86:87], 1, v[84:85]
	v_cvt_pk_bf16_f32 v80, v132, v133
	v_cvt_pk_bf16_f32 v81, v134, v135
	v_cvt_pk_bf16_f32 v82, v140, v141
	v_cvt_pk_bf16_f32 v83, v142, v143
	v_readlane_b32 s5, v253, 17
	v_readlane_b32 s8, v253, 20
	v_readlane_b32 s9, v253, 21
	v_readlane_b32 s10, v253, 22
	v_readlane_b32 s11, v253, 23
	v_readlane_b32 s12, v253, 24
	v_readlane_b32 s13, v253, 25
	v_readlane_b32 s14, v253, 26
	v_readlane_b32 s15, v253, 27
	v_readlane_b32 s16, v253, 28
	v_readlane_b32 s17, v253, 29
	v_readlane_b32 s18, v253, 30
	v_readlane_b32 s19, v253, 31
	global_store_dwordx4 v[84:85], v[80:83], off offset:256 sc1
.LBB0_126:
	s_waitcnt vmcnt(10)
	v_lshlrev_b32_e32 v88, 16, v120
	v_and_b32_e32 v89, 0xffff0000, v120
	v_rcp_f32_e32 v88, v88
	v_rcp_f32_e32 v89, v89
	v_lshlrev_b32_e32 v80, 16, v116
	v_and_b32_e32 v81, 0xffff0000, v116
	v_lshlrev_b32_e32 v90, 16, v121
	v_pk_mul_f32 v[80:81], v[88:89], v[80:81]
	v_and_b32_e32 v91, 0xffff0000, v121
	v_cndmask_b32_e64 v81, v81, v89, s[36:37]
	v_cndmask_b32_e64 v80, v80, v88, s[36:37]
	v_lshlrev_b32_e32 v82, 16, v117
	v_and_b32_e32 v83, 0xffff0000, v117
	v_pk_mul_f32 v[116:117], v[76:77], v[80:81]
	v_rcp_f32_e32 v76, v90
	v_rcp_f32_e32 v77, v91
	v_lshlrev_b32_e32 v92, 16, v122
	v_and_b32_e32 v93, 0xffff0000, v122
	v_lshlrev_b32_e32 v84, 16, v118
	v_pk_mul_f32 v[80:81], v[76:77], v[82:83]
	v_and_b32_e32 v85, 0xffff0000, v118
	v_cndmask_b32_e64 v77, v81, v77, s[36:37]
	v_cndmask_b32_e64 v76, v80, v76, s[36:37]
	v_lshlrev_b32_e32 v86, 16, v119
	v_and_b32_e32 v87, 0xffff0000, v119
	v_pk_mul_f32 v[118:119], v[78:79], v[76:77]
	v_rcp_f32_e32 v76, v92
	v_rcp_f32_e32 v77, v93
	v_lshlrev_b32_e32 v94, 16, v123
	v_and_b32_e32 v95, 0xffff0000, v123
	s_and_b64 vcc, exec, s[38:39]
	v_pk_mul_f32 v[78:79], v[76:77], v[84:85]
	s_nop 0
	v_cndmask_b32_e64 v77, v79, v77, s[36:37]
	v_cndmask_b32_e64 v76, v78, v76, s[36:37]
	v_pk_mul_f32 v[120:121], v[72:73], v[76:77]
	v_rcp_f32_e32 v72, v94
	v_rcp_f32_e32 v73, v95
	s_nop 0
	v_pk_mul_f32 v[76:77], v[72:73], v[86:87]
	s_nop 0
	v_cndmask_b32_e64 v73, v77, v73, s[36:37]
	v_cndmask_b32_e64 v72, v76, v72, s[36:37]
	v_pk_mul_f32 v[122:123], v[74:75], v[72:73]
	s_cbranch_vccnz .LBB0_128
	s_lshl_b32 s22, s55, 8
	v_ashrrev_i32_e32 v213, 31, v212
	v_readlane_b32 s4, v253, 16
	v_lshlrev_b64 v[76:77], 11, v[212:213]
	v_readlane_b32 s6, v253, 18
	v_readlane_b32 s7, v253, 19
	s_ashr_i32 s23, s22, 31
	v_mov_b32_e32 v79, s23
	v_lshl_add_u64 v[76:77], s[6:7], 0, v[76:77]
	v_or_b32_e32 v78, s22, v192
	v_lshl_add_u64 v[76:77], v[78:79], 1, v[76:77]
	v_cvt_pk_bf16_f32 v72, v116, v117
	v_cvt_pk_bf16_f32 v73, v118, v119
	v_cvt_pk_bf16_f32 v74, v120, v121
	v_cvt_pk_bf16_f32 v75, v122, v123
	v_readlane_b32 s5, v253, 17
	v_readlane_b32 s8, v253, 20
	v_readlane_b32 s9, v253, 21
	v_readlane_b32 s10, v253, 22
	v_readlane_b32 s11, v253, 23
	v_readlane_b32 s12, v253, 24
	v_readlane_b32 s13, v253, 25
	v_readlane_b32 s14, v253, 26
	v_readlane_b32 s15, v253, 27
	v_readlane_b32 s16, v253, 28
	v_readlane_b32 s17, v253, 29
	v_readlane_b32 s18, v253, 30
	v_readlane_b32 s19, v253, 31
	global_store_dwordx4 v[76:77], v[72:75], off offset:256 sc1
.LBB0_128:
	s_waitcnt vmcnt(8)
	v_lshlrev_b32_e32 v80, 16, v104
	v_and_b32_e32 v81, 0xffff0000, v104
	v_rcp_f32_e32 v80, v80
	v_rcp_f32_e32 v81, v81
	v_lshlrev_b32_e32 v72, 16, v100
	v_and_b32_e32 v73, 0xffff0000, v100
	v_lshlrev_b32_e32 v82, 16, v105
	v_pk_mul_f32 v[72:73], v[80:81], v[72:73]
	v_and_b32_e32 v83, 0xffff0000, v105
	v_cndmask_b32_e64 v73, v73, v81, s[36:37]
	v_cndmask_b32_e64 v72, v72, v80, s[36:37]
	v_lshlrev_b32_e32 v74, 16, v101
	v_and_b32_e32 v75, 0xffff0000, v101
	v_pk_mul_f32 v[100:101], v[68:69], v[72:73]
	v_rcp_f32_e32 v68, v82
	v_rcp_f32_e32 v69, v83
	v_lshlrev_b32_e32 v84, 16, v106
	v_and_b32_e32 v85, 0xffff0000, v106
	v_lshlrev_b32_e32 v76, 16, v102
	v_pk_mul_f32 v[72:73], v[68:69], v[74:75]
	v_and_b32_e32 v77, 0xffff0000, v102
	v_cndmask_b32_e64 v69, v73, v69, s[36:37]
	v_cndmask_b32_e64 v68, v72, v68, s[36:37]
	v_lshlrev_b32_e32 v78, 16, v103
	v_and_b32_e32 v79, 0xffff0000, v103
	v_pk_mul_f32 v[102:103], v[70:71], v[68:69]
	v_rcp_f32_e32 v68, v84
	v_rcp_f32_e32 v69, v85
	v_lshlrev_b32_e32 v86, 16, v107
	v_and_b32_e32 v87, 0xffff0000, v107
	s_and_b64 vcc, exec, s[38:39]
	v_pk_mul_f32 v[70:71], v[68:69], v[76:77]
	s_nop 0
	v_cndmask_b32_e64 v69, v71, v69, s[36:37]
	v_cndmask_b32_e64 v68, v70, v68, s[36:37]
	v_pk_mul_f32 v[104:105], v[64:65], v[68:69]
	v_rcp_f32_e32 v64, v86
	v_rcp_f32_e32 v65, v87
	s_nop 0
	v_pk_mul_f32 v[68:69], v[64:65], v[78:79]
	s_nop 0
	v_cndmask_b32_e64 v65, v69, v65, s[36:37]
	v_cndmask_b32_e64 v64, v68, v64, s[36:37]
	v_pk_mul_f32 v[106:107], v[66:67], v[64:65]
	s_cbranch_vccnz .LBB0_130
	s_lshl_b32 s22, s55, 8
	v_ashrrev_i32_e32 v211, 31, v210
	v_readlane_b32 s4, v253, 16
	v_lshlrev_b64 v[68:69], 11, v[210:211]
	v_readlane_b32 s6, v253, 18
	v_readlane_b32 s7, v253, 19
	s_ashr_i32 s23, s22, 31
	v_mov_b32_e32 v71, s23
	v_lshl_add_u64 v[68:69], s[6:7], 0, v[68:69]
	v_or_b32_e32 v70, s22, v192
	v_lshl_add_u64 v[68:69], v[70:71], 1, v[68:69]
	v_cvt_pk_bf16_f32 v64, v100, v101
	v_cvt_pk_bf16_f32 v65, v102, v103
	v_cvt_pk_bf16_f32 v66, v104, v105
	v_cvt_pk_bf16_f32 v67, v106, v107
	v_readlane_b32 s5, v253, 17
	v_readlane_b32 s8, v253, 20
	v_readlane_b32 s9, v253, 21
	v_readlane_b32 s10, v253, 22
	v_readlane_b32 s11, v253, 23
	v_readlane_b32 s12, v253, 24
	v_readlane_b32 s13, v253, 25
	v_readlane_b32 s14, v253, 26
	v_readlane_b32 s15, v253, 27
	v_readlane_b32 s16, v253, 28
	v_readlane_b32 s17, v253, 29
	v_readlane_b32 s18, v253, 30
	v_readlane_b32 s19, v253, 31
	global_store_dwordx4 v[68:69], v[64:67], off offset:256 sc1
.LBB0_130:
	s_mov_b64 s[22:23], 0x101000
	s_nop 0
	v_lshl_add_u64 v[64:65], v[208:209], 0, s[22:23]
	v_add_co_u32_e32 v66, vcc, 0x101000, v208
	v_lshl_add_u64 v[64:65], v[64:65], 0, s[88:89]
	s_nop 0
	v_addc_co_u32_e32 v67, vcc, 0, v209, vcc
	s_mov_b64 s[22:23], 0x121000
	global_load_dwordx4 v[88:91], v[66:67], off
	global_load_dwordx4 v[92:95], v[64:65], off
	v_lshl_add_u64 v[64:65], v[208:209], 0, s[22:23]
	v_add_co_u32_e32 v66, vcc, 0x121000, v208
	v_lshl_add_u64 v[64:65], v[64:65], 0, s[88:89]
	s_nop 0
	v_addc_co_u32_e32 v67, vcc, 0, v209, vcc
	s_mov_b64 s[22:23], 0x141000
	global_load_dwordx4 v[80:83], v[66:67], off
	global_load_dwordx4 v[84:87], v[64:65], off
	v_lshl_add_u64 v[64:65], v[208:209], 0, s[22:23]
	v_add_co_u32_e32 v66, vcc, 0x141000, v208
	v_lshl_add_u64 v[64:65], v[64:65], 0, s[88:89]
	s_nop 0
	v_addc_co_u32_e32 v67, vcc, 0, v209, vcc
	s_mov_b64 s[22:23], 0x161000
	global_load_dwordx4 v[72:75], v[66:67], off
	global_load_dwordx4 v[76:79], v[64:65], off
	v_lshl_add_u64 v[68:69], v[208:209], 0, s[22:23]
	v_add_co_u32_e32 v64, vcc, 0x161000, v208
	v_lshl_add_u64 v[68:69], v[68:69], 0, s[88:89]
	s_nop 0
	v_addc_co_u32_e32 v65, vcc, 0, v209, vcc
	global_load_dwordx4 v[64:67], v[64:65], off
	s_waitcnt vmcnt(13)
	v_lshlrev_b32_e32 v207, 16, v144
	global_load_dwordx4 v[68:71], v[68:69], off
	v_and_b32_e32 v209, 0xffff0000, v144
	v_rcp_f32_e32 v208, v207
	v_rcp_f32_e32 v209, v209
	v_lshlrev_b32_e32 v210, 16, v145
	v_and_b32_e32 v211, 0xffff0000, v145
	v_lshlrev_b32_e32 v144, 16, v148
	v_and_b32_e32 v145, 0xffff0000, v148
	v_pk_mul_f32 v[144:145], v[208:209], v[144:145]
	v_lshlrev_b32_e32 v212, 16, v146
	v_cndmask_b32_e64 v145, v145, v209, s[36:37]
	v_cndmask_b32_e64 v144, v144, v208, s[36:37]
	v_pk_mul_f32 v[60:61], v[60:61], v[144:145]
	v_rcp_f32_e32 v144, v210
	v_rcp_f32_e32 v145, v211
	v_and_b32_e32 v213, 0xffff0000, v146
	v_lshlrev_b32_e32 v214, 16, v147
	v_and_b32_e32 v215, 0xffff0000, v147
	v_lshlrev_b32_e32 v146, 16, v149
	v_and_b32_e32 v147, 0xffff0000, v149
	v_pk_mul_f32 v[146:147], v[144:145], v[146:147]
	v_lshlrev_b32_e32 v148, 16, v150
	v_cndmask_b32_e64 v145, v147, v145, s[36:37]
	v_cndmask_b32_e64 v144, v146, v144, s[36:37]
	v_pk_mul_f32 v[62:63], v[62:63], v[144:145]
	v_rcp_f32_e32 v144, v212
	v_rcp_f32_e32 v145, v213
	v_and_b32_e32 v149, 0xffff0000, v150
	v_lshlrev_b32_e32 v150, 16, v151
	v_and_b32_e32 v151, 0xffff0000, v151
	v_pk_mul_f32 v[146:147], v[144:145], v[148:149]
	s_and_b64 vcc, exec, s[38:39]
	v_cndmask_b32_e64 v145, v147, v145, s[36:37]
	v_cndmask_b32_e64 v144, v146, v144, s[36:37]
	v_pk_mul_f32 v[56:57], v[56:57], v[144:145]
	v_rcp_f32_e32 v144, v214
	v_rcp_f32_e32 v145, v215
	s_nop 0
	v_pk_mul_f32 v[146:147], v[144:145], v[150:151]
	s_nop 0
	v_cndmask_b32_e64 v145, v147, v145, s[36:37]
	v_cndmask_b32_e64 v144, v146, v144, s[36:37]
	v_pk_mul_f32 v[58:59], v[58:59], v[144:145]
	v_lshl_add_u32 v144, s52, 8, v247
	s_cbranch_vccnz .LBB0_132
	v_ashrrev_i32_e32 v145, 31, v144
	v_readlane_b32 s4, v253, 16
	v_lshlrev_b64 v[150:151], 11, v[144:145]
	v_readlane_b32 s6, v253, 18
	v_readlane_b32 s7, v253, 19
	v_ashrrev_i32_e32 v207, 31, v206
	v_cvt_pk_bf16_f32 v146, v60, v61
	v_cvt_pk_bf16_f32 v147, v62, v63
	v_cvt_pk_bf16_f32 v148, v56, v57
	v_cvt_pk_bf16_f32 v149, v58, v59
	s_nop 0
	v_lshl_add_u64 v[150:151], s[6:7], 0, v[150:151]
	v_lshl_add_u64 v[150:151], v[206:207], 1, v[150:151]
	v_readlane_b32 s5, v253, 17
	v_readlane_b32 s8, v253, 20
	v_readlane_b32 s9, v253, 21
	v_readlane_b32 s10, v253, 22
	v_readlane_b32 s11, v253, 23
	v_readlane_b32 s12, v253, 24
	v_readlane_b32 s13, v253, 25
	v_readlane_b32 s14, v253, 26
	v_readlane_b32 s15, v253, 27
	v_readlane_b32 s16, v253, 28
	v_readlane_b32 s17, v253, 29
	v_readlane_b32 s18, v253, 30
	v_readlane_b32 s19, v253, 31
	global_store_dwordx4 v[150:151], v[146:149], off sc1
.LBB0_132:
	s_waitcnt vmcnt(12)
	v_lshlrev_b32_e32 v145, 16, v128
	s_nop 0
	v_and_b32_e32 v147, 0xffff0000, v128
	v_rcp_f32_e32 v146, v145
	v_rcp_f32_e32 v147, v147
	v_lshlrev_b32_e32 v148, 16, v129
	v_and_b32_e32 v149, 0xffff0000, v129
	v_lshlrev_b32_e32 v128, 16, v136
	v_and_b32_e32 v129, 0xffff0000, v136
	v_pk_mul_f32 v[128:129], v[146:147], v[128:129]
	v_lshlrev_b32_e32 v150, 16, v130
	v_cndmask_b32_e64 v129, v129, v147, s[36:37]
	v_cndmask_b32_e64 v128, v128, v146, s[36:37]
	v_pk_mul_f32 v[52:53], v[52:53], v[128:129]
	v_rcp_f32_e32 v128, v148
	v_rcp_f32_e32 v129, v149
	v_and_b32_e32 v151, 0xffff0000, v130
	v_lshlrev_b32_e32 v207, 16, v131
	v_and_b32_e32 v208, 0xffff0000, v131
	v_lshlrev_b32_e32 v130, 16, v137
	v_and_b32_e32 v131, 0xffff0000, v137
	v_pk_mul_f32 v[130:131], v[128:129], v[130:131]
	v_lshlrev_b32_e32 v136, 16, v138
	v_cndmask_b32_e64 v129, v131, v129, s[36:37]
	v_cndmask_b32_e64 v128, v130, v128, s[36:37]
	v_pk_mul_f32 v[54:55], v[54:55], v[128:129]
	v_rcp_f32_e32 v128, v150
	v_rcp_f32_e32 v129, v151
	v_and_b32_e32 v137, 0xffff0000, v138
	v_lshlrev_b32_e32 v138, 16, v139
	v_and_b32_e32 v139, 0xffff0000, v139
	v_pk_mul_f32 v[130:131], v[128:129], v[136:137]
	s_and_b64 vcc, exec, s[38:39]
	v_cndmask_b32_e64 v129, v131, v129, s[36:37]
	v_cndmask_b32_e64 v128, v130, v128, s[36:37]
	v_pk_mul_f32 v[48:49], v[48:49], v[128:129]
	v_rcp_f32_e32 v128, v207
	v_rcp_f32_e32 v129, v208
	s_nop 0
	v_pk_mul_f32 v[130:131], v[128:129], v[138:139]
	s_nop 0
	v_cndmask_b32_e64 v129, v131, v129, s[36:37]
	v_cndmask_b32_e64 v128, v130, v128, s[36:37]
	v_pk_mul_f32 v[50:51], v[50:51], v[128:129]
	v_lshl_add_u32 v128, s52, 8, v248
	s_cbranch_vccnz .LBB0_134
	v_ashrrev_i32_e32 v129, 31, v128
	v_readlane_b32 s4, v253, 16
	v_lshlrev_b64 v[130:131], 11, v[128:129]
	v_readlane_b32 s6, v253, 18
	v_readlane_b32 s7, v253, 19
	v_ashrrev_i32_e32 v207, 31, v206
	v_cvt_pk_bf16_f32 v136, v52, v53
	v_cvt_pk_bf16_f32 v137, v54, v55
	v_cvt_pk_bf16_f32 v138, v48, v49
	v_cvt_pk_bf16_f32 v139, v50, v51
	s_nop 0
	v_lshl_add_u64 v[130:131], s[6:7], 0, v[130:131]
	v_lshl_add_u64 v[130:131], v[206:207], 1, v[130:131]
	v_readlane_b32 s5, v253, 17
	v_readlane_b32 s8, v253, 20
	v_readlane_b32 s9, v253, 21
	v_readlane_b32 s10, v253, 22
	v_readlane_b32 s11, v253, 23
	v_readlane_b32 s12, v253, 24
	v_readlane_b32 s13, v253, 25
	v_readlane_b32 s14, v253, 26
	v_readlane_b32 s15, v253, 27
	v_readlane_b32 s16, v253, 28
	v_readlane_b32 s17, v253, 29
	v_readlane_b32 s18, v253, 30
	v_readlane_b32 s19, v253, 31
	global_store_dwordx4 v[130:131], v[136:139], off sc1
.LBB0_134:
	s_waitcnt vmcnt(10)
	v_lshlrev_b32_e32 v129, 16, v112
	v_and_b32_e32 v131, 0xffff0000, v112
	v_rcp_f32_e32 v130, v129
	v_rcp_f32_e32 v131, v131
	v_lshlrev_b32_e32 v136, 16, v113
	v_and_b32_e32 v137, 0xffff0000, v113
	v_lshlrev_b32_e32 v112, 16, v124
	v_and_b32_e32 v113, 0xffff0000, v124
	v_pk_mul_f32 v[112:113], v[130:131], v[112:113]
	v_lshlrev_b32_e32 v138, 16, v114
	v_cndmask_b32_e64 v113, v113, v131, s[36:37]
	v_cndmask_b32_e64 v112, v112, v130, s[36:37]
	v_pk_mul_f32 v[44:45], v[44:45], v[112:113]
	v_rcp_f32_e32 v112, v136
	v_rcp_f32_e32 v113, v137
	v_and_b32_e32 v139, 0xffff0000, v114
	v_lshlrev_b32_e32 v145, 16, v115
	v_and_b32_e32 v146, 0xffff0000, v115
	v_lshlrev_b32_e32 v114, 16, v125
	v_and_b32_e32 v115, 0xffff0000, v125
	v_pk_mul_f32 v[114:115], v[112:113], v[114:115]
	v_lshlrev_b32_e32 v124, 16, v126
	v_cndmask_b32_e64 v113, v115, v113, s[36:37]
	v_cndmask_b32_e64 v112, v114, v112, s[36:37]
	v_pk_mul_f32 v[46:47], v[46:47], v[112:113]
	v_rcp_f32_e32 v112, v138
	v_rcp_f32_e32 v113, v139
	v_and_b32_e32 v125, 0xffff0000, v126
	v_lshlrev_b32_e32 v126, 16, v127
	v_and_b32_e32 v127, 0xffff0000, v127
	v_pk_mul_f32 v[114:115], v[112:113], v[124:125]
	s_and_b64 vcc, exec, s[38:39]
	v_cndmask_b32_e64 v113, v115, v113, s[36:37]
	v_cndmask_b32_e64 v112, v114, v112, s[36:37]
	v_pk_mul_f32 v[40:41], v[40:41], v[112:113]
	v_rcp_f32_e32 v112, v145
	v_rcp_f32_e32 v113, v146
	s_nop 0
	v_pk_mul_f32 v[114:115], v[112:113], v[126:127]
	s_nop 0
	v_cndmask_b32_e64 v113, v115, v113, s[36:37]
	v_cndmask_b32_e64 v112, v114, v112, s[36:37]
	v_pk_mul_f32 v[42:43], v[42:43], v[112:113]
	v_lshl_add_u32 v112, s52, 8, v249
	s_cbranch_vccnz .LBB0_136
	v_ashrrev_i32_e32 v113, 31, v112
	v_readlane_b32 s4, v253, 16
	v_lshlrev_b64 v[114:115], 11, v[112:113]
	v_readlane_b32 s6, v253, 18
	v_readlane_b32 s7, v253, 19
	v_ashrrev_i32_e32 v207, 31, v206
	v_cvt_pk_bf16_f32 v124, v44, v45
	v_cvt_pk_bf16_f32 v125, v46, v47
	v_cvt_pk_bf16_f32 v126, v40, v41
	v_cvt_pk_bf16_f32 v127, v42, v43
	s_nop 0
	v_lshl_add_u64 v[114:115], s[6:7], 0, v[114:115]
	v_lshl_add_u64 v[114:115], v[206:207], 1, v[114:115]
	v_readlane_b32 s5, v253, 17
	v_readlane_b32 s8, v253, 20
	v_readlane_b32 s9, v253, 21
	v_readlane_b32 s10, v253, 22
	v_readlane_b32 s11, v253, 23
	v_readlane_b32 s12, v253, 24
	v_readlane_b32 s13, v253, 25
	v_readlane_b32 s14, v253, 26
	v_readlane_b32 s15, v253, 27
	v_readlane_b32 s16, v253, 28
	v_readlane_b32 s17, v253, 29
	v_readlane_b32 s18, v253, 30
	v_readlane_b32 s19, v253, 31
	global_store_dwordx4 v[114:115], v[124:127], off sc1
.LBB0_136:
	s_waitcnt vmcnt(8)
	v_lshlrev_b32_e32 v113, 16, v96
	v_and_b32_e32 v115, 0xffff0000, v96
	v_rcp_f32_e32 v114, v113
	v_rcp_f32_e32 v115, v115
	v_lshlrev_b32_e32 v124, 16, v97
	v_and_b32_e32 v125, 0xffff0000, v97
	v_lshlrev_b32_e32 v96, 16, v108
	v_and_b32_e32 v97, 0xffff0000, v108
	v_pk_mul_f32 v[96:97], v[114:115], v[96:97]
	v_lshlrev_b32_e32 v126, 16, v98
	v_cndmask_b32_e64 v97, v97, v115, s[36:37]
	v_cndmask_b32_e64 v96, v96, v114, s[36:37]
	v_pk_mul_f32 v[36:37], v[36:37], v[96:97]
	v_rcp_f32_e32 v96, v124
	v_rcp_f32_e32 v97, v125
	v_and_b32_e32 v127, 0xffff0000, v98
	v_lshlrev_b32_e32 v129, 16, v99
	v_and_b32_e32 v130, 0xffff0000, v99
	v_lshlrev_b32_e32 v98, 16, v109
	v_and_b32_e32 v99, 0xffff0000, v109
	v_pk_mul_f32 v[98:99], v[96:97], v[98:99]
	v_lshlrev_b32_e32 v108, 16, v110
	v_cndmask_b32_e64 v97, v99, v97, s[36:37]
	v_cndmask_b32_e64 v96, v98, v96, s[36:37]
	v_pk_mul_f32 v[38:39], v[38:39], v[96:97]
	v_rcp_f32_e32 v96, v126
	v_rcp_f32_e32 v97, v127
	v_and_b32_e32 v109, 0xffff0000, v110
	v_lshlrev_b32_e32 v110, 16, v111
	v_and_b32_e32 v111, 0xffff0000, v111
	v_pk_mul_f32 v[98:99], v[96:97], v[108:109]
	s_and_b64 vcc, exec, s[38:39]
	v_cndmask_b32_e64 v97, v99, v97, s[36:37]
	v_cndmask_b32_e64 v96, v98, v96, s[36:37]
	v_pk_mul_f32 v[32:33], v[32:33], v[96:97]
	v_rcp_f32_e32 v96, v129
	v_rcp_f32_e32 v97, v130
	s_nop 0
	v_pk_mul_f32 v[98:99], v[96:97], v[110:111]
	s_nop 0
	v_cndmask_b32_e64 v97, v99, v97, s[36:37]
	v_cndmask_b32_e64 v96, v98, v96, s[36:37]
	v_pk_mul_f32 v[34:35], v[34:35], v[96:97]
	v_lshl_add_u32 v96, s52, 8, v250
	s_cbranch_vccnz .LBB0_138
	v_ashrrev_i32_e32 v97, 31, v96
	v_readlane_b32 s4, v253, 16
	v_lshlrev_b64 v[98:99], 11, v[96:97]
	v_readlane_b32 s6, v253, 18
	v_readlane_b32 s7, v253, 19
	v_ashrrev_i32_e32 v207, 31, v206
	v_cvt_pk_bf16_f32 v108, v36, v37
	v_cvt_pk_bf16_f32 v109, v38, v39
	v_cvt_pk_bf16_f32 v110, v32, v33
	v_cvt_pk_bf16_f32 v111, v34, v35
	s_nop 0
	v_lshl_add_u64 v[98:99], s[6:7], 0, v[98:99]
	v_lshl_add_u64 v[98:99], v[206:207], 1, v[98:99]
	v_readlane_b32 s5, v253, 17
	v_readlane_b32 s8, v253, 20
	v_readlane_b32 s9, v253, 21
	v_readlane_b32 s10, v253, 22
	v_readlane_b32 s11, v253, 23
	v_readlane_b32 s12, v253, 24
	v_readlane_b32 s13, v253, 25
	v_readlane_b32 s14, v253, 26
	v_readlane_b32 s15, v253, 27
	v_readlane_b32 s16, v253, 28
	v_readlane_b32 s17, v253, 29
	v_readlane_b32 s18, v253, 30
	v_readlane_b32 s19, v253, 31
	global_store_dwordx4 v[98:99], v[108:111], off sc1
.LBB0_138:
	s_waitcnt vmcnt(6)
	v_lshlrev_b32_e32 v97, 16, v88
	v_and_b32_e32 v99, 0xffff0000, v88
	v_rcp_f32_e32 v98, v97
	v_rcp_f32_e32 v99, v99
	v_lshlrev_b32_e32 v108, 16, v89
	v_and_b32_e32 v109, 0xffff0000, v89
	v_lshlrev_b32_e32 v88, 16, v92
	v_and_b32_e32 v89, 0xffff0000, v92
	v_pk_mul_f32 v[88:89], v[98:99], v[88:89]
	v_lshlrev_b32_e32 v110, 16, v90
	v_cndmask_b32_e64 v89, v89, v99, s[36:37]
	v_cndmask_b32_e64 v88, v88, v98, s[36:37]
	v_pk_mul_f32 v[28:29], v[28:29], v[88:89]
	v_rcp_f32_e32 v88, v108
	v_rcp_f32_e32 v89, v109
	v_and_b32_e32 v111, 0xffff0000, v90
	v_lshlrev_b32_e32 v113, 16, v91
	v_and_b32_e32 v114, 0xffff0000, v91
	v_lshlrev_b32_e32 v90, 16, v93
	v_and_b32_e32 v91, 0xffff0000, v93
	v_pk_mul_f32 v[90:91], v[88:89], v[90:91]
	v_lshlrev_b32_e32 v92, 16, v94
	v_cndmask_b32_e64 v89, v91, v89, s[36:37]
	v_cndmask_b32_e64 v88, v90, v88, s[36:37]
	v_pk_mul_f32 v[30:31], v[30:31], v[88:89]
	v_rcp_f32_e32 v88, v110
	v_rcp_f32_e32 v89, v111
	v_and_b32_e32 v93, 0xffff0000, v94
	v_lshlrev_b32_e32 v94, 16, v95
	v_and_b32_e32 v95, 0xffff0000, v95
	v_pk_mul_f32 v[90:91], v[88:89], v[92:93]
	s_and_b64 vcc, exec, s[38:39]
	v_cndmask_b32_e64 v89, v91, v89, s[36:37]
	v_cndmask_b32_e64 v88, v90, v88, s[36:37]
	v_pk_mul_f32 v[24:25], v[24:25], v[88:89]
	v_rcp_f32_e32 v88, v113
	v_rcp_f32_e32 v89, v114
	s_nop 0
	v_pk_mul_f32 v[90:91], v[88:89], v[94:95]
	s_nop 0
	v_cndmask_b32_e64 v89, v91, v89, s[36:37]
	v_cndmask_b32_e64 v88, v90, v88, s[36:37]
	v_pk_mul_f32 v[26:27], v[26:27], v[88:89]
	s_cbranch_vccnz .LBB0_140
	s_lshl_b32 s22, s55, 8
	v_ashrrev_i32_e32 v145, 31, v144
	v_readlane_b32 s4, v253, 16
	v_lshlrev_b64 v[92:93], 11, v[144:145]
	v_readlane_b32 s6, v253, 18
	v_readlane_b32 s7, v253, 19
	s_ashr_i32 s23, s22, 31
	v_mov_b32_e32 v95, s23
	v_lshl_add_u64 v[92:93], s[6:7], 0, v[92:93]
	v_or_b32_e32 v94, s22, v192
	v_lshl_add_u64 v[92:93], v[94:95], 1, v[92:93]
	v_cvt_pk_bf16_f32 v88, v28, v29
	v_cvt_pk_bf16_f32 v89, v30, v31
	v_cvt_pk_bf16_f32 v90, v24, v25
	v_cvt_pk_bf16_f32 v91, v26, v27
	v_readlane_b32 s5, v253, 17
	v_readlane_b32 s8, v253, 20
	v_readlane_b32 s9, v253, 21
	v_readlane_b32 s10, v253, 22
	v_readlane_b32 s11, v253, 23
	v_readlane_b32 s12, v253, 24
	v_readlane_b32 s13, v253, 25
	v_readlane_b32 s14, v253, 26
	v_readlane_b32 s15, v253, 27
	v_readlane_b32 s16, v253, 28
	v_readlane_b32 s17, v253, 29
	v_readlane_b32 s18, v253, 30
	v_readlane_b32 s19, v253, 31
	global_store_dwordx4 v[92:93], v[88:91], off offset:256 sc1
.LBB0_140:
	s_waitcnt vmcnt(4)
	s_nop 1
	v_lshlrev_b32_e32 v88, 16, v80
	v_and_b32_e32 v89, 0xffff0000, v80
	v_rcp_f32_e32 v88, v88
	v_rcp_f32_e32 v89, v89
	v_lshlrev_b32_e32 v90, 16, v81
	v_and_b32_e32 v91, 0xffff0000, v81
	v_lshlrev_b32_e32 v80, 16, v84
	v_and_b32_e32 v81, 0xffff0000, v84
	v_pk_mul_f32 v[80:81], v[88:89], v[80:81]
	v_lshlrev_b32_e32 v92, 16, v82
	v_cndmask_b32_e64 v81, v81, v89, s[36:37]
	v_cndmask_b32_e64 v80, v80, v88, s[36:37]
	v_pk_mul_f32 v[20:21], v[20:21], v[80:81]
	v_rcp_f32_e32 v80, v90
	v_rcp_f32_e32 v81, v91
	v_and_b32_e32 v93, 0xffff0000, v82
	v_lshlrev_b32_e32 v94, 16, v83
	v_and_b32_e32 v95, 0xffff0000, v83
	v_lshlrev_b32_e32 v82, 16, v85
	v_and_b32_e32 v83, 0xffff0000, v85
	v_pk_mul_f32 v[82:83], v[80:81], v[82:83]
	v_lshlrev_b32_e32 v84, 16, v86
	v_cndmask_b32_e64 v81, v83, v81, s[36:37]
	v_cndmask_b32_e64 v80, v82, v80, s[36:37]
	v_pk_mul_f32 v[22:23], v[22:23], v[80:81]
	v_rcp_f32_e32 v80, v92
	v_rcp_f32_e32 v81, v93
	v_and_b32_e32 v85, 0xffff0000, v86
	v_lshlrev_b32_e32 v86, 16, v87
	v_and_b32_e32 v87, 0xffff0000, v87
	v_pk_mul_f32 v[82:83], v[80:81], v[84:85]
	s_and_b64 vcc, exec, s[38:39]
	v_cndmask_b32_e64 v81, v83, v81, s[36:37]
	v_cndmask_b32_e64 v80, v82, v80, s[36:37]
	v_pk_mul_f32 v[16:17], v[16:17], v[80:81]
	v_rcp_f32_e32 v80, v94
	v_rcp_f32_e32 v81, v95
	s_nop 0
	v_pk_mul_f32 v[82:83], v[80:81], v[86:87]
	s_nop 0
	v_cndmask_b32_e64 v81, v83, v81, s[36:37]
	v_cndmask_b32_e64 v80, v82, v80, s[36:37]
	v_pk_mul_f32 v[18:19], v[18:19], v[80:81]
	s_cbranch_vccnz .LBB0_142
	s_lshl_b32 s22, s55, 8
	v_ashrrev_i32_e32 v129, 31, v128
	v_readlane_b32 s4, v253, 16
	v_lshlrev_b64 v[84:85], 11, v[128:129]
	v_readlane_b32 s6, v253, 18
	v_readlane_b32 s7, v253, 19
	s_ashr_i32 s23, s22, 31
	v_mov_b32_e32 v87, s23
	v_lshl_add_u64 v[84:85], s[6:7], 0, v[84:85]
	v_or_b32_e32 v86, s22, v192
	v_lshl_add_u64 v[84:85], v[86:87], 1, v[84:85]
	v_cvt_pk_bf16_f32 v80, v20, v21
	v_cvt_pk_bf16_f32 v81, v22, v23
	v_cvt_pk_bf16_f32 v82, v16, v17
	v_cvt_pk_bf16_f32 v83, v18, v19
	v_readlane_b32 s5, v253, 17
	v_readlane_b32 s8, v253, 20
	v_readlane_b32 s9, v253, 21
	v_readlane_b32 s10, v253, 22
	v_readlane_b32 s11, v253, 23
	v_readlane_b32 s12, v253, 24
	v_readlane_b32 s13, v253, 25
	v_readlane_b32 s14, v253, 26
	v_readlane_b32 s15, v253, 27
	v_readlane_b32 s16, v253, 28
	v_readlane_b32 s17, v253, 29
	v_readlane_b32 s18, v253, 30
	v_readlane_b32 s19, v253, 31
	global_store_dwordx4 v[84:85], v[80:83], off offset:256 sc1
.LBB0_142:
	s_waitcnt vmcnt(2)
	s_nop 1
	v_lshlrev_b32_e32 v80, 16, v72
	v_and_b32_e32 v81, 0xffff0000, v72
	v_rcp_f32_e32 v80, v80
	v_rcp_f32_e32 v81, v81
	v_lshlrev_b32_e32 v82, 16, v73
	v_and_b32_e32 v83, 0xffff0000, v73
	v_lshlrev_b32_e32 v72, 16, v76
	v_and_b32_e32 v73, 0xffff0000, v76
	v_pk_mul_f32 v[72:73], v[80:81], v[72:73]
	v_lshlrev_b32_e32 v84, 16, v74
	v_cndmask_b32_e64 v73, v73, v81, s[36:37]
	v_cndmask_b32_e64 v72, v72, v80, s[36:37]
	v_pk_mul_f32 v[12:13], v[12:13], v[72:73]
	v_rcp_f32_e32 v72, v82
	v_rcp_f32_e32 v73, v83
	v_and_b32_e32 v85, 0xffff0000, v74
	v_lshlrev_b32_e32 v86, 16, v75
	v_and_b32_e32 v87, 0xffff0000, v75
	v_lshlrev_b32_e32 v74, 16, v77
	v_and_b32_e32 v75, 0xffff0000, v77
	v_pk_mul_f32 v[74:75], v[72:73], v[74:75]
	v_lshlrev_b32_e32 v76, 16, v78
	v_cndmask_b32_e64 v73, v75, v73, s[36:37]
	v_cndmask_b32_e64 v72, v74, v72, s[36:37]
	v_pk_mul_f32 v[14:15], v[14:15], v[72:73]
	v_rcp_f32_e32 v72, v84
	v_rcp_f32_e32 v73, v85
	v_and_b32_e32 v77, 0xffff0000, v78
	v_lshlrev_b32_e32 v78, 16, v79
	v_and_b32_e32 v79, 0xffff0000, v79
	v_pk_mul_f32 v[74:75], v[72:73], v[76:77]
	s_and_b64 vcc, exec, s[38:39]
	v_cndmask_b32_e64 v73, v75, v73, s[36:37]
	v_cndmask_b32_e64 v72, v74, v72, s[36:37]
	v_pk_mul_f32 v[4:5], v[4:5], v[72:73]
	v_rcp_f32_e32 v72, v86
	v_rcp_f32_e32 v73, v87
	s_nop 0
	v_pk_mul_f32 v[74:75], v[72:73], v[78:79]
	s_nop 0
	v_cndmask_b32_e64 v73, v75, v73, s[36:37]
	v_cndmask_b32_e64 v72, v74, v72, s[36:37]
	v_pk_mul_f32 v[6:7], v[6:7], v[72:73]
	s_cbranch_vccnz .LBB0_144
	s_lshl_b32 s22, s55, 8
	v_ashrrev_i32_e32 v113, 31, v112
	v_readlane_b32 s4, v253, 16
	v_lshlrev_b64 v[76:77], 11, v[112:113]
	v_readlane_b32 s6, v253, 18
	v_readlane_b32 s7, v253, 19
	s_ashr_i32 s23, s22, 31
	v_mov_b32_e32 v79, s23
	v_lshl_add_u64 v[76:77], s[6:7], 0, v[76:77]
	v_or_b32_e32 v78, s22, v192
	v_lshl_add_u64 v[76:77], v[78:79], 1, v[76:77]
	v_cvt_pk_bf16_f32 v72, v12, v13
	v_cvt_pk_bf16_f32 v73, v14, v15
	v_cvt_pk_bf16_f32 v74, v4, v5
	v_cvt_pk_bf16_f32 v75, v6, v7
	v_readlane_b32 s5, v253, 17
	v_readlane_b32 s8, v253, 20
	v_readlane_b32 s9, v253, 21
	v_readlane_b32 s10, v253, 22
	v_readlane_b32 s11, v253, 23
	v_readlane_b32 s12, v253, 24
	v_readlane_b32 s13, v253, 25
	v_readlane_b32 s14, v253, 26
	v_readlane_b32 s15, v253, 27
	v_readlane_b32 s16, v253, 28
	v_readlane_b32 s17, v253, 29
	v_readlane_b32 s18, v253, 30
	v_readlane_b32 s19, v253, 31
	global_store_dwordx4 v[76:77], v[72:75], off offset:256 sc1
.LBB0_144:
	s_waitcnt vmcnt(1)
	s_nop 1
	v_lshlrev_b32_e32 v72, 16, v64
	v_and_b32_e32 v73, 0xffff0000, v64
	v_rcp_f32_e32 v72, v72
	v_rcp_f32_e32 v73, v73
	v_lshlrev_b32_e32 v74, 16, v65
	v_and_b32_e32 v75, 0xffff0000, v65
	s_waitcnt vmcnt(0)
	v_lshlrev_b32_e32 v64, 16, v68
	v_and_b32_e32 v65, 0xffff0000, v68
	v_pk_mul_f32 v[64:65], v[72:73], v[64:65]
	v_lshlrev_b32_e32 v76, 16, v66
	v_cndmask_b32_e64 v65, v65, v73, s[36:37]
	v_cndmask_b32_e64 v64, v64, v72, s[36:37]
	v_pk_mul_f32 v[8:9], v[8:9], v[64:65]
	v_rcp_f32_e32 v64, v74
	v_rcp_f32_e32 v65, v75
	v_and_b32_e32 v77, 0xffff0000, v66
	v_lshlrev_b32_e32 v78, 16, v67
	v_and_b32_e32 v79, 0xffff0000, v67
	v_lshlrev_b32_e32 v66, 16, v69
	v_and_b32_e32 v67, 0xffff0000, v69
	v_pk_mul_f32 v[66:67], v[64:65], v[66:67]
	v_lshlrev_b32_e32 v68, 16, v70
	v_cndmask_b32_e64 v65, v67, v65, s[36:37]
	v_cndmask_b32_e64 v64, v66, v64, s[36:37]
	v_pk_mul_f32 v[10:11], v[10:11], v[64:65]
	v_rcp_f32_e32 v64, v76
	v_rcp_f32_e32 v65, v77
	v_and_b32_e32 v69, 0xffff0000, v70
	v_lshlrev_b32_e32 v70, 16, v71
	v_and_b32_e32 v71, 0xffff0000, v71
	v_pk_mul_f32 v[66:67], v[64:65], v[68:69]
	s_and_b64 vcc, exec, s[38:39]
	v_cndmask_b32_e64 v65, v67, v65, s[36:37]
	v_cndmask_b32_e64 v64, v66, v64, s[36:37]
	v_pk_mul_f32 v[0:1], v[0:1], v[64:65]
	v_rcp_f32_e32 v64, v78
	v_rcp_f32_e32 v65, v79
	s_nop 0
	v_pk_mul_f32 v[66:67], v[64:65], v[70:71]
	s_nop 0
	v_cndmask_b32_e64 v65, v67, v65, s[36:37]
	v_cndmask_b32_e64 v64, v66, v64, s[36:37]
	v_pk_mul_f32 v[2:3], v[2:3], v[64:65]
	s_cbranch_vccnz .LBB0_107
	s_lshl_b32 s22, s55, 8
	v_ashrrev_i32_e32 v97, 31, v96
	v_readlane_b32 s4, v253, 16
	v_lshlrev_b64 v[68:69], 11, v[96:97]
	v_readlane_b32 s6, v253, 18
	v_readlane_b32 s7, v253, 19
	s_ashr_i32 s23, s22, 31
	v_mov_b32_e32 v71, s23
	v_lshl_add_u64 v[68:69], s[6:7], 0, v[68:69]
	v_or_b32_e32 v70, s22, v192
	v_lshl_add_u64 v[68:69], v[70:71], 1, v[68:69]
	v_cvt_pk_bf16_f32 v64, v8, v9
	v_cvt_pk_bf16_f32 v65, v10, v11
	v_cvt_pk_bf16_f32 v66, v0, v1
	v_cvt_pk_bf16_f32 v67, v2, v3
	v_readlane_b32 s5, v253, 17
	v_readlane_b32 s8, v253, 20
	v_readlane_b32 s9, v253, 21
	v_readlane_b32 s10, v253, 22
	v_readlane_b32 s11, v253, 23
	v_readlane_b32 s12, v253, 24
	v_readlane_b32 s13, v253, 25
	v_readlane_b32 s14, v253, 26
	v_readlane_b32 s15, v253, 27
	v_readlane_b32 s16, v253, 28
	v_readlane_b32 s17, v253, 29
	v_readlane_b32 s18, v253, 30
	v_readlane_b32 s19, v253, 31
	global_store_dwordx4 v[68:69], v[64:67], off offset:256 sc1
	s_branch .LBB0_107

.LBB0_234:
	v_or_b32_e32 v141, 0x10000, v143
	v_add_u32_e32 v148, 0x10400, v143
	ds_read_b128 v[144:147], v141
	ds_read_b128 v[148:151], v148
	v_add_u32_e32 v141, 0x10800, v143
	v_add_u32_e32 v156, 0x10c00, v143
	ds_read_b128 v[152:155], v141
	ds_read_b128 v[156:159], v156
	s_add_u32 s34, s30, 0xfff00080
	s_addc_u32 s35, s31, -1
	s_cmp_eq_u32 s96, 12
	s_cselect_b32 s37, vcc_lo, s35
	s_cselect_b32 s36, vcc_hi, s34
	s_cselect_b32 s35, s33, s27
	s_cselect_b32 s34, s20, s26
	v_lshl_add_u64 v[190:191], s[30:31], 0, v[136:137]
	s_add_i32 m0, s38, 0xc000
	ds_read_b128 v[160:163], v142
	ds_read_b128 v[164:167], v142 offset:1024
	ds_read_b128 v[168:171], v142 offset:2048
	ds_read_b128 v[172:175], v142 offset:3072
	ds_read_b128 v[176:179], v142 offset:4096
	ds_read_b128 v[180:183], v142 offset:5120
	ds_read_b128 v[186:189], v142 offset:6144
	ds_read_b128 v[194:197], v142 offset:7168
	global_load_lds_dwordx4 v[190:191], off
	v_lshl_add_u64 v[190:191], s[30:31], 0, v[138:139]
	s_add_i32 m0, s38, 0xe000
	s_nop 0
	global_load_lds_dwordx4 v[190:191], off
	s_waitcnt lgkmcnt(8)
	s_barrier
	s_waitcnt lgkmcnt(0)
	s_setprio 1
	s_waitcnt lgkmcnt(0)
	v_mfma_f32_16x16x32_bf16 v[124:127], v[144:147], v[160:163], v[124:127]
	v_mfma_f32_16x16x32_bf16 v[120:123], v[152:155], v[160:163], v[120:123]
	v_mfma_f32_16x16x32_bf16 v[116:119], v[144:147], v[168:171], v[116:119]
	v_mfma_f32_16x16x32_bf16 v[112:115], v[152:155], v[168:171], v[112:115]
	v_mfma_f32_16x16x32_bf16 v[108:111], v[144:147], v[176:179], v[108:111]
	v_mfma_f32_16x16x32_bf16 v[104:107], v[152:155], v[176:179], v[104:107]
	v_mfma_f32_16x16x32_bf16 v[100:103], v[144:147], v[186:189], v[100:103]
	v_mfma_f32_16x16x32_bf16 v[96:99], v[152:155], v[186:189], v[96:99]
	v_mfma_f32_16x16x32_bf16 v[124:127], v[148:151], v[164:167], v[124:127]
	v_mfma_f32_16x16x32_bf16 v[120:123], v[156:159], v[164:167], v[120:123]
	v_mfma_f32_16x16x32_bf16 v[116:119], v[148:151], v[172:175], v[116:119]
	v_mfma_f32_16x16x32_bf16 v[112:115], v[156:159], v[172:175], v[112:115]
	v_mfma_f32_16x16x32_bf16 v[108:111], v[148:151], v[180:183], v[108:111]
	v_mfma_f32_16x16x32_bf16 v[104:107], v[156:159], v[180:183], v[104:107]
	v_mfma_f32_16x16x32_bf16 v[100:103], v[148:151], v[194:197], v[100:103]
	v_mfma_f32_16x16x32_bf16 v[96:99], v[156:159], v[194:197], v[96:99]
	s_setprio 0
	s_barrier
	v_or_b32_e32 v141, 0x14000, v143
	v_add_u32_e32 v190, 0x14400, v143
	ds_read_b128 v[198:201], v141
	ds_read_b128 v[202:205], v190
	v_add_u32_e32 v141, 0x14800, v143
	v_add_u32_e32 v190, 0x14c00, v143
	s_mov_b32 m0, s39
	ds_read_b128 v[206:209], v141
	ds_read_b128 v[210:213], v190
	v_lshl_add_u64 v[190:191], s[34:35], 0, v[132:133]
	global_load_lds_dwordx4 v[190:191], off
	v_lshl_add_u64 v[214:215], s[34:35], 0, v[128:129]
	s_mov_b32 m0, s40
	s_nop 0
	global_load_lds_dwordx4 v[214:215], off
	s_barrier
	s_waitcnt lgkmcnt(0)
	s_setprio 1
	s_waitcnt lgkmcnt(0)
	v_mfma_f32_16x16x32_bf16 v[92:95], v[198:201], v[160:163], v[92:95]
	v_mfma_f32_16x16x32_bf16 v[88:91], v[206:209], v[160:163], v[88:91]
	v_mfma_f32_16x16x32_bf16 v[84:87], v[198:201], v[168:171], v[84:87]
	v_mfma_f32_16x16x32_bf16 v[80:83], v[206:209], v[168:171], v[80:83]
	v_mfma_f32_16x16x32_bf16 v[76:79], v[198:201], v[176:179], v[76:79]
	v_mfma_f32_16x16x32_bf16 v[72:75], v[206:209], v[176:179], v[72:75]
	v_mfma_f32_16x16x32_bf16 v[68:71], v[198:201], v[186:189], v[68:71]
	v_mfma_f32_16x16x32_bf16 v[64:67], v[206:209], v[186:189], v[64:67]
	v_mfma_f32_16x16x32_bf16 v[92:95], v[202:205], v[164:167], v[92:95]
	v_mfma_f32_16x16x32_bf16 v[88:91], v[210:213], v[164:167], v[88:91]
	v_mfma_f32_16x16x32_bf16 v[84:87], v[202:205], v[172:175], v[84:87]
	v_mfma_f32_16x16x32_bf16 v[80:83], v[210:213], v[172:175], v[80:83]
	v_mfma_f32_16x16x32_bf16 v[76:79], v[202:205], v[180:183], v[76:79]
	v_mfma_f32_16x16x32_bf16 v[72:75], v[210:213], v[180:183], v[72:75]
	v_mfma_f32_16x16x32_bf16 v[68:71], v[202:205], v[194:197], v[68:71]
	v_mfma_f32_16x16x32_bf16 v[64:67], v[210:213], v[194:197], v[64:67]
	s_setprio 0
	s_mov_b32 m0, s38
	v_lshl_add_u64 v[216:217], s[36:37], 0, v[134:135]
	s_barrier
	ds_read_b128 v[160:163], v142 offset:16384
	ds_read_b128 v[164:167], v142 offset:17408
	ds_read_b128 v[168:171], v142 offset:18432
	ds_read_b128 v[172:175], v142 offset:19456
	ds_read_b128 v[176:179], v142 offset:20480
	ds_read_b128 v[180:183], v142 offset:21504
	ds_read_b128 v[186:189], v142 offset:22528
	ds_read_b128 v[194:197], v142 offset:23552
	global_load_lds_dwordx4 v[216:217], off
	v_lshl_add_u64 v[242:243], s[36:37], 0, v[130:131]
	s_mov_b32 m0, s41
	s_nop 0
	global_load_lds_dwordx4 v[242:243], off
	s_barrier
	s_waitcnt lgkmcnt(0)
	s_setprio 1
	s_waitcnt lgkmcnt(0)
	v_mfma_f32_16x16x32_bf16 v[60:63], v[144:147], v[160:163], v[60:63]
	v_mfma_f32_16x16x32_bf16 v[56:59], v[152:155], v[160:163], v[56:59]
	v_mfma_f32_16x16x32_bf16 v[52:55], v[144:147], v[168:171], v[52:55]
	v_mfma_f32_16x16x32_bf16 v[48:51], v[152:155], v[168:171], v[48:51]
	v_mfma_f32_16x16x32_bf16 v[44:47], v[144:147], v[176:179], v[44:47]
	v_mfma_f32_16x16x32_bf16 v[40:43], v[152:155], v[176:179], v[40:43]
	v_mfma_f32_16x16x32_bf16 v[36:39], v[144:147], v[186:189], v[36:39]
	v_mfma_f32_16x16x32_bf16 v[32:35], v[152:155], v[186:189], v[32:35]
	v_mfma_f32_16x16x32_bf16 v[60:63], v[148:151], v[164:167], v[60:63]
	v_mfma_f32_16x16x32_bf16 v[56:59], v[156:159], v[164:167], v[56:59]
	v_mfma_f32_16x16x32_bf16 v[52:55], v[148:151], v[172:175], v[52:55]
	v_mfma_f32_16x16x32_bf16 v[48:51], v[156:159], v[172:175], v[48:51]
	v_mfma_f32_16x16x32_bf16 v[44:47], v[148:151], v[180:183], v[44:47]
	v_mfma_f32_16x16x32_bf16 v[40:43], v[156:159], v[180:183], v[40:43]
	v_mfma_f32_16x16x32_bf16 v[36:39], v[148:151], v[194:197], v[36:39]
	v_mfma_f32_16x16x32_bf16 v[32:35], v[156:159], v[194:197], v[32:35]
	s_setprio 0
	s_barrier
	s_add_u32 s66, s34, 0x800000
	s_addc_u32 s67, s35, 0
	s_mov_b32 m0, s42
	v_lshl_add_u64 v[144:145], s[66:67], 0, v[132:133]
	global_load_lds_dwordx4 v[144:145], off
	v_lshl_add_u64 v[144:145], s[66:67], 0, v[128:129]
	s_mov_b32 m0, s43
	s_nop 0
	global_load_lds_dwordx4 v[144:145], off
	s_waitcnt vmcnt(6)
	s_barrier
	s_setprio 1
	v_mfma_f32_16x16x32_bf16 v[28:31], v[198:201], v[160:163], v[28:31]
	v_mfma_f32_16x16x32_bf16 v[24:27], v[206:209], v[160:163], v[24:27]
	v_mfma_f32_16x16x32_bf16 v[20:23], v[198:201], v[168:171], v[20:23]
	v_mfma_f32_16x16x32_bf16 v[16:19], v[206:209], v[168:171], v[16:19]
	v_mfma_f32_16x16x32_bf16 v[12:15], v[198:201], v[176:179], v[12:15]
	v_mfma_f32_16x16x32_bf16 v[8:11], v[206:209], v[176:179], v[8:11]
	v_mfma_f32_16x16x32_bf16 v[4:7], v[198:201], v[186:189], v[4:7]
	v_mfma_f32_16x16x32_bf16 v[0:3], v[206:209], v[186:189], v[0:3]
	v_mfma_f32_16x16x32_bf16 v[28:31], v[202:205], v[164:167], v[28:31]
	v_mfma_f32_16x16x32_bf16 v[24:27], v[210:213], v[164:167], v[24:27]
	v_mfma_f32_16x16x32_bf16 v[20:23], v[202:205], v[172:175], v[20:23]
	v_mfma_f32_16x16x32_bf16 v[16:19], v[210:213], v[172:175], v[16:19]
	v_mfma_f32_16x16x32_bf16 v[12:15], v[202:205], v[180:183], v[12:15]
	v_mfma_f32_16x16x32_bf16 v[8:11], v[210:213], v[180:183], v[8:11]
	v_mfma_f32_16x16x32_bf16 v[4:7], v[202:205], v[194:197], v[4:7]
	v_mfma_f32_16x16x32_bf16 v[0:3], v[210:213], v[194:197], v[0:3]
	s_setprio 0
	v_or_b32_e32 v141, 0x18000, v143
	v_add_u32_e32 v148, 0x18400, v143
	s_barrier
	ds_read_b128 v[144:147], v141
	ds_read_b128 v[148:151], v148
	v_add_u32_e32 v141, 0x18800, v143
	v_add_u32_e32 v156, 0x18c00, v143
	ds_read_b128 v[152:155], v141
	ds_read_b128 v[156:159], v156
	s_add_u32 s36, s36, 0x100000
	s_addc_u32 s37, s37, 0
	s_mov_b32 m0, s44
	v_lshl_add_u64 v[198:199], s[36:37], 0, v[134:135]
	ds_read_b128 v[160:163], v142 offset:32768
	ds_read_b128 v[164:167], v142 offset:33792
	ds_read_b128 v[168:171], v142 offset:34816
	ds_read_b128 v[172:175], v142 offset:35840
	ds_read_b128 v[176:179], v142 offset:36864
	ds_read_b128 v[180:183], v142 offset:37888
	ds_read_b128 v[186:189], v142 offset:38912
	ds_read_b128 v[194:197], v142 offset:39936
	global_load_lds_dwordx4 v[198:199], off
	v_lshl_add_u64 v[198:199], s[36:37], 0, v[130:131]
	s_mov_b32 m0, s45
	s_nop 0
	global_load_lds_dwordx4 v[198:199], off
	s_waitcnt lgkmcnt(8)
	s_barrier
	s_waitcnt lgkmcnt(0)
	s_setprio 1
	s_waitcnt lgkmcnt(0)
	v_mfma_f32_16x16x32_bf16 v[124:127], v[144:147], v[160:163], v[124:127]
	v_mfma_f32_16x16x32_bf16 v[120:123], v[152:155], v[160:163], v[120:123]
	v_mfma_f32_16x16x32_bf16 v[116:119], v[144:147], v[168:171], v[116:119]
	v_mfma_f32_16x16x32_bf16 v[112:115], v[152:155], v[168:171], v[112:115]
	v_mfma_f32_16x16x32_bf16 v[108:111], v[144:147], v[176:179], v[108:111]
	v_mfma_f32_16x16x32_bf16 v[104:107], v[152:155], v[176:179], v[104:107]
	v_mfma_f32_16x16x32_bf16 v[100:103], v[144:147], v[186:189], v[100:103]
	v_mfma_f32_16x16x32_bf16 v[96:99], v[152:155], v[186:189], v[96:99]
	v_mfma_f32_16x16x32_bf16 v[124:127], v[148:151], v[164:167], v[124:127]
	v_mfma_f32_16x16x32_bf16 v[120:123], v[156:159], v[164:167], v[120:123]
	v_mfma_f32_16x16x32_bf16 v[116:119], v[148:151], v[172:175], v[116:119]
	v_mfma_f32_16x16x32_bf16 v[112:115], v[156:159], v[172:175], v[112:115]
	v_mfma_f32_16x16x32_bf16 v[108:111], v[148:151], v[180:183], v[108:111]
	v_mfma_f32_16x16x32_bf16 v[104:107], v[156:159], v[180:183], v[104:107]
	v_mfma_f32_16x16x32_bf16 v[100:103], v[148:151], v[194:197], v[100:103]
	v_mfma_f32_16x16x32_bf16 v[96:99], v[156:159], v[194:197], v[96:99]
	s_setprio 0
	s_barrier
	v_or_b32_e32 v141, 0x1c000, v143
	s_mov_b32 m0, s46
	v_add_u32_e32 v192, 0x1c400, v143
	ds_read_b128 v[198:201], v141
	ds_read_b128 v[202:205], v192
	v_add_u32_e32 v141, 0x1c800, v143
	v_lshl_add_u64 v[190:191], v[190:191], 0, s[24:25]
	v_add_u32_e32 v192, 0x1cc00, v143
	ds_read_b128 v[206:209], v141
	ds_read_b128 v[210:213], v192
	global_load_lds_dwordx4 v[190:191], off
	v_lshl_add_u64 v[190:191], v[214:215], 0, s[24:25]
	s_mov_b32 m0, s47
	s_nop 0
	global_load_lds_dwordx4 v[190:191], off
	s_barrier
	s_waitcnt lgkmcnt(0)
	s_setprio 1
	s_waitcnt lgkmcnt(0)
	v_mfma_f32_16x16x32_bf16 v[92:95], v[198:201], v[160:163], v[92:95]
	v_mfma_f32_16x16x32_bf16 v[88:91], v[206:209], v[160:163], v[88:91]
	v_mfma_f32_16x16x32_bf16 v[84:87], v[198:201], v[168:171], v[84:87]
	v_mfma_f32_16x16x32_bf16 v[80:83], v[206:209], v[168:171], v[80:83]
	v_mfma_f32_16x16x32_bf16 v[76:79], v[198:201], v[176:179], v[76:79]
	v_mfma_f32_16x16x32_bf16 v[72:75], v[206:209], v[176:179], v[72:75]
	v_mfma_f32_16x16x32_bf16 v[68:71], v[198:201], v[186:189], v[68:71]
	v_mfma_f32_16x16x32_bf16 v[64:67], v[206:209], v[186:189], v[64:67]
	v_mfma_f32_16x16x32_bf16 v[92:95], v[202:205], v[164:167], v[92:95]
	v_mfma_f32_16x16x32_bf16 v[88:91], v[210:213], v[164:167], v[88:91]
	v_mfma_f32_16x16x32_bf16 v[84:87], v[202:205], v[172:175], v[84:87]
	v_mfma_f32_16x16x32_bf16 v[80:83], v[210:213], v[172:175], v[80:83]
	v_mfma_f32_16x16x32_bf16 v[76:79], v[202:205], v[180:183], v[76:79]
	v_mfma_f32_16x16x32_bf16 v[72:75], v[210:213], v[180:183], v[72:75]
	v_mfma_f32_16x16x32_bf16 v[68:71], v[202:205], v[194:197], v[68:71]
	v_mfma_f32_16x16x32_bf16 v[64:67], v[210:213], v[194:197], v[64:67]
	s_setprio 0
	s_mov_b32 m0, s48
	v_lshl_add_u64 v[190:191], v[216:217], 0, s[24:25]
	s_barrier
	ds_read_b128 v[160:163], v142 offset:49152
	ds_read_b128 v[164:167], v142 offset:50176
	ds_read_b128 v[168:171], v142 offset:51200
	ds_read_b128 v[172:175], v142 offset:52224
	ds_read_b128 v[176:179], v142 offset:53248
	ds_read_b128 v[180:183], v142 offset:54272
	ds_read_b128 v[186:189], v142 offset:55296
	ds_read_b128 v[194:197], v142 offset:56320
	global_load_lds_dwordx4 v[190:191], off
	v_lshl_add_u64 v[190:191], v[242:243], 0, s[24:25]
	s_mov_b32 m0, s49
	s_nop 0
	global_load_lds_dwordx4 v[190:191], off
	s_barrier
	s_waitcnt lgkmcnt(0)
	s_setprio 1
	s_waitcnt lgkmcnt(0)
	v_mfma_f32_16x16x32_bf16 v[60:63], v[144:147], v[160:163], v[60:63]
	v_mfma_f32_16x16x32_bf16 v[56:59], v[152:155], v[160:163], v[56:59]
	v_mfma_f32_16x16x32_bf16 v[52:55], v[144:147], v[168:171], v[52:55]
	v_mfma_f32_16x16x32_bf16 v[48:51], v[152:155], v[168:171], v[48:51]
	v_mfma_f32_16x16x32_bf16 v[44:47], v[144:147], v[176:179], v[44:47]
	v_mfma_f32_16x16x32_bf16 v[40:43], v[152:155], v[176:179], v[40:43]
	v_mfma_f32_16x16x32_bf16 v[36:39], v[144:147], v[186:189], v[36:39]
	v_mfma_f32_16x16x32_bf16 v[32:35], v[152:155], v[186:189], v[32:35]
	v_mfma_f32_16x16x32_bf16 v[60:63], v[148:151], v[164:167], v[60:63]
	v_mfma_f32_16x16x32_bf16 v[56:59], v[156:159], v[164:167], v[56:59]
	v_mfma_f32_16x16x32_bf16 v[52:55], v[148:151], v[172:175], v[52:55]
	v_mfma_f32_16x16x32_bf16 v[48:51], v[156:159], v[172:175], v[48:51]
	v_mfma_f32_16x16x32_bf16 v[44:47], v[148:151], v[180:183], v[44:47]
	v_mfma_f32_16x16x32_bf16 v[40:43], v[156:159], v[180:183], v[40:43]
	v_mfma_f32_16x16x32_bf16 v[36:39], v[148:151], v[194:197], v[36:39]
	v_mfma_f32_16x16x32_bf16 v[32:35], v[156:159], v[194:197], v[32:35]
	s_setprio 0
	s_barrier
	s_add_u32 s34, s34, 0x800080
	s_addc_u32 s35, s35, 0
	s_mov_b32 m0, s50
	v_lshl_add_u64 v[144:145], s[34:35], 0, v[132:133]
	global_load_lds_dwordx4 v[144:145], off
	v_lshl_add_u64 v[144:145], s[34:35], 0, v[128:129]
	s_mov_b32 m0, s51
	s_nop 0
	global_load_lds_dwordx4 v[144:145], off
	s_waitcnt vmcnt(6)
	s_barrier
	s_setprio 1
	v_mfma_f32_16x16x32_bf16 v[28:31], v[198:201], v[160:163], v[28:31]
	v_mfma_f32_16x16x32_bf16 v[24:27], v[206:209], v[160:163], v[24:27]
	v_mfma_f32_16x16x32_bf16 v[20:23], v[198:201], v[168:171], v[20:23]
	v_mfma_f32_16x16x32_bf16 v[16:19], v[206:209], v[168:171], v[16:19]
	v_mfma_f32_16x16x32_bf16 v[12:15], v[198:201], v[176:179], v[12:15]
	v_mfma_f32_16x16x32_bf16 v[8:11], v[206:209], v[176:179], v[8:11]
	v_mfma_f32_16x16x32_bf16 v[4:7], v[198:201], v[186:189], v[4:7]
	v_mfma_f32_16x16x32_bf16 v[0:3], v[206:209], v[186:189], v[0:3]
	v_mfma_f32_16x16x32_bf16 v[28:31], v[202:205], v[164:167], v[28:31]
	v_mfma_f32_16x16x32_bf16 v[24:27], v[210:213], v[164:167], v[24:27]
	v_mfma_f32_16x16x32_bf16 v[20:23], v[202:205], v[172:175], v[20:23]
	v_mfma_f32_16x16x32_bf16 v[16:19], v[210:213], v[172:175], v[16:19]
	v_mfma_f32_16x16x32_bf16 v[12:15], v[202:205], v[180:183], v[12:15]
	v_mfma_f32_16x16x32_bf16 v[8:11], v[210:213], v[180:183], v[8:11]
	v_mfma_f32_16x16x32_bf16 v[4:7], v[202:205], v[194:197], v[4:7]
	v_mfma_f32_16x16x32_bf16 v[0:3], v[210:213], v[194:197], v[0:3]
	s_setprio 0
	s_add_i32 s96, s96, 2
	s_add_u32 s30, s30, 0x100
	s_addc_u32 s31, s31, 0
	s_add_u32 s26, s26, 0x100
	s_addc_u32 s27, s27, 0
	s_cmp_gt_u32 s96, 13
	s_barrier
	s_cbranch_scc0 .LBB0_234
	s_lshl_b32 s20, s71, 7
	s_lshl_b32 s26, s56, 4
	s_or_b32 s27, s26, s20
	s_add_i32 s34, s27, s52
	s_lshl_b32 s88, s70, 19
	v_readlane_b32 s72, v253, 16
	s_ashr_i32 s35, s34, 31
	s_lshl_b64 s[30:31], s[88:89], 4
	v_readlane_b32 s74, v253, 18
	v_readlane_b32 s75, v253, 19
	s_add_u32 s27, s74, s30
	s_addc_u32 s30, s75, s31
	s_lshl_b64 s[34:35], s[34:35], 13
	s_add_u32 s31, s27, s34
	s_addc_u32 s33, s30, s35
	s_add_u32 s34, s31, s63
	s_addc_u32 s35, s33, 0
	v_cvt_pk_bf16_f32 v124, v124, v125
	v_cvt_pk_bf16_f32 v125, v126, v127
	v_cvt_pk_bf16_f32 v126, v120, v121
	v_lshl_add_u64 v[120:121], s[34:35], 0, v[184:185]
	s_add_i32 s34, s54, s20
	s_add_i32 s34, s34, s26
	s_ashr_i32 s35, s34, 31
	s_lshl_b64 s[34:35], s[34:35], 13
	s_add_u32 s36, s27, s34
	s_addc_u32 s37, s30, s35
	s_add_u32 s34, s36, s63
	s_addc_u32 s35, s37, 0
	v_cvt_pk_bf16_f32 v116, v116, v117
	v_cvt_pk_bf16_f32 v117, v118, v119
	v_cvt_pk_bf16_f32 v118, v112, v113
	v_lshl_add_u64 v[112:113], s[34:35], 0, v[184:185]
	s_add_i32 s34, s55, s20
	s_add_i32 s34, s34, s26
	s_ashr_i32 s35, s34, 31
	s_lshl_b64 s[34:35], s[34:35], 13
	s_add_u32 s66, s27, s34
	s_addc_u32 s67, s30, s35
	s_add_u32 s34, s66, s63
	s_addc_u32 s35, s67, 0
	v_cvt_pk_bf16_f32 v108, v108, v109
	v_cvt_pk_bf16_f32 v109, v110, v111
	v_cvt_pk_bf16_f32 v110, v104, v105
	v_lshl_add_u64 v[104:105], s[34:35], 0, v[184:185]
	s_add_i32 s34, s58, s20
	s_add_i32 s34, s34, s26
	s_ashr_i32 s35, s34, 31
	s_lshl_b64 s[34:35], s[34:35], 13
	s_add_u32 s70, s27, s34
	s_addc_u32 s71, s30, s35
	s_add_u32 s34, s70, s63
	s_addc_u32 s35, s71, 0
	v_cvt_pk_bf16_f32 v100, v100, v101
	v_cvt_pk_bf16_f32 v101, v102, v103
	v_cvt_pk_bf16_f32 v102, v96, v97
	v_lshl_add_u64 v[96:97], s[34:35], 0, v[184:185]
	s_add_u32 s34, s31, s64
	s_addc_u32 s35, s33, 0
	v_cvt_pk_bf16_f32 v92, v92, v93
	v_cvt_pk_bf16_f32 v93, v94, v95
	v_cvt_pk_bf16_f32 v94, v88, v89
	v_lshl_add_u64 v[88:89], s[34:35], 0, v[184:185]
	s_add_u32 s34, s36, s64
	s_addc_u32 s35, s37, 0
	v_cvt_pk_bf16_f32 v84, v84, v85
	v_cvt_pk_bf16_f32 v85, v86, v87
	v_cvt_pk_bf16_f32 v86, v80, v81
	v_lshl_add_u64 v[80:81], s[34:35], 0, v[184:185]
	s_add_u32 s34, s66, s64
	s_addc_u32 s35, s67, 0
	v_cvt_pk_bf16_f32 v76, v76, v77
	v_cvt_pk_bf16_f32 v77, v78, v79
	v_cvt_pk_bf16_f32 v78, v72, v73
	v_lshl_add_u64 v[72:73], s[34:35], 0, v[184:185]
	s_add_u32 s34, s70, s64
	s_addc_u32 s35, s71, 0
	s_add_i32 s31, s53, s20
	v_cvt_pk_bf16_f32 v68, v68, v69
	v_cvt_pk_bf16_f32 v69, v70, v71
	v_cvt_pk_bf16_f32 v70, v64, v65
	v_lshl_add_u64 v[64:65], s[34:35], 0, v[184:185]
	s_add_i32 s34, s31, s26
	s_ashr_i32 s35, s34, 31
	s_lshl_b64 s[34:35], s[34:35], 13
	s_add_u32 s31, s27, s34
	s_addc_u32 s33, s30, s35
	s_add_u32 s34, s31, s63
	s_addc_u32 s35, s33, 0
	v_cvt_pk_bf16_f32 v60, v60, v61
	v_cvt_pk_bf16_f32 v61, v62, v63
	v_cvt_pk_bf16_f32 v62, v56, v57
	v_lshl_add_u64 v[56:57], s[34:35], 0, v[184:185]
	s_add_i32 s34, s59, s20
	s_add_i32 s34, s34, s26
	s_ashr_i32 s35, s34, 31
	s_lshl_b64 s[34:35], s[34:35], 13
	s_add_u32 s36, s27, s34
	s_addc_u32 s37, s30, s35
	s_add_u32 s34, s36, s63
	s_addc_u32 s35, s37, 0
	v_cvt_pk_bf16_f32 v52, v52, v53
	v_cvt_pk_bf16_f32 v53, v54, v55
	v_cvt_pk_bf16_f32 v54, v48, v49
	v_lshl_add_u64 v[48:49], s[34:35], 0, v[184:185]
	s_add_i32 s34, s60, s20
	s_add_i32 s34, s34, s26
	s_ashr_i32 s35, s34, 31
	s_lshl_b64 s[34:35], s[34:35], 13
	s_add_u32 s66, s27, s34
	s_addc_u32 s67, s30, s35
	s_add_u32 s34, s66, s63
	s_addc_u32 s35, s67, 0
	s_add_i32 s20, s61, s20
	v_cvt_pk_bf16_f32 v44, v44, v45
	v_cvt_pk_bf16_f32 v45, v46, v47
	v_cvt_pk_bf16_f32 v46, v40, v41
	v_lshl_add_u64 v[40:41], s[34:35], 0, v[184:185]
	s_add_i32 s34, s20, s26
	s_ashr_i32 s35, s34, 31
	s_lshl_b64 s[34:35], s[34:35], 13
	s_add_u32 s20, s27, s34
	s_addc_u32 s30, s30, s35
	s_add_u32 s26, s20, s63
	s_addc_u32 s27, s30, 0
	v_cvt_pk_bf16_f32 v36, v36, v37
	v_cvt_pk_bf16_f32 v37, v38, v39
	v_cvt_pk_bf16_f32 v38, v32, v33
	v_lshl_add_u64 v[32:33], s[26:27], 0, v[184:185]
	s_add_u32 s26, s31, s64
	s_addc_u32 s27, s33, 0
	v_cvt_pk_bf16_f32 v28, v28, v29
	v_cvt_pk_bf16_f32 v29, v30, v31
	v_cvt_pk_bf16_f32 v30, v24, v25
	v_lshl_add_u64 v[24:25], s[26:27], 0, v[184:185]
	s_add_u32 s26, s36, s64
	s_addc_u32 s27, s37, 0
	v_cvt_pk_bf16_f32 v20, v20, v21
	v_cvt_pk_bf16_f32 v21, v22, v23
	v_cvt_pk_bf16_f32 v22, v16, v17
	v_lshl_add_u64 v[16:17], s[26:27], 0, v[184:185]
	s_add_u32 s26, s66, s64
	s_addc_u32 s27, s67, 0
	v_cvt_pk_bf16_f32 v12, v12, v13
	v_cvt_pk_bf16_f32 v13, v14, v15
	v_cvt_pk_bf16_f32 v14, v8, v9
	v_lshl_add_u64 v[8:9], s[26:27], 0, v[184:185]
	s_add_u32 s26, s20, s64
	s_addc_u32 s27, s30, 0
	v_mov_b32_e32 v141, v185
	v_cvt_pk_bf16_f32 v4, v4, v5
	v_cvt_pk_bf16_f32 v5, v6, v7
	v_cvt_pk_bf16_f32 v6, v0, v1
	v_lshl_add_u64 v[0:1], s[26:27], 0, v[184:185]
	v_readlane_b32 s78, v253, 22
	v_readlane_b32 s79, v253, 23
	v_lshl_add_u64 v[120:121], v[120:121], 0, v[140:141]
	v_lshl_add_u64 v[112:113], v[112:113], 0, v[140:141]
	v_lshl_add_u64 v[104:105], v[104:105], 0, v[140:141]
	v_lshl_add_u64 v[96:97], v[96:97], 0, v[140:141]
	v_lshl_add_u64 v[88:89], v[88:89], 0, v[140:141]
	v_lshl_add_u64 v[80:81], v[80:81], 0, v[140:141]
	v_lshl_add_u64 v[72:73], v[72:73], 0, v[140:141]
	v_lshl_add_u64 v[64:65], v[64:65], 0, v[140:141]
	v_lshl_add_u64 v[56:57], v[56:57], 0, v[140:141]
	v_lshl_add_u64 v[48:49], v[48:49], 0, v[140:141]
	v_lshl_add_u64 v[40:41], v[40:41], 0, v[140:141]
	v_lshl_add_u64 v[32:33], v[32:33], 0, v[140:141]
	v_lshl_add_u64 v[24:25], v[24:25], 0, v[140:141]
	v_lshl_add_u64 v[16:17], v[16:17], 0, v[140:141]
	v_lshl_add_u64 v[8:9], v[8:9], 0, v[140:141]
	v_lshl_add_u64 v[0:1], v[0:1], 0, v[140:141]
	s_and_b64 vcc, exec, s[0:1]
	s_mov_b32 s71, s65
	s_mov_b32 s70, s68
	s_mov_b32 s56, s69
	v_readlane_b32 s96, v255, 22
	v_cvt_pk_bf16_f32 v127, v122, v123
	v_readlane_b32 s73, v253, 17
	v_readlane_b32 s76, v253, 20
	v_readlane_b32 s77, v253, 21
	v_readlane_b32 s80, v253, 24
	v_readlane_b32 s81, v253, 25
	v_readlane_b32 s82, v253, 26
	v_readlane_b32 s83, v253, 27
	v_readlane_b32 s84, v253, 28
	v_readlane_b32 s85, v253, 29
	v_readlane_b32 s86, v253, 30
	v_readlane_b32 s87, v253, 31
	global_store_dwordx4 v[120:121], v[124:127], off sc1
	v_cvt_pk_bf16_f32 v119, v114, v115
	global_store_dwordx4 v[112:113], v[116:119], off sc1
	v_cvt_pk_bf16_f32 v111, v106, v107
	global_store_dwordx4 v[104:105], v[108:111], off sc1
	v_cvt_pk_bf16_f32 v103, v98, v99
	global_store_dwordx4 v[96:97], v[100:103], off sc1
	v_cvt_pk_bf16_f32 v95, v90, v91
	global_store_dwordx4 v[88:89], v[92:95], off sc1
	v_cvt_pk_bf16_f32 v87, v82, v83
	global_store_dwordx4 v[80:81], v[84:87], off sc1
	v_cvt_pk_bf16_f32 v79, v74, v75
	global_store_dwordx4 v[72:73], v[76:79], off sc1
	v_cvt_pk_bf16_f32 v71, v66, v67
	global_store_dwordx4 v[64:65], v[68:71], off sc1
	v_cvt_pk_bf16_f32 v63, v58, v59
	global_store_dwordx4 v[56:57], v[60:63], off sc1
	v_cvt_pk_bf16_f32 v55, v50, v51
	global_store_dwordx4 v[48:49], v[52:55], off sc1
	v_cvt_pk_bf16_f32 v47, v42, v43
	global_store_dwordx4 v[40:41], v[44:47], off sc1
	v_cvt_pk_bf16_f32 v39, v34, v35
	global_store_dwordx4 v[32:33], v[36:39], off sc1
	v_cvt_pk_bf16_f32 v31, v26, v27
	global_store_dwordx4 v[24:25], v[28:31], off sc1
	v_cvt_pk_bf16_f32 v23, v18, v19
	global_store_dwordx4 v[16:17], v[20:23], off sc1
	v_cvt_pk_bf16_f32 v15, v10, v11
	global_store_dwordx4 v[8:9], v[12:15], off sc1
	v_cvt_pk_bf16_f32 v7, v2, v3
	global_store_dwordx4 v[0:1], v[4:7], off sc1
	s_cbranch_vccz .LBB0_233
	v_readlane_b32 s84, v255, 43
	s_waitcnt vmcnt(0)
	v_readlane_b32 s86, v255, 45
	v_readlane_b32 s87, v255, 46
	v_readlane_b32 s72, v255, 23
	v_readlane_b32 s86, v255, 31
	s_cmpk_gt_u32 s93, 0xff
	v_readlane_b32 s85, v255, 44
	v_readlane_b32 s73, v255, 24
	v_readlane_b32 s74, v255, 25
	v_readlane_b32 s75, v255, 26
	v_readlane_b32 s76, v255, 27
	v_readlane_b32 s77, v255, 28
	v_readlane_b32 s78, v255, 29
	v_readlane_b32 s79, v255, 30
	s_mov_b32 s80, s57
	v_readlane_b32 s93, v255, 34
	v_readlane_b32 s81, v255, 33
	v_readlane_b32 s87, v255, 32
	s_mov_b32 s70, 0xbfb8aa3b
	s_mov_b32 s71, 0x42ce8ed0
	s_cbranch_scc1 .LBB0_238
	s_barrier

.LBB0_245:
	v_or_b32_e32 v144, 0x10000, v143
	v_add_u32_e32 v148, 0x10400, v143
	v_add_u32_e32 v152, 0x10800, v143
	v_add_u32_e32 v156, 0x10c00, v143
	ds_read_b128 v[144:147], v144
	ds_read_b128 v[148:151], v148
	ds_read_b128 v[152:155], v152
	ds_read_b128 v[156:159], v156
	s_add_u32 s34, s30, 0xfffe0080
	s_addc_u32 s35, s31, -1
	s_cmp_eq_u32 s61, 4
	s_cselect_b32 s37, s79, s35
	s_cselect_b32 s36, s78, s34
	s_cselect_b32 s35, s20, s27
	s_cselect_b32 s34, s60, s26
	v_lshl_add_u64 v[190:191], s[30:31], 0, v[138:139]
	s_add_i32 m0, s38, 0xc000
	ds_read_b128 v[160:163], v142
	ds_read_b128 v[164:167], v142 offset:1024
	ds_read_b128 v[168:171], v142 offset:2048
	ds_read_b128 v[172:175], v142 offset:3072
	ds_read_b128 v[176:179], v142 offset:4096
	ds_read_b128 v[180:183], v142 offset:5120
	ds_read_b128 v[186:189], v142 offset:6144
	ds_read_b128 v[194:197], v142 offset:7168
	global_load_lds_dwordx4 v[190:191], off
	v_lshl_add_u64 v[190:191], s[30:31], 0, v[140:141]
	s_add_i32 m0, s38, 0xe000
	s_nop 0
	global_load_lds_dwordx4 v[190:191], off
	s_waitcnt lgkmcnt(8)
	s_barrier
	s_waitcnt lgkmcnt(0)
	s_setprio 1
	s_waitcnt lgkmcnt(0)
	v_mfma_f32_16x16x32_bf16 v[124:127], v[144:147], v[160:163], v[124:127]
	v_mfma_f32_16x16x32_bf16 v[120:123], v[152:155], v[160:163], v[120:123]
	v_mfma_f32_16x16x32_bf16 v[116:119], v[144:147], v[168:171], v[116:119]
	v_mfma_f32_16x16x32_bf16 v[112:115], v[152:155], v[168:171], v[112:115]
	v_mfma_f32_16x16x32_bf16 v[108:111], v[144:147], v[176:179], v[108:111]
	v_mfma_f32_16x16x32_bf16 v[104:107], v[152:155], v[176:179], v[104:107]
	v_mfma_f32_16x16x32_bf16 v[100:103], v[144:147], v[186:189], v[100:103]
	v_mfma_f32_16x16x32_bf16 v[96:99], v[152:155], v[186:189], v[96:99]
	v_mfma_f32_16x16x32_bf16 v[124:127], v[148:151], v[164:167], v[124:127]
	v_mfma_f32_16x16x32_bf16 v[120:123], v[156:159], v[164:167], v[120:123]
	v_mfma_f32_16x16x32_bf16 v[116:119], v[148:151], v[172:175], v[116:119]
	v_mfma_f32_16x16x32_bf16 v[112:115], v[156:159], v[172:175], v[112:115]
	v_mfma_f32_16x16x32_bf16 v[108:111], v[148:151], v[180:183], v[108:111]
	v_mfma_f32_16x16x32_bf16 v[104:107], v[156:159], v[180:183], v[104:107]
	v_mfma_f32_16x16x32_bf16 v[100:103], v[148:151], v[194:197], v[100:103]
	v_mfma_f32_16x16x32_bf16 v[96:99], v[156:159], v[194:197], v[96:99]
	s_setprio 0
	s_barrier
	v_or_b32_e32 v190, 0x14000, v143
	v_add_u32_e32 v191, 0x14400, v143
	ds_read_b128 v[198:201], v190
	ds_read_b128 v[202:205], v191
	v_add_u32_e32 v190, 0x14800, v143
	v_add_u32_e32 v191, 0x14c00, v143
	s_mov_b32 m0, s1
	ds_read_b128 v[206:209], v190
	ds_read_b128 v[210:213], v191
	v_lshl_add_u64 v[190:191], s[34:35], 0, v[184:185]
	global_load_lds_dwordx4 v[190:191], off
	v_lshl_add_u64 v[214:215], s[34:35], 0, v[128:129]
	s_mov_b32 m0, s39
	s_nop 0
	global_load_lds_dwordx4 v[214:215], off
	s_barrier
	s_waitcnt lgkmcnt(0)
	s_setprio 1
	s_waitcnt lgkmcnt(0)
	v_mfma_f32_16x16x32_bf16 v[92:95], v[198:201], v[160:163], v[92:95]
	v_mfma_f32_16x16x32_bf16 v[88:91], v[206:209], v[160:163], v[88:91]
	v_mfma_f32_16x16x32_bf16 v[84:87], v[198:201], v[168:171], v[84:87]
	v_mfma_f32_16x16x32_bf16 v[80:83], v[206:209], v[168:171], v[80:83]
	v_mfma_f32_16x16x32_bf16 v[76:79], v[198:201], v[176:179], v[76:79]
	v_mfma_f32_16x16x32_bf16 v[72:75], v[206:209], v[176:179], v[72:75]
	v_mfma_f32_16x16x32_bf16 v[68:71], v[198:201], v[186:189], v[68:71]
	v_mfma_f32_16x16x32_bf16 v[64:67], v[206:209], v[186:189], v[64:67]
	v_mfma_f32_16x16x32_bf16 v[92:95], v[202:205], v[164:167], v[92:95]
	v_mfma_f32_16x16x32_bf16 v[88:91], v[210:213], v[164:167], v[88:91]
	v_mfma_f32_16x16x32_bf16 v[84:87], v[202:205], v[172:175], v[84:87]
	v_mfma_f32_16x16x32_bf16 v[80:83], v[210:213], v[172:175], v[80:83]
	v_mfma_f32_16x16x32_bf16 v[76:79], v[202:205], v[180:183], v[76:79]
	v_mfma_f32_16x16x32_bf16 v[72:75], v[210:213], v[180:183], v[72:75]
	v_mfma_f32_16x16x32_bf16 v[68:71], v[202:205], v[194:197], v[68:71]
	v_mfma_f32_16x16x32_bf16 v[64:67], v[210:213], v[194:197], v[64:67]
	s_setprio 0
	s_mov_b32 m0, s38
	v_lshl_add_u64 v[216:217], s[36:37], 0, v[132:133]
	s_barrier
	ds_read_b128 v[160:163], v142 offset:16384
	ds_read_b128 v[164:167], v142 offset:17408
	ds_read_b128 v[168:171], v142 offset:18432
	ds_read_b128 v[172:175], v142 offset:19456
	ds_read_b128 v[176:179], v142 offset:20480
	ds_read_b128 v[180:183], v142 offset:21504
	ds_read_b128 v[186:189], v142 offset:22528
	ds_read_b128 v[194:197], v142 offset:23552
	global_load_lds_dwordx4 v[216:217], off
	v_lshl_add_u64 v[242:243], s[36:37], 0, v[130:131]
	s_mov_b32 m0, s40
	s_nop 0
	global_load_lds_dwordx4 v[242:243], off
	s_barrier
	s_waitcnt lgkmcnt(0)
	s_setprio 1
	s_waitcnt lgkmcnt(0)
	v_mfma_f32_16x16x32_bf16 v[60:63], v[144:147], v[160:163], v[60:63]
	v_mfma_f32_16x16x32_bf16 v[56:59], v[152:155], v[160:163], v[56:59]
	v_mfma_f32_16x16x32_bf16 v[52:55], v[144:147], v[168:171], v[52:55]
	v_mfma_f32_16x16x32_bf16 v[48:51], v[152:155], v[168:171], v[48:51]
	v_mfma_f32_16x16x32_bf16 v[44:47], v[144:147], v[176:179], v[44:47]
	v_mfma_f32_16x16x32_bf16 v[40:43], v[152:155], v[176:179], v[40:43]
	v_mfma_f32_16x16x32_bf16 v[36:39], v[144:147], v[186:189], v[36:39]
	v_mfma_f32_16x16x32_bf16 v[32:35], v[152:155], v[186:189], v[32:35]
	v_mfma_f32_16x16x32_bf16 v[60:63], v[148:151], v[164:167], v[60:63]
	v_mfma_f32_16x16x32_bf16 v[56:59], v[156:159], v[164:167], v[56:59]
	v_mfma_f32_16x16x32_bf16 v[52:55], v[148:151], v[172:175], v[52:55]
	v_mfma_f32_16x16x32_bf16 v[48:51], v[156:159], v[172:175], v[48:51]
	v_mfma_f32_16x16x32_bf16 v[44:47], v[148:151], v[180:183], v[44:47]
	v_mfma_f32_16x16x32_bf16 v[40:43], v[156:159], v[180:183], v[40:43]
	v_mfma_f32_16x16x32_bf16 v[36:39], v[148:151], v[194:197], v[36:39]
	v_mfma_f32_16x16x32_bf16 v[32:35], v[156:159], v[194:197], v[32:35]
	s_setprio 0
	s_barrier
	s_add_u32 s62, s34, 0x100000
	s_addc_u32 s63, s35, 0
	s_mov_b32 m0, s41
	v_lshl_add_u64 v[144:145], s[62:63], 0, v[184:185]
	global_load_lds_dwordx4 v[144:145], off
	v_lshl_add_u64 v[144:145], s[62:63], 0, v[128:129]
	s_mov_b32 m0, s42
	s_nop 0
	global_load_lds_dwordx4 v[144:145], off
	s_waitcnt vmcnt(6)
	s_barrier
	s_setprio 1
	v_mfma_f32_16x16x32_bf16 v[28:31], v[198:201], v[160:163], v[28:31]
	v_mfma_f32_16x16x32_bf16 v[24:27], v[206:209], v[160:163], v[24:27]
	v_mfma_f32_16x16x32_bf16 v[20:23], v[198:201], v[168:171], v[20:23]
	v_mfma_f32_16x16x32_bf16 v[16:19], v[206:209], v[168:171], v[16:19]
	v_mfma_f32_16x16x32_bf16 v[12:15], v[198:201], v[176:179], v[12:15]
	v_mfma_f32_16x16x32_bf16 v[8:11], v[206:209], v[176:179], v[8:11]
	v_mfma_f32_16x16x32_bf16 v[4:7], v[198:201], v[186:189], v[4:7]
	v_mfma_f32_16x16x32_bf16 v[0:3], v[206:209], v[186:189], v[0:3]
	v_mfma_f32_16x16x32_bf16 v[28:31], v[202:205], v[164:167], v[28:31]
	v_mfma_f32_16x16x32_bf16 v[24:27], v[210:213], v[164:167], v[24:27]
	v_mfma_f32_16x16x32_bf16 v[20:23], v[202:205], v[172:175], v[20:23]
	v_mfma_f32_16x16x32_bf16 v[16:19], v[210:213], v[172:175], v[16:19]
	v_mfma_f32_16x16x32_bf16 v[12:15], v[202:205], v[180:183], v[12:15]
	v_mfma_f32_16x16x32_bf16 v[8:11], v[210:213], v[180:183], v[8:11]
	v_mfma_f32_16x16x32_bf16 v[4:7], v[202:205], v[194:197], v[4:7]
	v_mfma_f32_16x16x32_bf16 v[0:3], v[210:213], v[194:197], v[0:3]
	s_setprio 0
	v_or_b32_e32 v144, 0x18000, v143
	v_add_u32_e32 v148, 0x18400, v143
	v_add_u32_e32 v152, 0x18800, v143
	v_add_u32_e32 v156, 0x18c00, v143
	s_barrier
	ds_read_b128 v[144:147], v144
	ds_read_b128 v[148:151], v148
	ds_read_b128 v[152:155], v152
	ds_read_b128 v[156:159], v156
	s_add_u32 s36, s36, 0x20000
	s_addc_u32 s37, s37, 0
	s_mov_b32 m0, s43
	v_lshl_add_u64 v[198:199], s[36:37], 0, v[132:133]
	ds_read_b128 v[160:163], v142 offset:32768
	ds_read_b128 v[164:167], v142 offset:33792
	ds_read_b128 v[168:171], v142 offset:34816
	ds_read_b128 v[172:175], v142 offset:35840
	ds_read_b128 v[176:179], v142 offset:36864
	ds_read_b128 v[180:183], v142 offset:37888
	ds_read_b128 v[186:189], v142 offset:38912
	ds_read_b128 v[194:197], v142 offset:39936
	global_load_lds_dwordx4 v[198:199], off
	v_lshl_add_u64 v[198:199], s[36:37], 0, v[130:131]
	s_mov_b32 m0, s44
	s_nop 0
	global_load_lds_dwordx4 v[198:199], off
	s_waitcnt lgkmcnt(8)
	s_barrier
	s_waitcnt lgkmcnt(0)
	s_setprio 1
	s_waitcnt lgkmcnt(0)
	v_mfma_f32_16x16x32_bf16 v[124:127], v[144:147], v[160:163], v[124:127]
	v_mfma_f32_16x16x32_bf16 v[120:123], v[152:155], v[160:163], v[120:123]
	v_mfma_f32_16x16x32_bf16 v[116:119], v[144:147], v[168:171], v[116:119]
	v_mfma_f32_16x16x32_bf16 v[112:115], v[152:155], v[168:171], v[112:115]
	v_mfma_f32_16x16x32_bf16 v[108:111], v[144:147], v[176:179], v[108:111]
	v_mfma_f32_16x16x32_bf16 v[104:107], v[152:155], v[176:179], v[104:107]
	v_mfma_f32_16x16x32_bf16 v[100:103], v[144:147], v[186:189], v[100:103]
	v_mfma_f32_16x16x32_bf16 v[96:99], v[152:155], v[186:189], v[96:99]
	v_mfma_f32_16x16x32_bf16 v[124:127], v[148:151], v[164:167], v[124:127]
	v_mfma_f32_16x16x32_bf16 v[120:123], v[156:159], v[164:167], v[120:123]
	v_mfma_f32_16x16x32_bf16 v[116:119], v[148:151], v[172:175], v[116:119]
	v_mfma_f32_16x16x32_bf16 v[112:115], v[156:159], v[172:175], v[112:115]
	v_mfma_f32_16x16x32_bf16 v[108:111], v[148:151], v[180:183], v[108:111]
	v_mfma_f32_16x16x32_bf16 v[104:107], v[156:159], v[180:183], v[104:107]
	v_mfma_f32_16x16x32_bf16 v[100:103], v[148:151], v[194:197], v[100:103]
	v_mfma_f32_16x16x32_bf16 v[96:99], v[156:159], v[194:197], v[96:99]
	s_setprio 0
	s_barrier
	v_or_b32_e32 v192, 0x1c000, v143
	v_add_u32_e32 v202, 0x1c400, v143
	s_mov_b32 m0, s45
	ds_read_b128 v[198:201], v192
	ds_read_b128 v[202:205], v202
	v_add_u32_e32 v192, 0x1c800, v143
	v_add_u32_e32 v210, 0x1cc00, v143
	v_lshl_add_u64 v[190:191], v[190:191], 0, s[24:25]
	ds_read_b128 v[206:209], v192
	ds_read_b128 v[210:213], v210
	global_load_lds_dwordx4 v[190:191], off
	v_lshl_add_u64 v[190:191], v[214:215], 0, s[24:25]
	s_mov_b32 m0, s46
	s_nop 0
	global_load_lds_dwordx4 v[190:191], off
	s_barrier
	s_waitcnt lgkmcnt(0)
	s_setprio 1
	s_waitcnt lgkmcnt(0)
	v_mfma_f32_16x16x32_bf16 v[92:95], v[198:201], v[160:163], v[92:95]
	v_mfma_f32_16x16x32_bf16 v[88:91], v[206:209], v[160:163], v[88:91]
	v_mfma_f32_16x16x32_bf16 v[84:87], v[198:201], v[168:171], v[84:87]
	v_mfma_f32_16x16x32_bf16 v[80:83], v[206:209], v[168:171], v[80:83]
	v_mfma_f32_16x16x32_bf16 v[76:79], v[198:201], v[176:179], v[76:79]
	v_mfma_f32_16x16x32_bf16 v[72:75], v[206:209], v[176:179], v[72:75]
	v_mfma_f32_16x16x32_bf16 v[68:71], v[198:201], v[186:189], v[68:71]
	v_mfma_f32_16x16x32_bf16 v[64:67], v[206:209], v[186:189], v[64:67]
	v_mfma_f32_16x16x32_bf16 v[92:95], v[202:205], v[164:167], v[92:95]
	v_mfma_f32_16x16x32_bf16 v[88:91], v[210:213], v[164:167], v[88:91]
	v_mfma_f32_16x16x32_bf16 v[84:87], v[202:205], v[172:175], v[84:87]
	v_mfma_f32_16x16x32_bf16 v[80:83], v[210:213], v[172:175], v[80:83]
	v_mfma_f32_16x16x32_bf16 v[76:79], v[202:205], v[180:183], v[76:79]
	v_mfma_f32_16x16x32_bf16 v[72:75], v[210:213], v[180:183], v[72:75]
	v_mfma_f32_16x16x32_bf16 v[68:71], v[202:205], v[194:197], v[68:71]
	v_mfma_f32_16x16x32_bf16 v[64:67], v[210:213], v[194:197], v[64:67]
	s_setprio 0
	s_mov_b32 m0, s47
	v_lshl_add_u64 v[190:191], v[216:217], 0, s[24:25]
	s_barrier
	ds_read_b128 v[160:163], v142 offset:49152
	ds_read_b128 v[164:167], v142 offset:50176
	ds_read_b128 v[168:171], v142 offset:51200
	ds_read_b128 v[172:175], v142 offset:52224
	ds_read_b128 v[176:179], v142 offset:53248
	ds_read_b128 v[180:183], v142 offset:54272
	ds_read_b128 v[186:189], v142 offset:55296
	ds_read_b128 v[194:197], v142 offset:56320
	global_load_lds_dwordx4 v[190:191], off
	v_lshl_add_u64 v[190:191], v[242:243], 0, s[24:25]
	s_mov_b32 m0, s48
	s_nop 0
	global_load_lds_dwordx4 v[190:191], off
	s_barrier
	s_waitcnt lgkmcnt(0)
	s_setprio 1
	s_waitcnt lgkmcnt(0)
	v_mfma_f32_16x16x32_bf16 v[60:63], v[144:147], v[160:163], v[60:63]
	v_mfma_f32_16x16x32_bf16 v[56:59], v[152:155], v[160:163], v[56:59]
	v_mfma_f32_16x16x32_bf16 v[52:55], v[144:147], v[168:171], v[52:55]
	v_mfma_f32_16x16x32_bf16 v[48:51], v[152:155], v[168:171], v[48:51]
	v_mfma_f32_16x16x32_bf16 v[44:47], v[144:147], v[176:179], v[44:47]
	v_mfma_f32_16x16x32_bf16 v[40:43], v[152:155], v[176:179], v[40:43]
	v_mfma_f32_16x16x32_bf16 v[36:39], v[144:147], v[186:189], v[36:39]
	v_mfma_f32_16x16x32_bf16 v[32:35], v[152:155], v[186:189], v[32:35]
	v_mfma_f32_16x16x32_bf16 v[60:63], v[148:151], v[164:167], v[60:63]
	v_mfma_f32_16x16x32_bf16 v[56:59], v[156:159], v[164:167], v[56:59]
	v_mfma_f32_16x16x32_bf16 v[52:55], v[148:151], v[172:175], v[52:55]
	v_mfma_f32_16x16x32_bf16 v[48:51], v[156:159], v[172:175], v[48:51]
	v_mfma_f32_16x16x32_bf16 v[44:47], v[148:151], v[180:183], v[44:47]
	v_mfma_f32_16x16x32_bf16 v[40:43], v[156:159], v[180:183], v[40:43]
	v_mfma_f32_16x16x32_bf16 v[36:39], v[148:151], v[194:197], v[36:39]
	v_mfma_f32_16x16x32_bf16 v[32:35], v[156:159], v[194:197], v[32:35]
	s_setprio 0
	s_barrier
	s_add_u32 s34, s34, 0x100080
	s_addc_u32 s35, s35, 0
	s_mov_b32 m0, s49
	v_lshl_add_u64 v[144:145], s[34:35], 0, v[184:185]
	global_load_lds_dwordx4 v[144:145], off
	v_lshl_add_u64 v[144:145], s[34:35], 0, v[128:129]
	s_mov_b32 m0, s50
	s_nop 0
	global_load_lds_dwordx4 v[144:145], off
	s_waitcnt vmcnt(6)
	s_barrier
	s_setprio 1
	v_mfma_f32_16x16x32_bf16 v[28:31], v[198:201], v[160:163], v[28:31]
	v_mfma_f32_16x16x32_bf16 v[24:27], v[206:209], v[160:163], v[24:27]
	v_mfma_f32_16x16x32_bf16 v[20:23], v[198:201], v[168:171], v[20:23]
	v_mfma_f32_16x16x32_bf16 v[16:19], v[206:209], v[168:171], v[16:19]
	v_mfma_f32_16x16x32_bf16 v[12:15], v[198:201], v[176:179], v[12:15]
	v_mfma_f32_16x16x32_bf16 v[8:11], v[206:209], v[176:179], v[8:11]
	v_mfma_f32_16x16x32_bf16 v[4:7], v[198:201], v[186:189], v[4:7]
	v_mfma_f32_16x16x32_bf16 v[0:3], v[206:209], v[186:189], v[0:3]
	v_mfma_f32_16x16x32_bf16 v[28:31], v[202:205], v[164:167], v[28:31]
	v_mfma_f32_16x16x32_bf16 v[24:27], v[210:213], v[164:167], v[24:27]
	v_mfma_f32_16x16x32_bf16 v[20:23], v[202:205], v[172:175], v[20:23]
	v_mfma_f32_16x16x32_bf16 v[16:19], v[210:213], v[172:175], v[16:19]
	v_mfma_f32_16x16x32_bf16 v[12:15], v[202:205], v[180:183], v[12:15]
	v_mfma_f32_16x16x32_bf16 v[8:11], v[210:213], v[180:183], v[8:11]
	v_mfma_f32_16x16x32_bf16 v[4:7], v[202:205], v[194:197], v[4:7]
	v_mfma_f32_16x16x32_bf16 v[0:3], v[210:213], v[194:197], v[0:3]
	s_setprio 0
	s_add_i32 s61, s61, 2
	s_add_u32 s30, s30, 0x100
	s_addc_u32 s31, s31, 0
	s_add_u32 s26, s26, 0x100
	s_addc_u32 s27, s27, 0
	s_cmp_gt_u32 s61, 5
	s_barrier
	s_cbranch_scc0 .LBB0_245
	s_lshl_b32 s20, s59, 4
	s_add_i32 s30, s20, s51
	s_add_i32 s34, s52, s20
	s_add_i32 s36, s53, s20
	s_ashr_i32 s31, s30, 31
	s_ashr_i32 s35, s34, 31
	s_ashr_i32 s37, s36, 31
	s_lshl_b64 s[26:27], s[30:31], 13
	s_lshl_b64 s[34:35], s[34:35], 13
	s_lshl_b64 s[36:37], s[36:37], 13
	v_cvt_pk_bf16_f32 v124, v124, v125
	v_cvt_pk_bf16_f32 v125, v126, v127
	v_cvt_pk_bf16_f32 v126, v120, v121
	v_lshl_add_u64 v[120:121], v[134:135], 0, s[26:27]
	v_cvt_pk_bf16_f32 v116, v116, v117
	v_cvt_pk_bf16_f32 v117, v118, v119
	v_cvt_pk_bf16_f32 v118, v112, v113
	v_lshl_add_u64 v[112:113], v[134:135], 0, s[34:35]
	v_cvt_pk_bf16_f32 v108, v108, v109
	v_cvt_pk_bf16_f32 v109, v110, v111
	v_cvt_pk_bf16_f32 v110, v104, v105
	v_lshl_add_u64 v[104:105], v[134:135], 0, s[36:37]
	s_add_i32 s60, s54, s20
	v_cvt_pk_bf16_f32 v92, v92, v93
	v_cvt_pk_bf16_f32 v93, v94, v95
	v_cvt_pk_bf16_f32 v94, v88, v89
	v_lshl_add_u64 v[88:89], v[136:137], 0, s[26:27]
	v_cvt_pk_bf16_f32 v84, v84, v85
	v_cvt_pk_bf16_f32 v85, v86, v87
	v_cvt_pk_bf16_f32 v86, v80, v81
	v_lshl_add_u64 v[80:81], v[136:137], 0, s[34:35]
	v_cvt_pk_bf16_f32 v76, v76, v77
	v_cvt_pk_bf16_f32 v77, v78, v79
	v_cvt_pk_bf16_f32 v78, v72, v73
	v_lshl_add_u64 v[72:73], v[136:137], 0, s[36:37]
	s_add_i32 s26, s30, 8
	s_add_i32 s34, s30, 9
	s_add_i32 s36, s30, 10
	s_add_i32 s30, s30, 11
	s_ashr_i32 s61, s60, 31
	s_ashr_i32 s27, s26, 31
	s_ashr_i32 s35, s34, 31
	s_ashr_i32 s37, s36, 31
	s_ashr_i32 s31, s30, 31
	s_lshl_b64 s[60:61], s[60:61], 13
	s_lshl_b64 s[26:27], s[26:27], 13
	s_lshl_b64 s[34:35], s[34:35], 13
	s_lshl_b64 s[36:37], s[36:37], 13
	s_lshl_b64 s[30:31], s[30:31], 13
	v_cvt_pk_bf16_f32 v100, v100, v101
	v_cvt_pk_bf16_f32 v101, v102, v103
	v_cvt_pk_bf16_f32 v102, v96, v97
	v_lshl_add_u64 v[96:97], v[134:135], 0, s[60:61]
	v_cvt_pk_bf16_f32 v68, v68, v69
	v_cvt_pk_bf16_f32 v69, v70, v71
	v_cvt_pk_bf16_f32 v70, v64, v65
	v_lshl_add_u64 v[64:65], v[136:137], 0, s[60:61]
	v_cvt_pk_bf16_f32 v60, v60, v61
	v_cvt_pk_bf16_f32 v61, v62, v63
	v_cvt_pk_bf16_f32 v62, v56, v57
	v_lshl_add_u64 v[56:57], v[134:135], 0, s[26:27]
	v_cvt_pk_bf16_f32 v52, v52, v53
	v_cvt_pk_bf16_f32 v53, v54, v55
	v_cvt_pk_bf16_f32 v54, v48, v49
	v_lshl_add_u64 v[48:49], v[134:135], 0, s[34:35]
	v_cvt_pk_bf16_f32 v44, v44, v45
	v_cvt_pk_bf16_f32 v45, v46, v47
	v_cvt_pk_bf16_f32 v46, v40, v41
	v_lshl_add_u64 v[40:41], v[134:135], 0, s[36:37]
	v_cvt_pk_bf16_f32 v36, v36, v37
	v_cvt_pk_bf16_f32 v37, v38, v39
	v_cvt_pk_bf16_f32 v38, v32, v33
	v_lshl_add_u64 v[32:33], v[134:135], 0, s[30:31]
	v_cvt_pk_bf16_f32 v28, v28, v29
	v_cvt_pk_bf16_f32 v29, v30, v31
	v_cvt_pk_bf16_f32 v30, v24, v25
	v_lshl_add_u64 v[24:25], v[136:137], 0, s[26:27]
	v_cvt_pk_bf16_f32 v20, v20, v21
	v_cvt_pk_bf16_f32 v21, v22, v23
	v_cvt_pk_bf16_f32 v22, v16, v17
	v_lshl_add_u64 v[16:17], v[136:137], 0, s[34:35]
	v_cvt_pk_bf16_f32 v12, v12, v13
	v_cvt_pk_bf16_f32 v13, v14, v15
	v_cvt_pk_bf16_f32 v14, v8, v9
	v_lshl_add_u64 v[8:9], v[136:137], 0, s[36:37]
	v_cvt_pk_bf16_f32 v4, v4, v5
	v_cvt_pk_bf16_f32 v5, v6, v7
	v_cvt_pk_bf16_f32 v6, v0, v1
	v_lshl_add_u64 v[0:1], v[136:137], 0, s[30:31]
	s_and_b64 vcc, exec, s[28:29]
	s_mov_b32 s59, s58
	v_cvt_pk_bf16_f32 v127, v122, v123
	global_store_dwordx4 v[120:121], v[124:127], off sc1
	v_cvt_pk_bf16_f32 v119, v114, v115
	global_store_dwordx4 v[112:113], v[116:119], off sc1
	v_cvt_pk_bf16_f32 v111, v106, v107
	global_store_dwordx4 v[104:105], v[108:111], off sc1
	v_cvt_pk_bf16_f32 v103, v98, v99
	global_store_dwordx4 v[96:97], v[100:103], off sc1
	v_cvt_pk_bf16_f32 v95, v90, v91
	global_store_dwordx4 v[88:89], v[92:95], off sc1
	v_cvt_pk_bf16_f32 v87, v82, v83
	global_store_dwordx4 v[80:81], v[84:87], off sc1
	v_cvt_pk_bf16_f32 v79, v74, v75
	global_store_dwordx4 v[72:73], v[76:79], off sc1
	v_cvt_pk_bf16_f32 v71, v66, v67
	global_store_dwordx4 v[64:65], v[68:71], off sc1
	v_cvt_pk_bf16_f32 v63, v58, v59
	global_store_dwordx4 v[56:57], v[60:63], off sc1
	v_cvt_pk_bf16_f32 v55, v50, v51
	global_store_dwordx4 v[48:49], v[52:55], off sc1
	v_cvt_pk_bf16_f32 v47, v42, v43
	global_store_dwordx4 v[40:41], v[44:47], off sc1
	v_cvt_pk_bf16_f32 v39, v34, v35
	global_store_dwordx4 v[32:33], v[36:39], off sc1
	v_cvt_pk_bf16_f32 v31, v26, v27
	global_store_dwordx4 v[24:25], v[28:31], off sc1
	v_cvt_pk_bf16_f32 v23, v18, v19
	global_store_dwordx4 v[16:17], v[20:23], off sc1
	v_cvt_pk_bf16_f32 v15, v10, v11
	global_store_dwordx4 v[8:9], v[12:15], off sc1
	v_cvt_pk_bf16_f32 v7, v2, v3
	global_store_dwordx4 v[0:1], v[4:7], off sc1
	s_cbranch_vccz .LBB0_244
	s_waitcnt vmcnt(0)
	s_cmpk_gt_u32 s33, 0xff
	s_cbranch_scc1 .LBB0_249
	s_barrier

.LBB0_299:
	v_or_b32_e32 v128, 0x10000, v143
	v_add_u32_e32 v152, 0x10400, v143
	v_add_u32_e32 v157, 0x10800, v143
	v_add_u32_e32 v162, 0x10c00, v143
	ds_read_b128 v[128:131], v128
	ds_read_b128 v[152:155], v152
	ds_read_b128 v[158:161], v157
	ds_read_b128 v[162:165], v162
	s_add_u32 s28, s0, 0xfffc0080
	s_addc_u32 s29, s1, -1
	s_cmp_eq_u32 s27, 12
	s_cselect_b32 s31, s20, s29
	s_cselect_b32 s30, s34, s28
	s_cselect_b32 s29, s35, s26
	s_cselect_b32 s28, s36, s37
	v_lshl_add_u64 v[182:183], s[0:1], 0, v[148:149]
	s_add_i32 m0, s58, 0xc000
	ds_read_b128 v[166:169], v141
	ds_read_b128 v[170:173], v141 offset:1024
	ds_read_b128 v[174:177], v141 offset:2048
	ds_read_b128 v[178:181], v141 offset:3072
	ds_read_b128 v[186:189], v141 offset:4096
	ds_read_b128 v[194:197], v141 offset:5120
	ds_read_b128 v[198:201], v141 offset:6144
	ds_read_b128 v[202:205], v141 offset:7168
	global_load_lds_dwordx4 v[182:183], off
	v_lshl_add_u64 v[182:183], s[0:1], 0, v[150:151]
	s_add_i32 m0, s58, 0xe000
	s_nop 0
	global_load_lds_dwordx4 v[182:183], off
	s_waitcnt lgkmcnt(8)
	s_barrier
	s_waitcnt lgkmcnt(0)
	s_setprio 1
	s_waitcnt lgkmcnt(0)
	v_mfma_f32_16x16x32_bf16 v[124:127], v[128:131], v[166:169], v[124:127]
	v_mfma_f32_16x16x32_bf16 v[120:123], v[158:161], v[166:169], v[120:123]
	v_mfma_f32_16x16x32_bf16 v[116:119], v[128:131], v[174:177], v[116:119]
	v_mfma_f32_16x16x32_bf16 v[112:115], v[158:161], v[174:177], v[112:115]
	v_mfma_f32_16x16x32_bf16 v[108:111], v[128:131], v[186:189], v[108:111]
	v_mfma_f32_16x16x32_bf16 v[104:107], v[158:161], v[186:189], v[104:107]
	v_mfma_f32_16x16x32_bf16 v[100:103], v[128:131], v[198:201], v[100:103]
	v_mfma_f32_16x16x32_bf16 v[96:99], v[158:161], v[198:201], v[96:99]
	v_mfma_f32_16x16x32_bf16 v[124:127], v[152:155], v[170:173], v[124:127]
	v_mfma_f32_16x16x32_bf16 v[120:123], v[162:165], v[170:173], v[120:123]
	v_mfma_f32_16x16x32_bf16 v[116:119], v[152:155], v[178:181], v[116:119]
	v_mfma_f32_16x16x32_bf16 v[112:115], v[162:165], v[178:181], v[112:115]
	v_mfma_f32_16x16x32_bf16 v[108:111], v[152:155], v[194:197], v[108:111]
	v_mfma_f32_16x16x32_bf16 v[104:107], v[162:165], v[194:197], v[104:107]
	v_mfma_f32_16x16x32_bf16 v[100:103], v[152:155], v[202:205], v[100:103]
	v_mfma_f32_16x16x32_bf16 v[96:99], v[162:165], v[202:205], v[96:99]
	s_setprio 0
	s_barrier
	v_or_b32_e32 v157, 0x14000, v143
	v_add_u32_e32 v182, 0x14400, v143
	ds_read_b128 v[206:209], v157
	ds_read_b128 v[210:213], v182
	v_add_u32_e32 v157, 0x14800, v143
	v_add_u32_e32 v182, 0x14c00, v143
	s_mov_b32 m0, s39
	ds_read_b128 v[214:217], v157
	ds_read_b128 v[242:245], v182
	v_lshl_add_u64 v[182:183], s[28:29], 0, v[134:135]
	global_load_lds_dwordx4 v[182:183], off
	v_lshl_add_u64 v[190:191], s[28:29], 0, v[138:139]
	s_mov_b32 m0, s59
	s_nop 0
	global_load_lds_dwordx4 v[190:191], off
	s_barrier
	s_waitcnt lgkmcnt(0)
	s_setprio 1
	s_waitcnt lgkmcnt(0)
	v_mfma_f32_16x16x32_bf16 v[92:95], v[206:209], v[166:169], v[92:95]
	v_mfma_f32_16x16x32_bf16 v[88:91], v[214:217], v[166:169], v[88:91]
	v_mfma_f32_16x16x32_bf16 v[84:87], v[206:209], v[174:177], v[84:87]
	v_mfma_f32_16x16x32_bf16 v[80:83], v[214:217], v[174:177], v[80:83]
	v_mfma_f32_16x16x32_bf16 v[76:79], v[206:209], v[186:189], v[76:79]
	v_mfma_f32_16x16x32_bf16 v[72:75], v[214:217], v[186:189], v[72:75]
	v_mfma_f32_16x16x32_bf16 v[68:71], v[206:209], v[198:201], v[68:71]
	v_mfma_f32_16x16x32_bf16 v[64:67], v[214:217], v[198:201], v[64:67]
	v_mfma_f32_16x16x32_bf16 v[92:95], v[210:213], v[170:173], v[92:95]
	v_mfma_f32_16x16x32_bf16 v[88:91], v[242:245], v[170:173], v[88:91]
	v_mfma_f32_16x16x32_bf16 v[84:87], v[210:213], v[178:181], v[84:87]
	v_mfma_f32_16x16x32_bf16 v[80:83], v[242:245], v[178:181], v[80:83]
	v_mfma_f32_16x16x32_bf16 v[76:79], v[210:213], v[194:197], v[76:79]
	v_mfma_f32_16x16x32_bf16 v[72:75], v[242:245], v[194:197], v[72:75]
	v_mfma_f32_16x16x32_bf16 v[68:71], v[210:213], v[202:205], v[68:71]
	v_mfma_f32_16x16x32_bf16 v[64:67], v[242:245], v[202:205], v[64:67]
	s_setprio 0
	s_mov_b32 m0, s58
	v_lshl_add_u64 v[246:247], s[30:31], 0, v[132:133]
	s_barrier
	ds_read_b128 v[166:169], v141 offset:16384
	ds_read_b128 v[170:173], v141 offset:17408
	ds_read_b128 v[174:177], v141 offset:18432
	ds_read_b128 v[178:181], v141 offset:19456
	ds_read_b128 v[186:189], v141 offset:20480
	ds_read_b128 v[194:197], v141 offset:21504
	ds_read_b128 v[198:201], v141 offset:22528
	ds_read_b128 v[202:205], v141 offset:23552
	global_load_lds_dwordx4 v[246:247], off
	v_lshl_add_u64 v[248:249], s[30:31], 0, v[136:137]
	s_mov_b32 m0, s60
	s_nop 0
	global_load_lds_dwordx4 v[248:249], off
	s_barrier
	s_waitcnt lgkmcnt(0)
	s_setprio 1
	s_waitcnt lgkmcnt(0)
	v_mfma_f32_16x16x32_bf16 v[60:63], v[128:131], v[166:169], v[60:63]
	v_mfma_f32_16x16x32_bf16 v[56:59], v[158:161], v[166:169], v[56:59]
	v_mfma_f32_16x16x32_bf16 v[52:55], v[128:131], v[174:177], v[52:55]
	v_mfma_f32_16x16x32_bf16 v[48:51], v[158:161], v[174:177], v[48:51]
	v_mfma_f32_16x16x32_bf16 v[44:47], v[128:131], v[186:189], v[44:47]
	v_mfma_f32_16x16x32_bf16 v[40:43], v[158:161], v[186:189], v[40:43]
	v_mfma_f32_16x16x32_bf16 v[36:39], v[128:131], v[198:201], v[36:39]
	v_mfma_f32_16x16x32_bf16 v[32:35], v[158:161], v[198:201], v[32:35]
	v_mfma_f32_16x16x32_bf16 v[60:63], v[152:155], v[170:173], v[60:63]
	v_mfma_f32_16x16x32_bf16 v[56:59], v[162:165], v[170:173], v[56:59]
	v_mfma_f32_16x16x32_bf16 v[52:55], v[152:155], v[178:181], v[52:55]
	v_mfma_f32_16x16x32_bf16 v[48:51], v[162:165], v[178:181], v[48:51]
	v_mfma_f32_16x16x32_bf16 v[44:47], v[152:155], v[194:197], v[44:47]
	v_mfma_f32_16x16x32_bf16 v[40:43], v[162:165], v[194:197], v[40:43]
	v_mfma_f32_16x16x32_bf16 v[36:39], v[152:155], v[202:205], v[36:39]
	v_mfma_f32_16x16x32_bf16 v[32:35], v[162:165], v[202:205], v[32:35]
	s_setprio 0
	s_barrier
	s_add_u32 s46, s28, 0x40000
	s_addc_u32 s47, s29, 0
	s_mov_b32 m0, s61
	v_lshl_add_u64 v[128:129], s[46:47], 0, v[134:135]
	global_load_lds_dwordx4 v[128:129], off
	v_lshl_add_u64 v[128:129], s[46:47], 0, v[138:139]
	s_mov_b32 m0, s62
	s_nop 0
	global_load_lds_dwordx4 v[128:129], off
	s_waitcnt vmcnt(6)
	s_barrier
	s_setprio 1
	v_mfma_f32_16x16x32_bf16 v[28:31], v[206:209], v[166:169], v[28:31]
	v_mfma_f32_16x16x32_bf16 v[24:27], v[214:217], v[166:169], v[24:27]
	v_mfma_f32_16x16x32_bf16 v[20:23], v[206:209], v[174:177], v[20:23]
	v_mfma_f32_16x16x32_bf16 v[16:19], v[214:217], v[174:177], v[16:19]
	v_mfma_f32_16x16x32_bf16 v[12:15], v[206:209], v[186:189], v[12:15]
	v_mfma_f32_16x16x32_bf16 v[8:11], v[214:217], v[186:189], v[8:11]
	v_mfma_f32_16x16x32_bf16 v[4:7], v[206:209], v[198:201], v[4:7]
	v_mfma_f32_16x16x32_bf16 v[0:3], v[214:217], v[198:201], v[0:3]
	v_mfma_f32_16x16x32_bf16 v[28:31], v[210:213], v[170:173], v[28:31]
	v_mfma_f32_16x16x32_bf16 v[24:27], v[242:245], v[170:173], v[24:27]
	v_mfma_f32_16x16x32_bf16 v[20:23], v[210:213], v[178:181], v[20:23]
	v_mfma_f32_16x16x32_bf16 v[16:19], v[242:245], v[178:181], v[16:19]
	v_mfma_f32_16x16x32_bf16 v[12:15], v[210:213], v[194:197], v[12:15]
	v_mfma_f32_16x16x32_bf16 v[8:11], v[242:245], v[194:197], v[8:11]
	v_mfma_f32_16x16x32_bf16 v[4:7], v[210:213], v[202:205], v[4:7]
	v_mfma_f32_16x16x32_bf16 v[0:3], v[242:245], v[202:205], v[0:3]
	s_setprio 0
	v_or_b32_e32 v128, 0x18000, v143
	v_add_u32_e32 v152, 0x18400, v143
	v_add_u32_e32 v157, 0x18800, v143
	v_add_u32_e32 v162, 0x18c00, v143
	s_barrier
	ds_read_b128 v[128:131], v128
	ds_read_b128 v[152:155], v152
	ds_read_b128 v[158:161], v157
	ds_read_b128 v[162:165], v162
	s_add_u32 s30, s30, 0x40000
	s_addc_u32 s31, s31, 0
	s_mov_b32 m0, s63
	v_lshl_add_u64 v[206:207], s[30:31], 0, v[132:133]
	ds_read_b128 v[166:169], v141 offset:32768
	ds_read_b128 v[170:173], v141 offset:33792
	ds_read_b128 v[174:177], v141 offset:34816
	ds_read_b128 v[178:181], v141 offset:35840
	ds_read_b128 v[186:189], v141 offset:36864
	ds_read_b128 v[194:197], v141 offset:37888
	ds_read_b128 v[198:201], v141 offset:38912
	ds_read_b128 v[202:205], v141 offset:39936
	global_load_lds_dwordx4 v[206:207], off
	v_lshl_add_u64 v[206:207], s[30:31], 0, v[136:137]
	s_mov_b32 m0, s64
	s_nop 0
	global_load_lds_dwordx4 v[206:207], off
	s_waitcnt lgkmcnt(8)
	s_barrier
	s_waitcnt lgkmcnt(0)
	s_setprio 1
	s_waitcnt lgkmcnt(0)
	v_mfma_f32_16x16x32_bf16 v[124:127], v[128:131], v[166:169], v[124:127]
	v_mfma_f32_16x16x32_bf16 v[120:123], v[158:161], v[166:169], v[120:123]
	v_mfma_f32_16x16x32_bf16 v[116:119], v[128:131], v[174:177], v[116:119]
	v_mfma_f32_16x16x32_bf16 v[112:115], v[158:161], v[174:177], v[112:115]
	v_mfma_f32_16x16x32_bf16 v[108:111], v[128:131], v[186:189], v[108:111]
	v_mfma_f32_16x16x32_bf16 v[104:107], v[158:161], v[186:189], v[104:107]
	v_mfma_f32_16x16x32_bf16 v[100:103], v[128:131], v[198:201], v[100:103]
	v_mfma_f32_16x16x32_bf16 v[96:99], v[158:161], v[198:201], v[96:99]
	v_mfma_f32_16x16x32_bf16 v[124:127], v[152:155], v[170:173], v[124:127]
	v_mfma_f32_16x16x32_bf16 v[120:123], v[162:165], v[170:173], v[120:123]
	v_mfma_f32_16x16x32_bf16 v[116:119], v[152:155], v[178:181], v[116:119]
	v_mfma_f32_16x16x32_bf16 v[112:115], v[162:165], v[178:181], v[112:115]
	v_mfma_f32_16x16x32_bf16 v[108:111], v[152:155], v[194:197], v[108:111]
	v_mfma_f32_16x16x32_bf16 v[104:107], v[162:165], v[194:197], v[104:107]
	v_mfma_f32_16x16x32_bf16 v[100:103], v[152:155], v[202:205], v[100:103]
	v_mfma_f32_16x16x32_bf16 v[96:99], v[162:165], v[202:205], v[96:99]
	s_setprio 0
	s_barrier
	v_or_b32_e32 v157, 0x1c000, v143
	s_mov_b32 m0, s68
	v_add_u32_e32 v184, 0x1c400, v143
	ds_read_b128 v[206:209], v157
	ds_read_b128 v[210:213], v184
	v_add_u32_e32 v157, 0x1c800, v143
	v_lshl_add_u64 v[182:183], v[182:183], 0, s[24:25]
	v_add_u32_e32 v184, 0x1cc00, v143
	ds_read_b128 v[214:217], v157
	ds_read_b128 v[242:245], v184
	global_load_lds_dwordx4 v[182:183], off
	v_lshl_add_u64 v[182:183], v[190:191], 0, s[24:25]
	s_mov_b32 m0, s69
	s_nop 0
	global_load_lds_dwordx4 v[182:183], off
	s_barrier
	s_waitcnt lgkmcnt(0)
	s_setprio 1
	s_waitcnt lgkmcnt(0)
	v_mfma_f32_16x16x32_bf16 v[92:95], v[206:209], v[166:169], v[92:95]
	v_mfma_f32_16x16x32_bf16 v[88:91], v[214:217], v[166:169], v[88:91]
	v_mfma_f32_16x16x32_bf16 v[84:87], v[206:209], v[174:177], v[84:87]
	v_mfma_f32_16x16x32_bf16 v[80:83], v[214:217], v[174:177], v[80:83]
	v_mfma_f32_16x16x32_bf16 v[76:79], v[206:209], v[186:189], v[76:79]
	v_mfma_f32_16x16x32_bf16 v[72:75], v[214:217], v[186:189], v[72:75]
	v_mfma_f32_16x16x32_bf16 v[68:71], v[206:209], v[198:201], v[68:71]
	v_mfma_f32_16x16x32_bf16 v[64:67], v[214:217], v[198:201], v[64:67]
	v_mfma_f32_16x16x32_bf16 v[92:95], v[210:213], v[170:173], v[92:95]
	v_mfma_f32_16x16x32_bf16 v[88:91], v[242:245], v[170:173], v[88:91]
	v_mfma_f32_16x16x32_bf16 v[84:87], v[210:213], v[178:181], v[84:87]
	v_mfma_f32_16x16x32_bf16 v[80:83], v[242:245], v[178:181], v[80:83]
	v_mfma_f32_16x16x32_bf16 v[76:79], v[210:213], v[194:197], v[76:79]
	v_mfma_f32_16x16x32_bf16 v[72:75], v[242:245], v[194:197], v[72:75]
	v_mfma_f32_16x16x32_bf16 v[68:71], v[210:213], v[202:205], v[68:71]
	v_mfma_f32_16x16x32_bf16 v[64:67], v[242:245], v[202:205], v[64:67]
	s_setprio 0
	s_mov_b32 m0, s70
	v_lshl_add_u64 v[182:183], v[246:247], 0, s[24:25]
	s_barrier
	ds_read_b128 v[166:169], v141 offset:49152
	ds_read_b128 v[170:173], v141 offset:50176
	ds_read_b128 v[174:177], v141 offset:51200
	ds_read_b128 v[178:181], v141 offset:52224
	ds_read_b128 v[186:189], v141 offset:53248
	ds_read_b128 v[194:197], v141 offset:54272
	ds_read_b128 v[198:201], v141 offset:55296
	ds_read_b128 v[202:205], v141 offset:56320
	global_load_lds_dwordx4 v[182:183], off
	v_lshl_add_u64 v[182:183], v[248:249], 0, s[24:25]
	s_mov_b32 m0, s71
	s_nop 0
	global_load_lds_dwordx4 v[182:183], off
	s_barrier
	s_waitcnt lgkmcnt(0)
	s_setprio 1
	s_waitcnt lgkmcnt(0)
	v_mfma_f32_16x16x32_bf16 v[60:63], v[128:131], v[166:169], v[60:63]
	v_mfma_f32_16x16x32_bf16 v[56:59], v[158:161], v[166:169], v[56:59]
	v_mfma_f32_16x16x32_bf16 v[52:55], v[128:131], v[174:177], v[52:55]
	v_mfma_f32_16x16x32_bf16 v[48:51], v[158:161], v[174:177], v[48:51]
	v_mfma_f32_16x16x32_bf16 v[44:47], v[128:131], v[186:189], v[44:47]
	v_mfma_f32_16x16x32_bf16 v[40:43], v[158:161], v[186:189], v[40:43]
	v_mfma_f32_16x16x32_bf16 v[36:39], v[128:131], v[198:201], v[36:39]
	v_mfma_f32_16x16x32_bf16 v[32:35], v[158:161], v[198:201], v[32:35]
	v_mfma_f32_16x16x32_bf16 v[60:63], v[152:155], v[170:173], v[60:63]
	v_mfma_f32_16x16x32_bf16 v[56:59], v[162:165], v[170:173], v[56:59]
	v_mfma_f32_16x16x32_bf16 v[52:55], v[152:155], v[178:181], v[52:55]
	v_mfma_f32_16x16x32_bf16 v[48:51], v[162:165], v[178:181], v[48:51]
	v_mfma_f32_16x16x32_bf16 v[44:47], v[152:155], v[194:197], v[44:47]
	v_mfma_f32_16x16x32_bf16 v[40:43], v[162:165], v[194:197], v[40:43]
	v_mfma_f32_16x16x32_bf16 v[36:39], v[152:155], v[202:205], v[36:39]
	v_mfma_f32_16x16x32_bf16 v[32:35], v[162:165], v[202:205], v[32:35]
	s_setprio 0
	s_barrier
	s_add_u32 s28, s28, 0x40080
	s_addc_u32 s29, s29, 0
	s_mov_b32 m0, s52
	v_lshl_add_u64 v[128:129], s[28:29], 0, v[134:135]
	global_load_lds_dwordx4 v[128:129], off
	v_lshl_add_u64 v[128:129], s[28:29], 0, v[138:139]
	s_mov_b32 m0, s50
	s_nop 0
	global_load_lds_dwordx4 v[128:129], off
	s_waitcnt vmcnt(6)
	s_barrier
	s_setprio 1
	v_mfma_f32_16x16x32_bf16 v[28:31], v[206:209], v[166:169], v[28:31]
	v_mfma_f32_16x16x32_bf16 v[24:27], v[214:217], v[166:169], v[24:27]
	v_mfma_f32_16x16x32_bf16 v[20:23], v[206:209], v[174:177], v[20:23]
	v_mfma_f32_16x16x32_bf16 v[16:19], v[214:217], v[174:177], v[16:19]
	v_mfma_f32_16x16x32_bf16 v[12:15], v[206:209], v[186:189], v[12:15]
	v_mfma_f32_16x16x32_bf16 v[8:11], v[214:217], v[186:189], v[8:11]
	v_mfma_f32_16x16x32_bf16 v[4:7], v[206:209], v[198:201], v[4:7]
	v_mfma_f32_16x16x32_bf16 v[0:3], v[214:217], v[198:201], v[0:3]
	v_mfma_f32_16x16x32_bf16 v[28:31], v[210:213], v[170:173], v[28:31]
	v_mfma_f32_16x16x32_bf16 v[24:27], v[242:245], v[170:173], v[24:27]
	v_mfma_f32_16x16x32_bf16 v[20:23], v[210:213], v[178:181], v[20:23]
	v_mfma_f32_16x16x32_bf16 v[16:19], v[242:245], v[178:181], v[16:19]
	v_mfma_f32_16x16x32_bf16 v[12:15], v[210:213], v[194:197], v[12:15]
	v_mfma_f32_16x16x32_bf16 v[8:11], v[242:245], v[194:197], v[8:11]
	v_mfma_f32_16x16x32_bf16 v[4:7], v[210:213], v[202:205], v[4:7]
	v_mfma_f32_16x16x32_bf16 v[0:3], v[242:245], v[202:205], v[0:3]
	s_setprio 0
	s_add_i32 s27, s27, 2
	s_add_u32 s0, s0, 0x100
	s_addc_u32 s1, s1, 0
	s_add_u32 s37, s37, 0x100
	s_addc_u32 s26, s26, 0
	s_cmp_gt_u32 s27, 13
	s_barrier
	s_cbranch_scc0 .LBB0_299
	s_lshl_b32 s20, s53, 8
	s_add_i32 s20, s20, s66
	s_lshl_b32 s46, s38, 8
	s_cmp_lg_u32 s33, 0
	v_or_b32_e32 v154, s20, v140
	v_or_b32_e32 v152, s46, v144
	s_cselect_b64 s[28:29], -1, 0
	s_movk_i32 s33, 0x3fff
	s_and_b64 vcc, exec, s[28:29]
	v_and_b32_e32 v157, 0xcf, v154
	v_cmp_lt_i32_e64 s[0:1], s33, v152
	s_cbranch_vccz .LBB0_306
	s_ashr_i32 s30, s20, 8
	v_cvt_pk_bf16_f32 v128, v124, v125
	v_cvt_pk_bf16_f32 v129, v126, v127
	v_cvt_pk_bf16_f32 v130, v120, v121
	v_cvt_pk_bf16_f32 v131, v122, v123
	s_and_saveexec_b64 s[26:27], s[0:1]
	s_xor_b64 s[0:1], exec, s[26:27]
	s_cbranch_execz .LBB0_303
	s_add_i32 s26, s46, 0xffffc000
	s_lshr_b32 s26, s26, 7
	v_lshl_add_u32 v184, v157, 4, s26
	s_ashr_i32 s31, s30, 31
	v_lshl_add_u64 v[158:159], v[184:185], 0, s[30:31]
	v_lshlrev_b64 v[158:159], 9, v[158:159]
	v_lshl_add_u64 v[158:159], v[146:147], 0, v[158:159]
	global_store_dwordx4 v[158:159], v[128:131], off sc1
.LBB0_303:
	s_andn2_saveexec_b64 s[0:1], s[0:1]
	s_cbranch_execz .LBB0_305
	s_ashr_i32 s26, s38, 3
	v_lshlrev_b32_e32 v184, 3, v157
	s_ashr_i32 s27, s26, 31
	v_lshl_add_u64 v[158:159], v[184:185], 0, s[26:27]
	v_readlane_b32 s4, v253, 16
	s_ashr_i32 s31, s30, 31
	v_lshlrev_b64 v[158:159], 13, v[158:159]
	v_readlane_b32 s10, v253, 22
	v_readlane_b32 s11, v253, 23
	v_and_b32_e32 v153, 0x778, v152
	s_lshl_b64 s[26:27], s[30:31], 12
	v_lshl_add_u64 v[158:159], s[10:11], 0, v[158:159]
	v_lshl_add_u64 v[158:159], v[158:159], 0, s[26:27]
	v_lshlrev_b32_e32 v184, 1, v153
	v_lshl_add_u64 v[158:159], v[158:159], 0, v[184:185]
	v_readlane_b32 s5, v253, 17
	v_readlane_b32 s6, v253, 18
	v_readlane_b32 s7, v253, 19
	v_readlane_b32 s8, v253, 20
	v_readlane_b32 s9, v253, 21
	v_readlane_b32 s12, v253, 24
	v_readlane_b32 s13, v253, 25
	v_readlane_b32 s14, v253, 26
	v_readlane_b32 s15, v253, 27
	v_readlane_b32 s16, v253, 28
	v_readlane_b32 s17, v253, 29
	v_readlane_b32 s18, v253, 30
	v_readlane_b32 s19, v253, 31
	global_store_dwordx4 v[158:159], v[128:131], off sc1

.LBB0_306:
.LBB0_307:
	s_cmp_lt_i32 s38, 8
	s_mov_b64 s[0:1], -1
	s_cbranch_scc0 .LBB0_309
	v_ashrrev_i32_e32 v155, 31, v154
	v_readlane_b32 s4, v253, 16
	v_lshlrev_b64 v[158:159], 12, v[154:155]
	v_readlane_b32 s5, v253, 17
	v_ashrrev_i32_e32 v153, 31, v152
	v_cvt_pk_bf16_f32 v128, v124, v125
	v_cvt_pk_bf16_f32 v129, v126, v127
	v_cvt_pk_bf16_f32 v130, v120, v121
	v_cvt_pk_bf16_f32 v131, v122, v123
	s_nop 0
	v_lshl_add_u64 v[158:159], s[4:5], 0, v[158:159]
	v_lshl_add_u64 v[158:159], v[152:153], 1, v[158:159]
	v_readlane_b32 s6, v253, 18
	v_readlane_b32 s7, v253, 19
	v_readlane_b32 s8, v253, 20
	v_readlane_b32 s9, v253, 21
	v_readlane_b32 s10, v253, 22
	v_readlane_b32 s11, v253, 23
	v_readlane_b32 s12, v253, 24
	v_readlane_b32 s13, v253, 25
	v_readlane_b32 s14, v253, 26
	v_readlane_b32 s15, v253, 27
	v_readlane_b32 s16, v253, 28
	v_readlane_b32 s17, v253, 29
	v_readlane_b32 s18, v253, 30
	v_readlane_b32 s19, v253, 31
	global_store_dwordx4 v[158:159], v[128:131], off sc1
	s_mov_b64 s[0:1], 0

.LBB0_311:
	s_nop 1
	v_or_b32_e32 v124, 16, v154
	v_cndmask_b32_e64 v120, 0, 1, s[28:29]
	v_cmp_ne_u32_e64 s[36:37], 1, v120
	s_andn2_b64 vcc, exec, s[28:29]
	v_and_b32_e32 v126, 0xdf, v124
	s_cbranch_vccnz .LBB0_317
	s_ashr_i32 s0, s20, 8
	v_cmp_lt_i32_e32 vcc, s33, v152
	v_cvt_pk_bf16_f32 v120, v116, v117
	v_cvt_pk_bf16_f32 v121, v118, v119
	v_cvt_pk_bf16_f32 v122, v112, v113
	v_cvt_pk_bf16_f32 v123, v114, v115
	s_and_saveexec_b64 s[26:27], vcc
	s_xor_b64 s[28:29], exec, s[26:27]
	s_cbranch_execz .LBB0_314
	s_add_i32 s1, s46, 0xffffc000
	s_lshr_b32 s1, s1, 7
	v_lshl_add_u32 v184, v126, 4, s1
	s_ashr_i32 s1, s0, 31
	v_lshl_add_u64 v[128:129], v[184:185], 0, s[0:1]
	v_lshlrev_b64 v[128:129], 9, v[128:129]
	v_lshl_add_u64 v[128:129], v[146:147], 0, v[128:129]
	global_store_dwordx4 v[128:129], v[120:123], off sc1
.LBB0_314:
	s_andn2_saveexec_b64 s[28:29], s[28:29]
	s_cbranch_execz .LBB0_316
	s_ashr_i32 s26, s38, 3
	v_lshlrev_b32_e32 v184, 3, v126
	s_ashr_i32 s27, s26, 31
	v_lshl_add_u64 v[128:129], v[184:185], 0, s[26:27]
	v_readlane_b32 s4, v253, 16
	s_ashr_i32 s1, s0, 31
	v_lshlrev_b64 v[128:129], 13, v[128:129]
	v_readlane_b32 s10, v253, 22
	v_readlane_b32 s11, v253, 23
	v_and_b32_e32 v125, 0x778, v152
	s_lshl_b64 s[0:1], s[0:1], 12
	v_lshl_add_u64 v[128:129], s[10:11], 0, v[128:129]
	v_lshl_add_u64 v[128:129], v[128:129], 0, s[0:1]
	v_lshlrev_b32_e32 v184, 1, v125
	v_lshl_add_u64 v[128:129], v[128:129], 0, v[184:185]
	v_readlane_b32 s5, v253, 17
	v_readlane_b32 s6, v253, 18
	v_readlane_b32 s7, v253, 19
	v_readlane_b32 s8, v253, 20
	v_readlane_b32 s9, v253, 21
	v_readlane_b32 s12, v253, 24
	v_readlane_b32 s13, v253, 25
	v_readlane_b32 s14, v253, 26
	v_readlane_b32 s15, v253, 27
	v_readlane_b32 s16, v253, 28
	v_readlane_b32 s17, v253, 29
	v_readlane_b32 s18, v253, 30
	v_readlane_b32 s19, v253, 31
	global_store_dwordx4 v[128:129], v[120:123], off sc1

.LBB0_317:
.LBB0_318:
	s_cmp_gt_i32 s38, 7
	s_mov_b64 s[0:1], -1
	s_cbranch_scc1 .LBB0_320
	v_ashrrev_i32_e32 v125, 31, v124
	v_readlane_b32 s4, v253, 16
	v_lshlrev_b64 v[128:129], 12, v[124:125]
	v_readlane_b32 s5, v253, 17
	v_ashrrev_i32_e32 v153, 31, v152
	s_mov_b64 s[0:1], 0
	v_lshl_add_u64 v[128:129], s[4:5], 0, v[128:129]
	v_lshl_add_u64 v[128:129], v[152:153], 1, v[128:129]
	v_cvt_pk_bf16_f32 v120, v116, v117
	v_cvt_pk_bf16_f32 v121, v118, v119
	v_cvt_pk_bf16_f32 v122, v112, v113
	v_cvt_pk_bf16_f32 v123, v114, v115
	v_readlane_b32 s6, v253, 18
	v_readlane_b32 s7, v253, 19
	v_readlane_b32 s8, v253, 20
	v_readlane_b32 s9, v253, 21
	v_readlane_b32 s10, v253, 22
	v_readlane_b32 s11, v253, 23
	v_readlane_b32 s12, v253, 24
	v_readlane_b32 s13, v253, 25
	v_readlane_b32 s14, v253, 26
	v_readlane_b32 s15, v253, 27
	v_readlane_b32 s16, v253, 28
	v_readlane_b32 s17, v253, 29
	v_readlane_b32 s18, v253, 30
	v_readlane_b32 s19, v253, 31
	global_store_dwordx4 v[128:129], v[120:123], off sc1

.LBB0_322:
	s_nop 1
	v_or_b32_e32 v116, 32, v154
	s_and_b64 vcc, exec, s[36:37]
	v_and_b32_e32 v118, 0xef, v116
	s_cbranch_vccnz .LBB0_328
	s_ashr_i32 s0, s20, 8
	v_cmp_lt_i32_e32 vcc, s33, v152
	v_cvt_pk_bf16_f32 v112, v108, v109
	v_cvt_pk_bf16_f32 v113, v110, v111
	v_cvt_pk_bf16_f32 v114, v104, v105
	v_cvt_pk_bf16_f32 v115, v106, v107
	s_and_saveexec_b64 s[26:27], vcc
	s_xor_b64 s[28:29], exec, s[26:27]
	s_cbranch_execz .LBB0_325
	s_add_i32 s1, s46, 0xffffc000
	s_lshr_b32 s1, s1, 7
	v_lshl_add_u32 v184, v118, 4, s1
	s_ashr_i32 s1, s0, 31
	v_lshl_add_u64 v[120:121], v[184:185], 0, s[0:1]
	v_lshlrev_b64 v[120:121], 9, v[120:121]
	v_lshl_add_u64 v[120:121], v[146:147], 0, v[120:121]
	global_store_dwordx4 v[120:121], v[112:115], off sc1
.LBB0_325:
	s_andn2_saveexec_b64 s[28:29], s[28:29]
	s_cbranch_execz .LBB0_327
	s_ashr_i32 s26, s38, 3
	v_lshlrev_b32_e32 v184, 3, v118
	s_ashr_i32 s27, s26, 31
	v_lshl_add_u64 v[120:121], v[184:185], 0, s[26:27]
	v_readlane_b32 s4, v253, 16
	s_ashr_i32 s1, s0, 31
	v_lshlrev_b64 v[120:121], 13, v[120:121]
	v_readlane_b32 s10, v253, 22
	v_readlane_b32 s11, v253, 23
	v_and_b32_e32 v117, 0x778, v152
	s_lshl_b64 s[0:1], s[0:1], 12
	v_lshl_add_u64 v[120:121], s[10:11], 0, v[120:121]
	v_lshl_add_u64 v[120:121], v[120:121], 0, s[0:1]
	v_lshlrev_b32_e32 v184, 1, v117
	v_lshl_add_u64 v[120:121], v[120:121], 0, v[184:185]
	v_readlane_b32 s5, v253, 17
	v_readlane_b32 s6, v253, 18
	v_readlane_b32 s7, v253, 19
	v_readlane_b32 s8, v253, 20
	v_readlane_b32 s9, v253, 21
	v_readlane_b32 s12, v253, 24
	v_readlane_b32 s13, v253, 25
	v_readlane_b32 s14, v253, 26
	v_readlane_b32 s15, v253, 27
	v_readlane_b32 s16, v253, 28
	v_readlane_b32 s17, v253, 29
	v_readlane_b32 s18, v253, 30
	v_readlane_b32 s19, v253, 31
	global_store_dwordx4 v[120:121], v[112:115], off sc1

.LBB0_328:
.LBB0_329:
	s_cmp_gt_i32 s38, 7
	s_mov_b64 s[0:1], -1
	s_cbranch_scc1 .LBB0_331
	v_ashrrev_i32_e32 v117, 31, v116
	v_readlane_b32 s4, v253, 16
	v_lshlrev_b64 v[120:121], 12, v[116:117]
	v_readlane_b32 s5, v253, 17
	v_ashrrev_i32_e32 v153, 31, v152
	s_mov_b64 s[0:1], 0
	v_lshl_add_u64 v[120:121], s[4:5], 0, v[120:121]
	v_lshl_add_u64 v[120:121], v[152:153], 1, v[120:121]
	v_cvt_pk_bf16_f32 v112, v108, v109
	v_cvt_pk_bf16_f32 v113, v110, v111
	v_cvt_pk_bf16_f32 v114, v104, v105
	v_cvt_pk_bf16_f32 v115, v106, v107
	v_readlane_b32 s6, v253, 18
	v_readlane_b32 s7, v253, 19
	v_readlane_b32 s8, v253, 20
	v_readlane_b32 s9, v253, 21
	v_readlane_b32 s10, v253, 22
	v_readlane_b32 s11, v253, 23
	v_readlane_b32 s12, v253, 24
	v_readlane_b32 s13, v253, 25
	v_readlane_b32 s14, v253, 26
	v_readlane_b32 s15, v253, 27
	v_readlane_b32 s16, v253, 28
	v_readlane_b32 s17, v253, 29
	v_readlane_b32 s18, v253, 30
	v_readlane_b32 s19, v253, 31
	global_store_dwordx4 v[120:121], v[112:115], off sc1

.LBB0_333:
	s_nop 1
	v_or_b32_e32 v108, 48, v154
	s_and_b64 vcc, exec, s[36:37]
	v_and_b32_e32 v110, 0xff, v108
	s_cbranch_vccnz .LBB0_339
	s_ashr_i32 s0, s20, 8
	v_cmp_lt_i32_e32 vcc, s33, v152
	v_cvt_pk_bf16_f32 v104, v100, v101
	v_cvt_pk_bf16_f32 v105, v102, v103
	v_cvt_pk_bf16_f32 v106, v96, v97
	v_cvt_pk_bf16_f32 v107, v98, v99
	s_and_saveexec_b64 s[26:27], vcc
	s_xor_b64 s[28:29], exec, s[26:27]
	s_cbranch_execz .LBB0_336
	s_add_i32 s1, s46, 0xffffc000
	s_lshr_b32 s1, s1, 7
	v_lshl_add_u32 v184, v110, 4, s1
	s_ashr_i32 s1, s0, 31
	v_lshl_add_u64 v[112:113], v[184:185], 0, s[0:1]
	v_lshlrev_b64 v[112:113], 9, v[112:113]
	v_lshl_add_u64 v[112:113], v[146:147], 0, v[112:113]
	global_store_dwordx4 v[112:113], v[104:107], off sc1
.LBB0_336:
	s_andn2_saveexec_b64 s[28:29], s[28:29]
	s_cbranch_execz .LBB0_338
	s_ashr_i32 s26, s38, 3
	v_lshlrev_b32_e32 v184, 3, v110
	s_ashr_i32 s27, s26, 31
	v_lshl_add_u64 v[112:113], v[184:185], 0, s[26:27]
	v_readlane_b32 s4, v253, 16
	s_ashr_i32 s1, s0, 31
	v_lshlrev_b64 v[112:113], 13, v[112:113]
	v_readlane_b32 s10, v253, 22
	v_readlane_b32 s11, v253, 23
	v_and_b32_e32 v109, 0x778, v152
	s_lshl_b64 s[0:1], s[0:1], 12
	v_lshl_add_u64 v[112:113], s[10:11], 0, v[112:113]
	v_lshl_add_u64 v[112:113], v[112:113], 0, s[0:1]
	v_lshlrev_b32_e32 v184, 1, v109
	v_lshl_add_u64 v[112:113], v[112:113], 0, v[184:185]
	v_readlane_b32 s5, v253, 17
	v_readlane_b32 s6, v253, 18
	v_readlane_b32 s7, v253, 19
	v_readlane_b32 s8, v253, 20
	v_readlane_b32 s9, v253, 21
	v_readlane_b32 s12, v253, 24
	v_readlane_b32 s13, v253, 25
	v_readlane_b32 s14, v253, 26
	v_readlane_b32 s15, v253, 27
	v_readlane_b32 s16, v253, 28
	v_readlane_b32 s17, v253, 29
	v_readlane_b32 s18, v253, 30
	v_readlane_b32 s19, v253, 31
	global_store_dwordx4 v[112:113], v[104:107], off sc1

.LBB0_339:
.LBB0_340:
	s_cmp_gt_i32 s38, 7
	s_mov_b64 s[0:1], -1
	s_cbranch_scc1 .LBB0_342
	v_ashrrev_i32_e32 v109, 31, v108
	v_readlane_b32 s4, v253, 16
	v_lshlrev_b64 v[112:113], 12, v[108:109]
	v_readlane_b32 s5, v253, 17
	v_ashrrev_i32_e32 v153, 31, v152
	s_mov_b64 s[0:1], 0
	v_lshl_add_u64 v[112:113], s[4:5], 0, v[112:113]
	v_lshl_add_u64 v[112:113], v[152:153], 1, v[112:113]
	v_cvt_pk_bf16_f32 v104, v100, v101
	v_cvt_pk_bf16_f32 v105, v102, v103
	v_cvt_pk_bf16_f32 v106, v96, v97
	v_cvt_pk_bf16_f32 v107, v98, v99
	v_readlane_b32 s6, v253, 18
	v_readlane_b32 s7, v253, 19
	v_readlane_b32 s8, v253, 20
	v_readlane_b32 s9, v253, 21
	v_readlane_b32 s10, v253, 22
	v_readlane_b32 s11, v253, 23
	v_readlane_b32 s12, v253, 24
	v_readlane_b32 s13, v253, 25
	v_readlane_b32 s14, v253, 26
	v_readlane_b32 s15, v253, 27
	v_readlane_b32 s16, v253, 28
	v_readlane_b32 s17, v253, 29
	v_readlane_b32 s18, v253, 30
	v_readlane_b32 s19, v253, 31
	global_store_dwordx4 v[112:113], v[104:107], off sc1

.LBB0_344:
	s_nop 1
	v_or_b32_e32 v100, s46, v156
	s_and_b64 vcc, exec, s[36:37]
	v_cmp_lt_i32_e64 s[0:1], s33, v100
	s_cbranch_vccnz .LBB0_350
	s_ashr_i32 s28, s20, 8
	v_cvt_pk_bf16_f32 v96, v92, v93
	v_cvt_pk_bf16_f32 v97, v94, v95
	v_cvt_pk_bf16_f32 v98, v88, v89
	v_cvt_pk_bf16_f32 v99, v90, v91
	s_and_saveexec_b64 s[26:27], s[0:1]
	s_xor_b64 s[0:1], exec, s[26:27]
	s_cbranch_execz .LBB0_347
	s_add_i32 s26, s46, 0xffffc000
	s_lshr_b32 s26, s26, 7
	v_lshl_add_u32 v184, v157, 4, s26
	s_ashr_i32 s29, s28, 31
	v_lshl_add_u64 v[102:103], v[184:185], 0, s[28:29]
	v_lshlrev_b64 v[102:103], 9, v[102:103]
	v_lshl_add_u64 v[102:103], v[146:147], 0, v[102:103]
	global_store_dwordx4 v[102:103], v[96:99], off offset:256 sc1
.LBB0_347:
	s_andn2_saveexec_b64 s[0:1], s[0:1]
	s_cbranch_execz .LBB0_349
	s_ashr_i32 s26, s38, 3
	v_lshlrev_b32_e32 v184, 3, v157
	s_ashr_i32 s27, s26, 31
	v_lshl_add_u64 v[102:103], v[184:185], 0, s[26:27]
	v_readlane_b32 s4, v253, 16
	s_ashr_i32 s29, s28, 31
	v_lshlrev_b64 v[102:103], 13, v[102:103]
	v_readlane_b32 s10, v253, 22
	v_readlane_b32 s11, v253, 23
	v_and_b32_e32 v101, 0x7f8, v100
	s_lshl_b64 s[26:27], s[28:29], 12
	v_lshl_add_u64 v[102:103], s[10:11], 0, v[102:103]
	v_lshl_add_u64 v[102:103], v[102:103], 0, s[26:27]
	v_lshlrev_b32_e32 v184, 1, v101
	v_lshl_add_u64 v[102:103], v[102:103], 0, v[184:185]
	v_readlane_b32 s5, v253, 17
	v_readlane_b32 s6, v253, 18
	v_readlane_b32 s7, v253, 19
	v_readlane_b32 s8, v253, 20
	v_readlane_b32 s9, v253, 21
	v_readlane_b32 s12, v253, 24
	v_readlane_b32 s13, v253, 25
	v_readlane_b32 s14, v253, 26
	v_readlane_b32 s15, v253, 27
	v_readlane_b32 s16, v253, 28
	v_readlane_b32 s17, v253, 29
	v_readlane_b32 s18, v253, 30
	v_readlane_b32 s19, v253, 31
	global_store_dwordx4 v[102:103], v[96:99], off sc1

.LBB0_350:
.LBB0_351:
	s_cmp_gt_i32 s38, 7
	s_mov_b64 s[0:1], -1
	s_cbranch_scc1 .LBB0_353
	v_ashrrev_i32_e32 v155, 31, v154
	v_readlane_b32 s4, v253, 16
	v_lshlrev_b64 v[102:103], 12, v[154:155]
	v_readlane_b32 s5, v253, 17
	s_ashr_i32 s47, s46, 31
	v_lshl_add_u64 v[104:105], s[46:47], 0, v[144:145]
	v_lshl_add_u64 v[102:103], s[4:5], 0, v[102:103]
	v_lshl_add_u64 v[102:103], v[104:105], 1, v[102:103]
	s_mov_b64 s[0:1], 0
	v_cvt_pk_bf16_f32 v96, v92, v93
	v_cvt_pk_bf16_f32 v97, v94, v95
	v_cvt_pk_bf16_f32 v98, v88, v89
	v_cvt_pk_bf16_f32 v99, v90, v91
	v_readlane_b32 s6, v253, 18
	v_readlane_b32 s7, v253, 19
	v_readlane_b32 s8, v253, 20
	v_readlane_b32 s9, v253, 21
	v_readlane_b32 s10, v253, 22
	v_readlane_b32 s11, v253, 23
	v_readlane_b32 s12, v253, 24
	v_readlane_b32 s13, v253, 25
	v_readlane_b32 s14, v253, 26
	v_readlane_b32 s15, v253, 27
	v_readlane_b32 s16, v253, 28
	v_readlane_b32 s17, v253, 29
	v_readlane_b32 s18, v253, 30
	v_readlane_b32 s19, v253, 31
	global_store_dwordx4 v[102:103], v[96:99], off offset:256 sc1

.LBB0_355:
	s_and_b64 vcc, exec, s[36:37]
	s_cbranch_vccnz .LBB0_361
	s_ashr_i32 s0, s20, 8
	v_cmp_lt_i32_e32 vcc, s33, v100
	v_cvt_pk_bf16_f32 v88, v84, v85
	v_cvt_pk_bf16_f32 v89, v86, v87
	v_cvt_pk_bf16_f32 v90, v80, v81
	v_cvt_pk_bf16_f32 v91, v82, v83
	s_and_saveexec_b64 s[26:27], vcc
	s_xor_b64 s[28:29], exec, s[26:27]
	s_cbranch_execz .LBB0_358
	s_add_i32 s1, s46, 0xffffc000
	s_lshr_b32 s1, s1, 7
	v_lshl_add_u32 v184, v126, 4, s1
	s_ashr_i32 s1, s0, 31
	v_lshl_add_u64 v[92:93], v[184:185], 0, s[0:1]
	v_lshlrev_b64 v[92:93], 9, v[92:93]
	v_lshl_add_u64 v[92:93], v[146:147], 0, v[92:93]
	global_store_dwordx4 v[92:93], v[88:91], off offset:256 sc1
.LBB0_358:
	s_andn2_saveexec_b64 s[28:29], s[28:29]
	s_cbranch_execz .LBB0_360
	s_ashr_i32 s26, s38, 3
	v_lshlrev_b32_e32 v184, 3, v126
	s_ashr_i32 s27, s26, 31
	v_lshl_add_u64 v[92:93], v[184:185], 0, s[26:27]
	v_readlane_b32 s4, v253, 16
	s_ashr_i32 s1, s0, 31
	v_lshlrev_b64 v[92:93], 13, v[92:93]
	v_readlane_b32 s10, v253, 22
	v_readlane_b32 s11, v253, 23
	v_and_b32_e32 v94, 0x7f8, v100
	s_lshl_b64 s[0:1], s[0:1], 12
	v_lshl_add_u64 v[92:93], s[10:11], 0, v[92:93]
	v_lshl_add_u64 v[92:93], v[92:93], 0, s[0:1]
	v_lshlrev_b32_e32 v184, 1, v94
	v_lshl_add_u64 v[92:93], v[92:93], 0, v[184:185]
	v_readlane_b32 s5, v253, 17
	v_readlane_b32 s6, v253, 18
	v_readlane_b32 s7, v253, 19
	v_readlane_b32 s8, v253, 20
	v_readlane_b32 s9, v253, 21
	v_readlane_b32 s12, v253, 24
	v_readlane_b32 s13, v253, 25
	v_readlane_b32 s14, v253, 26
	v_readlane_b32 s15, v253, 27
	v_readlane_b32 s16, v253, 28
	v_readlane_b32 s17, v253, 29
	v_readlane_b32 s18, v253, 30
	v_readlane_b32 s19, v253, 31
	global_store_dwordx4 v[92:93], v[88:91], off sc1

.LBB0_361:
.LBB0_362:
	s_cmp_gt_i32 s38, 7
	s_mov_b64 s[0:1], -1
	s_cbranch_scc1 .LBB0_364
	v_ashrrev_i32_e32 v125, 31, v124
	v_readlane_b32 s4, v253, 16
	v_lshlrev_b64 v[92:93], 12, v[124:125]
	v_readlane_b32 s5, v253, 17
	s_ashr_i32 s47, s46, 31
	v_lshl_add_u64 v[94:95], s[46:47], 0, v[144:145]
	v_lshl_add_u64 v[92:93], s[4:5], 0, v[92:93]
	v_lshl_add_u64 v[92:93], v[94:95], 1, v[92:93]
	s_mov_b64 s[0:1], 0
	v_cvt_pk_bf16_f32 v88, v84, v85
	v_cvt_pk_bf16_f32 v89, v86, v87
	v_cvt_pk_bf16_f32 v90, v80, v81
	v_cvt_pk_bf16_f32 v91, v82, v83
	v_readlane_b32 s6, v253, 18
	v_readlane_b32 s7, v253, 19
	v_readlane_b32 s8, v253, 20
	v_readlane_b32 s9, v253, 21
	v_readlane_b32 s10, v253, 22
	v_readlane_b32 s11, v253, 23
	v_readlane_b32 s12, v253, 24
	v_readlane_b32 s13, v253, 25
	v_readlane_b32 s14, v253, 26
	v_readlane_b32 s15, v253, 27
	v_readlane_b32 s16, v253, 28
	v_readlane_b32 s17, v253, 29
	v_readlane_b32 s18, v253, 30
	v_readlane_b32 s19, v253, 31
	global_store_dwordx4 v[92:93], v[88:91], off offset:256 sc1

.LBB0_366:
	s_and_b64 vcc, exec, s[36:37]
	s_cbranch_vccnz .LBB0_372
	s_ashr_i32 s0, s20, 8
	v_cmp_lt_i32_e32 vcc, s33, v100
	v_cvt_pk_bf16_f32 v80, v76, v77
	v_cvt_pk_bf16_f32 v81, v78, v79
	v_cvt_pk_bf16_f32 v82, v72, v73
	v_cvt_pk_bf16_f32 v83, v74, v75
	s_and_saveexec_b64 s[26:27], vcc
	s_xor_b64 s[28:29], exec, s[26:27]
	s_cbranch_execz .LBB0_369
	s_add_i32 s1, s46, 0xffffc000
	s_lshr_b32 s1, s1, 7
	v_lshl_add_u32 v184, v118, 4, s1
	s_ashr_i32 s1, s0, 31
	v_lshl_add_u64 v[84:85], v[184:185], 0, s[0:1]
	v_lshlrev_b64 v[84:85], 9, v[84:85]
	v_lshl_add_u64 v[84:85], v[146:147], 0, v[84:85]
	global_store_dwordx4 v[84:85], v[80:83], off offset:256 sc1
.LBB0_369:
	s_andn2_saveexec_b64 s[28:29], s[28:29]
	s_cbranch_execz .LBB0_371
	s_ashr_i32 s26, s38, 3
	v_lshlrev_b32_e32 v184, 3, v118
	s_ashr_i32 s27, s26, 31
	v_lshl_add_u64 v[84:85], v[184:185], 0, s[26:27]
	v_readlane_b32 s4, v253, 16
	s_ashr_i32 s1, s0, 31
	v_lshlrev_b64 v[84:85], 13, v[84:85]
	v_readlane_b32 s10, v253, 22
	v_readlane_b32 s11, v253, 23
	v_and_b32_e32 v86, 0x7f8, v100
	s_lshl_b64 s[0:1], s[0:1], 12
	v_lshl_add_u64 v[84:85], s[10:11], 0, v[84:85]
	v_lshl_add_u64 v[84:85], v[84:85], 0, s[0:1]
	v_lshlrev_b32_e32 v184, 1, v86
	v_lshl_add_u64 v[84:85], v[84:85], 0, v[184:185]
	v_readlane_b32 s5, v253, 17
	v_readlane_b32 s6, v253, 18
	v_readlane_b32 s7, v253, 19
	v_readlane_b32 s8, v253, 20
	v_readlane_b32 s9, v253, 21
	v_readlane_b32 s12, v253, 24
	v_readlane_b32 s13, v253, 25
	v_readlane_b32 s14, v253, 26
	v_readlane_b32 s15, v253, 27
	v_readlane_b32 s16, v253, 28
	v_readlane_b32 s17, v253, 29
	v_readlane_b32 s18, v253, 30
	v_readlane_b32 s19, v253, 31
	global_store_dwordx4 v[84:85], v[80:83], off sc1

.LBB0_372:
.LBB0_373:
	s_cmp_gt_i32 s38, 7
	s_mov_b64 s[0:1], -1
	s_cbranch_scc1 .LBB0_375
	v_ashrrev_i32_e32 v117, 31, v116
	v_readlane_b32 s4, v253, 16
	v_lshlrev_b64 v[84:85], 12, v[116:117]
	v_readlane_b32 s5, v253, 17
	s_ashr_i32 s47, s46, 31
	v_lshl_add_u64 v[86:87], s[46:47], 0, v[144:145]
	v_lshl_add_u64 v[84:85], s[4:5], 0, v[84:85]
	v_lshl_add_u64 v[84:85], v[86:87], 1, v[84:85]
	s_mov_b64 s[0:1], 0
	v_cvt_pk_bf16_f32 v80, v76, v77
	v_cvt_pk_bf16_f32 v81, v78, v79
	v_cvt_pk_bf16_f32 v82, v72, v73
	v_cvt_pk_bf16_f32 v83, v74, v75
	v_readlane_b32 s6, v253, 18
	v_readlane_b32 s7, v253, 19
	v_readlane_b32 s8, v253, 20
	v_readlane_b32 s9, v253, 21
	v_readlane_b32 s10, v253, 22
	v_readlane_b32 s11, v253, 23
	v_readlane_b32 s12, v253, 24
	v_readlane_b32 s13, v253, 25
	v_readlane_b32 s14, v253, 26
	v_readlane_b32 s15, v253, 27
	v_readlane_b32 s16, v253, 28
	v_readlane_b32 s17, v253, 29
	v_readlane_b32 s18, v253, 30
	v_readlane_b32 s19, v253, 31
	global_store_dwordx4 v[84:85], v[80:83], off offset:256 sc1

.LBB0_377:
	s_and_b64 vcc, exec, s[36:37]
	s_cbranch_vccnz .LBB0_383
	s_ashr_i32 s0, s20, 8
	v_cmp_lt_i32_e32 vcc, s33, v100
	v_cvt_pk_bf16_f32 v72, v68, v69
	v_cvt_pk_bf16_f32 v73, v70, v71
	v_cvt_pk_bf16_f32 v74, v64, v65
	v_cvt_pk_bf16_f32 v75, v66, v67
	s_and_saveexec_b64 s[26:27], vcc
	s_xor_b64 s[28:29], exec, s[26:27]
	s_cbranch_execz .LBB0_380
	s_add_i32 s1, s46, 0xffffc000
	s_lshr_b32 s1, s1, 7
	v_lshl_add_u32 v184, v110, 4, s1
	s_ashr_i32 s1, s0, 31
	v_lshl_add_u64 v[76:77], v[184:185], 0, s[0:1]
	v_lshlrev_b64 v[76:77], 9, v[76:77]
	v_lshl_add_u64 v[76:77], v[146:147], 0, v[76:77]
	global_store_dwordx4 v[76:77], v[72:75], off offset:256 sc1
.LBB0_380:
	s_andn2_saveexec_b64 s[28:29], s[28:29]
	s_cbranch_execz .LBB0_382
	s_ashr_i32 s26, s38, 3
	v_lshlrev_b32_e32 v184, 3, v110
	s_ashr_i32 s27, s26, 31
	v_lshl_add_u64 v[76:77], v[184:185], 0, s[26:27]
	v_readlane_b32 s4, v253, 16
	s_ashr_i32 s1, s0, 31
	v_lshlrev_b64 v[76:77], 13, v[76:77]
	v_readlane_b32 s10, v253, 22
	v_readlane_b32 s11, v253, 23
	v_and_b32_e32 v78, 0x7f8, v100
	s_lshl_b64 s[0:1], s[0:1], 12
	v_lshl_add_u64 v[76:77], s[10:11], 0, v[76:77]
	v_lshl_add_u64 v[76:77], v[76:77], 0, s[0:1]
	v_lshlrev_b32_e32 v184, 1, v78
	v_lshl_add_u64 v[76:77], v[76:77], 0, v[184:185]
	v_readlane_b32 s5, v253, 17
	v_readlane_b32 s6, v253, 18
	v_readlane_b32 s7, v253, 19
	v_readlane_b32 s8, v253, 20
	v_readlane_b32 s9, v253, 21
	v_readlane_b32 s12, v253, 24
	v_readlane_b32 s13, v253, 25
	v_readlane_b32 s14, v253, 26
	v_readlane_b32 s15, v253, 27
	v_readlane_b32 s16, v253, 28
	v_readlane_b32 s17, v253, 29
	v_readlane_b32 s18, v253, 30
	v_readlane_b32 s19, v253, 31
	global_store_dwordx4 v[76:77], v[72:75], off sc1

.LBB0_383:
.LBB0_384:
	s_cmp_gt_i32 s38, 7
	s_mov_b64 s[0:1], -1
	s_cbranch_scc1 .LBB0_386
	v_ashrrev_i32_e32 v109, 31, v108
	v_readlane_b32 s4, v253, 16
	v_lshlrev_b64 v[76:77], 12, v[108:109]
	v_readlane_b32 s5, v253, 17
	s_ashr_i32 s47, s46, 31
	v_lshl_add_u64 v[78:79], s[46:47], 0, v[144:145]
	v_lshl_add_u64 v[76:77], s[4:5], 0, v[76:77]
	v_lshl_add_u64 v[76:77], v[78:79], 1, v[76:77]
	s_mov_b64 s[0:1], 0
	v_cvt_pk_bf16_f32 v72, v68, v69
	v_cvt_pk_bf16_f32 v73, v70, v71
	v_cvt_pk_bf16_f32 v74, v64, v65
	v_cvt_pk_bf16_f32 v75, v66, v67
	v_readlane_b32 s6, v253, 18
	v_readlane_b32 s7, v253, 19
	v_readlane_b32 s8, v253, 20
	v_readlane_b32 s9, v253, 21
	v_readlane_b32 s10, v253, 22
	v_readlane_b32 s11, v253, 23
	v_readlane_b32 s12, v253, 24
	v_readlane_b32 s13, v253, 25
	v_readlane_b32 s14, v253, 26
	v_readlane_b32 s15, v253, 27
	v_readlane_b32 s16, v253, 28
	v_readlane_b32 s17, v253, 29
	v_readlane_b32 s18, v253, 30
	v_readlane_b32 s19, v253, 31
	global_store_dwordx4 v[76:77], v[72:75], off offset:256 sc1

.LBB0_388:
	s_addk_i32 s20, 0x80
	s_nop 0
	v_or_b32_e32 v68, s20, v140
	s_and_b64 vcc, exec, s[36:37]
	v_and_b32_e32 v70, 0xcf, v68
	s_cbranch_vccnz .LBB0_394
	s_ashr_i32 s0, s20, 8
	v_cmp_lt_i32_e32 vcc, s33, v152
	v_cvt_pk_bf16_f32 v64, v60, v61
	v_cvt_pk_bf16_f32 v65, v62, v63
	v_cvt_pk_bf16_f32 v66, v56, v57
	v_cvt_pk_bf16_f32 v67, v58, v59
	s_and_saveexec_b64 s[26:27], vcc
	s_xor_b64 s[28:29], exec, s[26:27]
	s_cbranch_execz .LBB0_391
	s_add_i32 s1, s46, 0xffffc000
	s_lshr_b32 s1, s1, 7
	v_lshl_add_u32 v184, v70, 4, s1
	s_ashr_i32 s1, s0, 31
	v_lshl_add_u64 v[72:73], v[184:185], 0, s[0:1]
	v_lshlrev_b64 v[72:73], 9, v[72:73]
	v_lshl_add_u64 v[72:73], v[146:147], 0, v[72:73]
	global_store_dwordx4 v[72:73], v[64:67], off sc1
.LBB0_391:
	s_andn2_saveexec_b64 s[28:29], s[28:29]
	s_cbranch_execz .LBB0_393
	s_ashr_i32 s26, s38, 3
	v_lshlrev_b32_e32 v184, 3, v70
	s_ashr_i32 s27, s26, 31
	v_lshl_add_u64 v[72:73], v[184:185], 0, s[26:27]
	v_readlane_b32 s4, v253, 16
	s_ashr_i32 s1, s0, 31
	v_lshlrev_b64 v[72:73], 13, v[72:73]
	v_readlane_b32 s10, v253, 22
	v_readlane_b32 s11, v253, 23
	v_and_b32_e32 v69, 0x778, v152
	s_lshl_b64 s[0:1], s[0:1], 12
	v_lshl_add_u64 v[72:73], s[10:11], 0, v[72:73]
	v_lshl_add_u64 v[72:73], v[72:73], 0, s[0:1]
	v_lshlrev_b32_e32 v184, 1, v69
	v_lshl_add_u64 v[72:73], v[72:73], 0, v[184:185]
	v_readlane_b32 s5, v253, 17
	v_readlane_b32 s6, v253, 18
	v_readlane_b32 s7, v253, 19
	v_readlane_b32 s8, v253, 20
	v_readlane_b32 s9, v253, 21
	v_readlane_b32 s12, v253, 24
	v_readlane_b32 s13, v253, 25
	v_readlane_b32 s14, v253, 26
	v_readlane_b32 s15, v253, 27
	v_readlane_b32 s16, v253, 28
	v_readlane_b32 s17, v253, 29
	v_readlane_b32 s18, v253, 30
	v_readlane_b32 s19, v253, 31
	global_store_dwordx4 v[72:73], v[64:67], off sc1

.LBB0_394:
.LBB0_395:
	s_cmp_gt_i32 s38, 7
	s_mov_b64 s[0:1], -1
	s_cbranch_scc1 .LBB0_397
	v_ashrrev_i32_e32 v69, 31, v68
	v_readlane_b32 s4, v253, 16
	v_lshlrev_b64 v[72:73], 12, v[68:69]
	v_readlane_b32 s5, v253, 17
	v_ashrrev_i32_e32 v153, 31, v152
	s_mov_b64 s[0:1], 0
	v_lshl_add_u64 v[72:73], s[4:5], 0, v[72:73]
	v_lshl_add_u64 v[72:73], v[152:153], 1, v[72:73]
	v_cvt_pk_bf16_f32 v64, v60, v61
	v_cvt_pk_bf16_f32 v65, v62, v63
	v_cvt_pk_bf16_f32 v66, v56, v57
	v_cvt_pk_bf16_f32 v67, v58, v59
	v_readlane_b32 s6, v253, 18
	v_readlane_b32 s7, v253, 19
	v_readlane_b32 s8, v253, 20
	v_readlane_b32 s9, v253, 21
	v_readlane_b32 s10, v253, 22
	v_readlane_b32 s11, v253, 23
	v_readlane_b32 s12, v253, 24
	v_readlane_b32 s13, v253, 25
	v_readlane_b32 s14, v253, 26
	v_readlane_b32 s15, v253, 27
	v_readlane_b32 s16, v253, 28
	v_readlane_b32 s17, v253, 29
	v_readlane_b32 s18, v253, 30
	v_readlane_b32 s19, v253, 31
	global_store_dwordx4 v[72:73], v[64:67], off sc1

.LBB0_399:
	s_nop 1
	v_or_b32_e32 v60, 16, v68
	s_and_b64 vcc, exec, s[36:37]
	v_and_b32_e32 v62, 0xdf, v60
	s_cbranch_vccnz .LBB0_405
	s_ashr_i32 s0, s20, 8
	v_cmp_lt_i32_e32 vcc, s33, v152
	v_cvt_pk_bf16_f32 v56, v52, v53
	v_cvt_pk_bf16_f32 v57, v54, v55
	v_cvt_pk_bf16_f32 v58, v48, v49
	v_cvt_pk_bf16_f32 v59, v50, v51
	s_and_saveexec_b64 s[26:27], vcc
	s_xor_b64 s[28:29], exec, s[26:27]
	s_cbranch_execz .LBB0_402
	s_add_i32 s1, s46, 0xffffc000
	s_lshr_b32 s1, s1, 7
	v_lshl_add_u32 v184, v62, 4, s1
	s_ashr_i32 s1, s0, 31
	v_lshl_add_u64 v[64:65], v[184:185], 0, s[0:1]
	v_lshlrev_b64 v[64:65], 9, v[64:65]
	v_lshl_add_u64 v[64:65], v[146:147], 0, v[64:65]
	global_store_dwordx4 v[64:65], v[56:59], off sc1
.LBB0_402:
	s_andn2_saveexec_b64 s[28:29], s[28:29]
	s_cbranch_execz .LBB0_404
	s_ashr_i32 s26, s38, 3
	v_lshlrev_b32_e32 v184, 3, v62
	s_ashr_i32 s27, s26, 31
	v_lshl_add_u64 v[64:65], v[184:185], 0, s[26:27]
	v_readlane_b32 s4, v253, 16
	s_ashr_i32 s1, s0, 31
	v_lshlrev_b64 v[64:65], 13, v[64:65]
	v_readlane_b32 s10, v253, 22
	v_readlane_b32 s11, v253, 23
	v_and_b32_e32 v61, 0x778, v152
	s_lshl_b64 s[0:1], s[0:1], 12
	v_lshl_add_u64 v[64:65], s[10:11], 0, v[64:65]
	v_lshl_add_u64 v[64:65], v[64:65], 0, s[0:1]
	v_lshlrev_b32_e32 v184, 1, v61
	v_lshl_add_u64 v[64:65], v[64:65], 0, v[184:185]
	v_readlane_b32 s5, v253, 17
	v_readlane_b32 s6, v253, 18
	v_readlane_b32 s7, v253, 19
	v_readlane_b32 s8, v253, 20
	v_readlane_b32 s9, v253, 21
	v_readlane_b32 s12, v253, 24
	v_readlane_b32 s13, v253, 25
	v_readlane_b32 s14, v253, 26
	v_readlane_b32 s15, v253, 27
	v_readlane_b32 s16, v253, 28
	v_readlane_b32 s17, v253, 29
	v_readlane_b32 s18, v253, 30
	v_readlane_b32 s19, v253, 31
	global_store_dwordx4 v[64:65], v[56:59], off sc1

.LBB0_405:
.LBB0_406:
	s_cmp_gt_i32 s38, 7
	s_mov_b64 s[0:1], -1
	s_cbranch_scc1 .LBB0_408
	v_ashrrev_i32_e32 v61, 31, v60
	v_readlane_b32 s4, v253, 16
	v_lshlrev_b64 v[64:65], 12, v[60:61]
	v_readlane_b32 s5, v253, 17
	v_ashrrev_i32_e32 v153, 31, v152
	s_mov_b64 s[0:1], 0
	v_lshl_add_u64 v[64:65], s[4:5], 0, v[64:65]
	v_lshl_add_u64 v[64:65], v[152:153], 1, v[64:65]
	v_cvt_pk_bf16_f32 v56, v52, v53
	v_cvt_pk_bf16_f32 v57, v54, v55
	v_cvt_pk_bf16_f32 v58, v48, v49
	v_cvt_pk_bf16_f32 v59, v50, v51
	v_readlane_b32 s6, v253, 18
	v_readlane_b32 s7, v253, 19
	v_readlane_b32 s8, v253, 20
	v_readlane_b32 s9, v253, 21
	v_readlane_b32 s10, v253, 22
	v_readlane_b32 s11, v253, 23
	v_readlane_b32 s12, v253, 24
	v_readlane_b32 s13, v253, 25
	v_readlane_b32 s14, v253, 26
	v_readlane_b32 s15, v253, 27
	v_readlane_b32 s16, v253, 28
	v_readlane_b32 s17, v253, 29
	v_readlane_b32 s18, v253, 30
	v_readlane_b32 s19, v253, 31
	global_store_dwordx4 v[64:65], v[56:59], off sc1

.LBB0_410:
	s_nop 1
	v_or_b32_e32 v52, 32, v68
	s_and_b64 vcc, exec, s[36:37]
	v_and_b32_e32 v54, 0xef, v52
	s_cbranch_vccnz .LBB0_416
	s_ashr_i32 s0, s20, 8
	v_cmp_lt_i32_e32 vcc, s33, v152
	v_cvt_pk_bf16_f32 v48, v44, v45
	v_cvt_pk_bf16_f32 v49, v46, v47
	v_cvt_pk_bf16_f32 v50, v40, v41
	v_cvt_pk_bf16_f32 v51, v42, v43
	s_and_saveexec_b64 s[26:27], vcc
	s_xor_b64 s[28:29], exec, s[26:27]
	s_cbranch_execz .LBB0_413
	s_add_i32 s1, s46, 0xffffc000
	s_lshr_b32 s1, s1, 7
	v_lshl_add_u32 v184, v54, 4, s1
	s_ashr_i32 s1, s0, 31
	v_lshl_add_u64 v[56:57], v[184:185], 0, s[0:1]
	v_lshlrev_b64 v[56:57], 9, v[56:57]
	v_lshl_add_u64 v[56:57], v[146:147], 0, v[56:57]
	global_store_dwordx4 v[56:57], v[48:51], off sc1
.LBB0_413:
	s_andn2_saveexec_b64 s[28:29], s[28:29]
	s_cbranch_execz .LBB0_415
	s_ashr_i32 s26, s38, 3
	v_lshlrev_b32_e32 v184, 3, v54
	s_ashr_i32 s27, s26, 31
	v_lshl_add_u64 v[56:57], v[184:185], 0, s[26:27]
	v_readlane_b32 s4, v253, 16
	s_ashr_i32 s1, s0, 31
	v_lshlrev_b64 v[56:57], 13, v[56:57]
	v_readlane_b32 s10, v253, 22
	v_readlane_b32 s11, v253, 23
	v_and_b32_e32 v53, 0x778, v152
	s_lshl_b64 s[0:1], s[0:1], 12
	v_lshl_add_u64 v[56:57], s[10:11], 0, v[56:57]
	v_lshl_add_u64 v[56:57], v[56:57], 0, s[0:1]
	v_lshlrev_b32_e32 v184, 1, v53
	v_lshl_add_u64 v[56:57], v[56:57], 0, v[184:185]
	v_readlane_b32 s5, v253, 17
	v_readlane_b32 s6, v253, 18
	v_readlane_b32 s7, v253, 19
	v_readlane_b32 s8, v253, 20
	v_readlane_b32 s9, v253, 21
	v_readlane_b32 s12, v253, 24
	v_readlane_b32 s13, v253, 25
	v_readlane_b32 s14, v253, 26
	v_readlane_b32 s15, v253, 27
	v_readlane_b32 s16, v253, 28
	v_readlane_b32 s17, v253, 29
	v_readlane_b32 s18, v253, 30
	v_readlane_b32 s19, v253, 31
	global_store_dwordx4 v[56:57], v[48:51], off sc1

.LBB0_416:
.LBB0_417:
	s_cmp_gt_i32 s38, 7
	s_mov_b64 s[0:1], -1
	s_cbranch_scc1 .LBB0_419
	v_ashrrev_i32_e32 v53, 31, v52
	v_readlane_b32 s4, v253, 16
	v_lshlrev_b64 v[56:57], 12, v[52:53]
	v_readlane_b32 s5, v253, 17
	v_ashrrev_i32_e32 v153, 31, v152
	s_mov_b64 s[0:1], 0
	v_lshl_add_u64 v[56:57], s[4:5], 0, v[56:57]
	v_lshl_add_u64 v[56:57], v[152:153], 1, v[56:57]
	v_cvt_pk_bf16_f32 v48, v44, v45
	v_cvt_pk_bf16_f32 v49, v46, v47
	v_cvt_pk_bf16_f32 v50, v40, v41
	v_cvt_pk_bf16_f32 v51, v42, v43
	v_readlane_b32 s6, v253, 18
	v_readlane_b32 s7, v253, 19
	v_readlane_b32 s8, v253, 20
	v_readlane_b32 s9, v253, 21
	v_readlane_b32 s10, v253, 22
	v_readlane_b32 s11, v253, 23
	v_readlane_b32 s12, v253, 24
	v_readlane_b32 s13, v253, 25
	v_readlane_b32 s14, v253, 26
	v_readlane_b32 s15, v253, 27
	v_readlane_b32 s16, v253, 28
	v_readlane_b32 s17, v253, 29
	v_readlane_b32 s18, v253, 30
	v_readlane_b32 s19, v253, 31
	global_store_dwordx4 v[56:57], v[48:51], off sc1

.LBB0_421:
	s_nop 1
	v_or_b32_e32 v44, 48, v68
	s_and_b64 vcc, exec, s[36:37]
	v_and_b32_e32 v46, 0xff, v44
	s_cbranch_vccnz .LBB0_427
	s_ashr_i32 s0, s20, 8
	v_cmp_lt_i32_e32 vcc, s33, v152
	v_cvt_pk_bf16_f32 v40, v36, v37
	v_cvt_pk_bf16_f32 v41, v38, v39
	v_cvt_pk_bf16_f32 v42, v32, v33
	v_cvt_pk_bf16_f32 v43, v34, v35
	s_and_saveexec_b64 s[26:27], vcc
	s_xor_b64 s[28:29], exec, s[26:27]
	s_cbranch_execz .LBB0_424
	s_add_i32 s1, s46, 0xffffc000
	s_lshr_b32 s1, s1, 7
	v_lshl_add_u32 v184, v46, 4, s1
	s_ashr_i32 s1, s0, 31
	v_lshl_add_u64 v[48:49], v[184:185], 0, s[0:1]
	v_lshlrev_b64 v[48:49], 9, v[48:49]
	v_lshl_add_u64 v[48:49], v[146:147], 0, v[48:49]
	global_store_dwordx4 v[48:49], v[40:43], off sc1
.LBB0_424:
	s_andn2_saveexec_b64 s[28:29], s[28:29]
	s_cbranch_execz .LBB0_426
	s_ashr_i32 s26, s38, 3
	v_lshlrev_b32_e32 v184, 3, v46
	s_ashr_i32 s27, s26, 31
	v_lshl_add_u64 v[48:49], v[184:185], 0, s[26:27]
	v_readlane_b32 s4, v253, 16
	s_ashr_i32 s1, s0, 31
	v_lshlrev_b64 v[48:49], 13, v[48:49]
	v_readlane_b32 s10, v253, 22
	v_readlane_b32 s11, v253, 23
	v_and_b32_e32 v45, 0x778, v152
	s_lshl_b64 s[0:1], s[0:1], 12
	v_lshl_add_u64 v[48:49], s[10:11], 0, v[48:49]
	v_lshl_add_u64 v[48:49], v[48:49], 0, s[0:1]
	v_lshlrev_b32_e32 v184, 1, v45
	v_lshl_add_u64 v[48:49], v[48:49], 0, v[184:185]
	v_readlane_b32 s5, v253, 17
	v_readlane_b32 s6, v253, 18
	v_readlane_b32 s7, v253, 19
	v_readlane_b32 s8, v253, 20
	v_readlane_b32 s9, v253, 21
	v_readlane_b32 s12, v253, 24
	v_readlane_b32 s13, v253, 25
	v_readlane_b32 s14, v253, 26
	v_readlane_b32 s15, v253, 27
	v_readlane_b32 s16, v253, 28
	v_readlane_b32 s17, v253, 29
	v_readlane_b32 s18, v253, 30
	v_readlane_b32 s19, v253, 31
	global_store_dwordx4 v[48:49], v[40:43], off sc1

.LBB0_427:
.LBB0_428:
	s_cmp_gt_i32 s38, 7
	s_mov_b64 s[0:1], -1
	s_cbranch_scc1 .LBB0_430
	v_ashrrev_i32_e32 v45, 31, v44
	v_readlane_b32 s4, v253, 16
	v_lshlrev_b64 v[48:49], 12, v[44:45]
	v_readlane_b32 s5, v253, 17
	v_ashrrev_i32_e32 v153, 31, v152
	s_mov_b64 s[0:1], 0
	v_lshl_add_u64 v[48:49], s[4:5], 0, v[48:49]
	v_lshl_add_u64 v[48:49], v[152:153], 1, v[48:49]
	v_cvt_pk_bf16_f32 v40, v36, v37
	v_cvt_pk_bf16_f32 v41, v38, v39
	v_cvt_pk_bf16_f32 v42, v32, v33
	v_cvt_pk_bf16_f32 v43, v34, v35
	v_readlane_b32 s6, v253, 18
	v_readlane_b32 s7, v253, 19
	v_readlane_b32 s8, v253, 20
	v_readlane_b32 s9, v253, 21
	v_readlane_b32 s10, v253, 22
	v_readlane_b32 s11, v253, 23
	v_readlane_b32 s12, v253, 24
	v_readlane_b32 s13, v253, 25
	v_readlane_b32 s14, v253, 26
	v_readlane_b32 s15, v253, 27
	v_readlane_b32 s16, v253, 28
	v_readlane_b32 s17, v253, 29
	v_readlane_b32 s18, v253, 30
	v_readlane_b32 s19, v253, 31
	global_store_dwordx4 v[48:49], v[40:43], off sc1

.LBB0_432:
	s_and_b64 vcc, exec, s[36:37]
	s_cbranch_vccnz .LBB0_438
	s_ashr_i32 s0, s20, 8
	v_cmp_lt_i32_e32 vcc, s33, v100
	v_cvt_pk_bf16_f32 v32, v28, v29
	v_cvt_pk_bf16_f32 v33, v30, v31
	v_cvt_pk_bf16_f32 v34, v24, v25
	v_cvt_pk_bf16_f32 v35, v26, v27
	s_and_saveexec_b64 s[26:27], vcc
	s_xor_b64 s[28:29], exec, s[26:27]
	s_cbranch_execz .LBB0_435
	s_add_i32 s1, s46, 0xffffc000
	s_lshr_b32 s1, s1, 7
	v_lshl_add_u32 v184, v70, 4, s1
	s_ashr_i32 s1, s0, 31
	v_lshl_add_u64 v[36:37], v[184:185], 0, s[0:1]
	v_lshlrev_b64 v[36:37], 9, v[36:37]
	v_lshl_add_u64 v[36:37], v[146:147], 0, v[36:37]
	global_store_dwordx4 v[36:37], v[32:35], off offset:256 sc1
.LBB0_435:
	s_andn2_saveexec_b64 s[28:29], s[28:29]
	s_cbranch_execz .LBB0_437
	s_ashr_i32 s26, s38, 3
	v_lshlrev_b32_e32 v184, 3, v70
	s_ashr_i32 s27, s26, 31
	v_lshl_add_u64 v[36:37], v[184:185], 0, s[26:27]
	v_readlane_b32 s4, v253, 16
	s_ashr_i32 s1, s0, 31
	v_lshlrev_b64 v[36:37], 13, v[36:37]
	v_readlane_b32 s10, v253, 22
	v_readlane_b32 s11, v253, 23
	v_and_b32_e32 v38, 0x7f8, v100
	s_lshl_b64 s[0:1], s[0:1], 12
	v_lshl_add_u64 v[36:37], s[10:11], 0, v[36:37]
	v_lshl_add_u64 v[36:37], v[36:37], 0, s[0:1]
	v_lshlrev_b32_e32 v184, 1, v38
	v_lshl_add_u64 v[36:37], v[36:37], 0, v[184:185]
	v_readlane_b32 s5, v253, 17
	v_readlane_b32 s6, v253, 18
	v_readlane_b32 s7, v253, 19
	v_readlane_b32 s8, v253, 20
	v_readlane_b32 s9, v253, 21
	v_readlane_b32 s12, v253, 24
	v_readlane_b32 s13, v253, 25
	v_readlane_b32 s14, v253, 26
	v_readlane_b32 s15, v253, 27
	v_readlane_b32 s16, v253, 28
	v_readlane_b32 s17, v253, 29
	v_readlane_b32 s18, v253, 30
	v_readlane_b32 s19, v253, 31
	global_store_dwordx4 v[36:37], v[32:35], off sc1

.LBB0_438:
.LBB0_439:
	s_cmp_gt_i32 s38, 7
	s_mov_b64 s[0:1], -1
	s_cbranch_scc1 .LBB0_441
	v_ashrrev_i32_e32 v69, 31, v68
	v_readlane_b32 s4, v253, 16
	v_lshlrev_b64 v[36:37], 12, v[68:69]
	v_readlane_b32 s5, v253, 17
	s_ashr_i32 s47, s46, 31
	v_lshl_add_u64 v[38:39], s[46:47], 0, v[144:145]
	v_lshl_add_u64 v[36:37], s[4:5], 0, v[36:37]
	v_lshl_add_u64 v[36:37], v[38:39], 1, v[36:37]
	s_mov_b64 s[0:1], 0
	v_cvt_pk_bf16_f32 v32, v28, v29
	v_cvt_pk_bf16_f32 v33, v30, v31
	v_cvt_pk_bf16_f32 v34, v24, v25
	v_cvt_pk_bf16_f32 v35, v26, v27
	v_readlane_b32 s6, v253, 18
	v_readlane_b32 s7, v253, 19
	v_readlane_b32 s8, v253, 20
	v_readlane_b32 s9, v253, 21
	v_readlane_b32 s10, v253, 22
	v_readlane_b32 s11, v253, 23
	v_readlane_b32 s12, v253, 24
	v_readlane_b32 s13, v253, 25
	v_readlane_b32 s14, v253, 26
	v_readlane_b32 s15, v253, 27
	v_readlane_b32 s16, v253, 28
	v_readlane_b32 s17, v253, 29
	v_readlane_b32 s18, v253, 30
	v_readlane_b32 s19, v253, 31
	global_store_dwordx4 v[36:37], v[32:35], off offset:256 sc1

.LBB0_443:
	s_and_b64 vcc, exec, s[36:37]
	s_cbranch_vccnz .LBB0_449
	s_ashr_i32 s0, s20, 8
	v_cmp_lt_i32_e32 vcc, s33, v100
	v_cvt_pk_bf16_f32 v24, v20, v21
	v_cvt_pk_bf16_f32 v25, v22, v23
	v_cvt_pk_bf16_f32 v26, v16, v17
	v_cvt_pk_bf16_f32 v27, v18, v19
	s_and_saveexec_b64 s[26:27], vcc
	s_xor_b64 s[28:29], exec, s[26:27]
	s_cbranch_execz .LBB0_446
	s_add_i32 s1, s46, 0xffffc000
	s_lshr_b32 s1, s1, 7
	v_lshl_add_u32 v184, v62, 4, s1
	s_ashr_i32 s1, s0, 31
	v_lshl_add_u64 v[28:29], v[184:185], 0, s[0:1]
	v_lshlrev_b64 v[28:29], 9, v[28:29]
	v_lshl_add_u64 v[28:29], v[146:147], 0, v[28:29]
	global_store_dwordx4 v[28:29], v[24:27], off offset:256 sc1
.LBB0_446:
	s_andn2_saveexec_b64 s[28:29], s[28:29]
	s_cbranch_execz .LBB0_448
	s_ashr_i32 s26, s38, 3
	v_lshlrev_b32_e32 v184, 3, v62
	s_ashr_i32 s27, s26, 31
	v_lshl_add_u64 v[28:29], v[184:185], 0, s[26:27]
	v_readlane_b32 s4, v253, 16
	s_ashr_i32 s1, s0, 31
	v_lshlrev_b64 v[28:29], 13, v[28:29]
	v_readlane_b32 s10, v253, 22
	v_readlane_b32 s11, v253, 23
	v_and_b32_e32 v30, 0x7f8, v100
	s_lshl_b64 s[0:1], s[0:1], 12
	v_lshl_add_u64 v[28:29], s[10:11], 0, v[28:29]
	v_lshl_add_u64 v[28:29], v[28:29], 0, s[0:1]
	v_lshlrev_b32_e32 v184, 1, v30
	v_lshl_add_u64 v[28:29], v[28:29], 0, v[184:185]
	v_readlane_b32 s5, v253, 17
	v_readlane_b32 s6, v253, 18
	v_readlane_b32 s7, v253, 19
	v_readlane_b32 s8, v253, 20
	v_readlane_b32 s9, v253, 21
	v_readlane_b32 s12, v253, 24
	v_readlane_b32 s13, v253, 25
	v_readlane_b32 s14, v253, 26
	v_readlane_b32 s15, v253, 27
	v_readlane_b32 s16, v253, 28
	v_readlane_b32 s17, v253, 29
	v_readlane_b32 s18, v253, 30
	v_readlane_b32 s19, v253, 31
	global_store_dwordx4 v[28:29], v[24:27], off sc1

.LBB0_449:
.LBB0_450:
	s_cmp_gt_i32 s38, 7
	s_mov_b64 s[0:1], -1
	s_cbranch_scc1 .LBB0_452
	v_ashrrev_i32_e32 v61, 31, v60
	v_readlane_b32 s4, v253, 16
	v_lshlrev_b64 v[28:29], 12, v[60:61]
	v_readlane_b32 s5, v253, 17
	s_ashr_i32 s47, s46, 31
	v_lshl_add_u64 v[30:31], s[46:47], 0, v[144:145]
	v_lshl_add_u64 v[28:29], s[4:5], 0, v[28:29]
	v_lshl_add_u64 v[28:29], v[30:31], 1, v[28:29]
	s_mov_b64 s[0:1], 0
	v_cvt_pk_bf16_f32 v24, v20, v21
	v_cvt_pk_bf16_f32 v25, v22, v23
	v_cvt_pk_bf16_f32 v26, v16, v17
	v_cvt_pk_bf16_f32 v27, v18, v19
	v_readlane_b32 s6, v253, 18
	v_readlane_b32 s7, v253, 19
	v_readlane_b32 s8, v253, 20
	v_readlane_b32 s9, v253, 21
	v_readlane_b32 s10, v253, 22
	v_readlane_b32 s11, v253, 23
	v_readlane_b32 s12, v253, 24
	v_readlane_b32 s13, v253, 25
	v_readlane_b32 s14, v253, 26
	v_readlane_b32 s15, v253, 27
	v_readlane_b32 s16, v253, 28
	v_readlane_b32 s17, v253, 29
	v_readlane_b32 s18, v253, 30
	v_readlane_b32 s19, v253, 31
	global_store_dwordx4 v[28:29], v[24:27], off offset:256 sc1

.LBB0_454:
	s_and_b64 vcc, exec, s[36:37]
	s_cbranch_vccnz .LBB0_460
	s_ashr_i32 s0, s20, 8
	v_cmp_lt_i32_e32 vcc, s33, v100
	v_cvt_pk_bf16_f32 v16, v12, v13
	v_cvt_pk_bf16_f32 v17, v14, v15
	v_cvt_pk_bf16_f32 v18, v8, v9
	v_cvt_pk_bf16_f32 v19, v10, v11
	s_and_saveexec_b64 s[26:27], vcc
	s_xor_b64 s[28:29], exec, s[26:27]
	s_cbranch_execz .LBB0_457
	s_add_i32 s1, s46, 0xffffc000
	s_lshr_b32 s1, s1, 7
	v_lshl_add_u32 v184, v54, 4, s1
	s_ashr_i32 s1, s0, 31
	v_lshl_add_u64 v[20:21], v[184:185], 0, s[0:1]
	v_lshlrev_b64 v[20:21], 9, v[20:21]
	v_lshl_add_u64 v[20:21], v[146:147], 0, v[20:21]
	global_store_dwordx4 v[20:21], v[16:19], off offset:256 sc1
.LBB0_457:
	s_andn2_saveexec_b64 s[28:29], s[28:29]
	s_cbranch_execz .LBB0_459
	s_ashr_i32 s26, s38, 3
	v_lshlrev_b32_e32 v184, 3, v54
	s_ashr_i32 s27, s26, 31
	v_lshl_add_u64 v[20:21], v[184:185], 0, s[26:27]
	v_readlane_b32 s4, v253, 16
	s_ashr_i32 s1, s0, 31
	v_lshlrev_b64 v[20:21], 13, v[20:21]
	v_readlane_b32 s10, v253, 22
	v_readlane_b32 s11, v253, 23
	v_and_b32_e32 v22, 0x7f8, v100
	s_lshl_b64 s[0:1], s[0:1], 12
	v_lshl_add_u64 v[20:21], s[10:11], 0, v[20:21]
	v_lshl_add_u64 v[20:21], v[20:21], 0, s[0:1]
	v_lshlrev_b32_e32 v184, 1, v22
	v_lshl_add_u64 v[20:21], v[20:21], 0, v[184:185]
	v_readlane_b32 s5, v253, 17
	v_readlane_b32 s6, v253, 18
	v_readlane_b32 s7, v253, 19
	v_readlane_b32 s8, v253, 20
	v_readlane_b32 s9, v253, 21
	v_readlane_b32 s12, v253, 24
	v_readlane_b32 s13, v253, 25
	v_readlane_b32 s14, v253, 26
	v_readlane_b32 s15, v253, 27
	v_readlane_b32 s16, v253, 28
	v_readlane_b32 s17, v253, 29
	v_readlane_b32 s18, v253, 30
	v_readlane_b32 s19, v253, 31
	global_store_dwordx4 v[20:21], v[16:19], off sc1

.LBB0_460:
.LBB0_461:
	s_cmp_gt_i32 s38, 7
	s_mov_b64 s[0:1], -1
	s_cbranch_scc1 .LBB0_463
	v_ashrrev_i32_e32 v53, 31, v52
	v_readlane_b32 s4, v253, 16
	v_lshlrev_b64 v[20:21], 12, v[52:53]
	v_readlane_b32 s5, v253, 17
	s_ashr_i32 s47, s46, 31
	v_lshl_add_u64 v[22:23], s[46:47], 0, v[144:145]
	v_lshl_add_u64 v[20:21], s[4:5], 0, v[20:21]
	v_lshl_add_u64 v[20:21], v[22:23], 1, v[20:21]
	s_mov_b64 s[0:1], 0
	v_cvt_pk_bf16_f32 v16, v12, v13
	v_cvt_pk_bf16_f32 v17, v14, v15
	v_cvt_pk_bf16_f32 v18, v8, v9
	v_cvt_pk_bf16_f32 v19, v10, v11
	v_readlane_b32 s6, v253, 18
	v_readlane_b32 s7, v253, 19
	v_readlane_b32 s8, v253, 20
	v_readlane_b32 s9, v253, 21
	v_readlane_b32 s10, v253, 22
	v_readlane_b32 s11, v253, 23
	v_readlane_b32 s12, v253, 24
	v_readlane_b32 s13, v253, 25
	v_readlane_b32 s14, v253, 26
	v_readlane_b32 s15, v253, 27
	v_readlane_b32 s16, v253, 28
	v_readlane_b32 s17, v253, 29
	v_readlane_b32 s18, v253, 30
	v_readlane_b32 s19, v253, 31
	global_store_dwordx4 v[20:21], v[16:19], off offset:256 sc1

.LBB0_465:
	s_and_b64 vcc, exec, s[36:37]
	s_cbranch_vccnz .LBB0_471
	s_ashr_i32 s0, s20, 8
	v_cmp_lt_i32_e32 vcc, s33, v100
	v_cvt_pk_bf16_f32 v8, v4, v5
	v_cvt_pk_bf16_f32 v9, v6, v7
	v_cvt_pk_bf16_f32 v10, v0, v1
	v_cvt_pk_bf16_f32 v11, v2, v3
	s_and_saveexec_b64 s[26:27], vcc
	s_xor_b64 s[28:29], exec, s[26:27]
	s_cbranch_execz .LBB0_468
	s_add_i32 s1, s46, 0xffffc000
	s_lshr_b32 s1, s1, 7
	v_lshl_add_u32 v184, v46, 4, s1
	s_ashr_i32 s1, s0, 31
	v_lshl_add_u64 v[12:13], v[184:185], 0, s[0:1]
	v_lshlrev_b64 v[12:13], 9, v[12:13]
	v_lshl_add_u64 v[12:13], v[146:147], 0, v[12:13]
	global_store_dwordx4 v[12:13], v[8:11], off offset:256 sc1
.LBB0_468:
	s_or_saveexec_b64 s[28:29], s[28:29]
	s_mov_b32 s36, 0x800000
	s_xor_b64 exec, exec, s[28:29]
	s_cbranch_execz .LBB0_470
	s_ashr_i32 s26, s38, 3
	v_lshlrev_b32_e32 v184, 3, v46
	s_ashr_i32 s27, s26, 31
	v_lshl_add_u64 v[12:13], v[184:185], 0, s[26:27]
	v_readlane_b32 s4, v253, 16
	s_ashr_i32 s1, s0, 31
	v_lshlrev_b64 v[12:13], 13, v[12:13]
	v_readlane_b32 s10, v253, 22
	v_readlane_b32 s11, v253, 23
	v_and_b32_e32 v14, 0x7f8, v100
	s_lshl_b64 s[0:1], s[0:1], 12
	v_lshl_add_u64 v[12:13], s[10:11], 0, v[12:13]
	v_lshl_add_u64 v[12:13], v[12:13], 0, s[0:1]
	v_lshlrev_b32_e32 v184, 1, v14
	v_lshl_add_u64 v[12:13], v[12:13], 0, v[184:185]
	v_readlane_b32 s5, v253, 17
	v_readlane_b32 s6, v253, 18
	v_readlane_b32 s7, v253, 19
	v_readlane_b32 s8, v253, 20
	v_readlane_b32 s9, v253, 21
	v_readlane_b32 s12, v253, 24
	v_readlane_b32 s13, v253, 25
	v_readlane_b32 s14, v253, 26
	v_readlane_b32 s15, v253, 27
	v_readlane_b32 s16, v253, 28
	v_readlane_b32 s17, v253, 29
	v_readlane_b32 s18, v253, 30
	v_readlane_b32 s19, v253, 31
	global_store_dwordx4 v[12:13], v[8:11], off sc1

.LBB0_472:
	s_cmp_gt_i32 s38, 7
	s_mov_b64 s[0:1], -1
	s_cbranch_scc1 .LBB0_474
	v_ashrrev_i32_e32 v45, 31, v44
	v_readlane_b32 s4, v253, 16
	v_lshlrev_b64 v[12:13], 12, v[44:45]
	v_readlane_b32 s5, v253, 17
	s_ashr_i32 s47, s46, 31
	v_lshl_add_u64 v[14:15], s[46:47], 0, v[144:145]
	v_lshl_add_u64 v[12:13], s[4:5], 0, v[12:13]
	v_lshl_add_u64 v[12:13], v[14:15], 1, v[12:13]
	s_mov_b64 s[0:1], 0
	v_cvt_pk_bf16_f32 v8, v4, v5
	v_cvt_pk_bf16_f32 v9, v6, v7
	v_cvt_pk_bf16_f32 v10, v0, v1
	v_cvt_pk_bf16_f32 v11, v2, v3
	v_readlane_b32 s6, v253, 18
	v_readlane_b32 s7, v253, 19
	v_readlane_b32 s8, v253, 20
	v_readlane_b32 s9, v253, 21
	v_readlane_b32 s10, v253, 22
	v_readlane_b32 s11, v253, 23
	v_readlane_b32 s12, v253, 24
	v_readlane_b32 s13, v253, 25
	v_readlane_b32 s14, v253, 26
	v_readlane_b32 s15, v253, 27
	v_readlane_b32 s16, v253, 28
	v_readlane_b32 s17, v253, 29
	v_readlane_b32 s18, v253, 30
	v_readlane_b32 s19, v253, 31
	global_store_dwordx4 v[12:13], v[8:11], off offset:256 sc1
